# GEMM phases: static priority raise for the second wave half, per-segment s_setprio flips removed
# baseline (speedup 1.0000x reference)
; __device__ __forceinline__ int lane_now() { int l; asm volatile("v_mbcnt_lo_u32_b32 %0, -1, 0\n\tv_mbcnt_hi_u32_b32 %0, -1, %0" : "=v"(l)); return l; }
; #define PG8_STAGE(bufoff, gbase, voff) do { _Pragma("unroll") for (int _i = 0; _i < 2; ++_i) \
;         __builtin_amdgcn_global_load_lds((const unsigned*)((const char*)(gbase) + (voff)[_i]), (PG8_LAS unsigned*)(lds + (bufoff) + ldsw + _i * 8192), 16, 0, 0); } while (0)
; #define PG8_BAR __builtin_amdgcn_s_barrier()
; #define lane (lane_now())
; template <class Epi, class Sched, bool ALIGN_EPI = false, bool SP2 = false>
; __device__ __forceinline__ void gemm_phase(PG8_LAS unsigned char* lds, const Gemm g, const Sched& S, const Epi& E, const int wid) {
;     const int lane = lane_now(), tid = wid * 64 + lane, wr = wid >> 2, wc = wid & 3, fr = lane & 15, fq = lane >> 4;
;     const int K = g.K, nt = K / BK;
;     unsigned voffA[2], voffB[2];
; #pragma unroll
;     for (int i = 0; i < 2; ++i) { int R, C; stage_rc(tid * 16 + i * 8192, R, C); const int Rb = Epi::PERM ? ((R & ~31) + perm32(R & 31)) : R;
;         voffA[i] = (unsigned)(R * K + C) * 2u; voffB[i] = (unsigned)(Rb * K + C) * 2u; }
;     const size_t kstep = (size_t)(BK * 2);
;     const size_t hstep = (size_t)HALF * K * 2;
;     const size_t tstep = 2 * hstep;
;     const unsigned ldsw = (unsigned)wid * 1024u;
;     const int aoff = lds_byte(wr * 64 + fr, fq * 8), boff = lds_byte(wc * 32 + fr, fq * 8);
;     ...
;     Unit cur, nxt; int ui = 0;
;     if (!S.next(0, cur)) return;
;     f32x4 acc[2][2][4][2];
; #pragma unroll
;     for (int a = 0; a < 2; ++a)
; #pragma unroll
;         for (int b = 0; b < 2; ++b)
; #pragma unroll
;             for (int m = 0; m < 4; ++m)
; #pragma unroll
;                 for (int n = 0; n < 2; ++n) acc[a][b][m][n] = (f32x4){0.f, 0.f, 0.f, 0.f};
;     bf16x8 At[4][2], B0[2][2], B1[2][2];
;     const char* cA = (const char*)g.A + (size_t)cur.pm * tstep; const char* cB = (const char*)g.Bt + (size_t)cur.pn * tstep;
;     S.a_ready(cur);
;     if constexpr (SP2) {
;         PG8_STAGE(PG8_SB(0, 0), cB, voffB); PG8_STAGE(PG8_SB(0, 1), cB + hstep, voffB); PG8_STAGE(PG8_SA(0, 0), cA, voffA); PG8_STAGE(PG8_SA(0, 1), cA + hstep, voffA);
;         if (wr == 1) PG8_BAR;
.LBB0_141:
	s_add_u32 s2, s92, 0x2b00000
	s_addc_u32 s3, s93, 0
	s_add_u32 s96, s92, 0x6b00000
	v_readlane_b32 s4, v244, 2
	s_addc_u32 s97, s93, 0
	s_lshr_b32 s5, s4, 8
	s_lshl_b32 s4, s5, 6
	v_writelane_b32 v244, s4, 17
	v_writelane_b32 v244, s5, 18
	s_lshl_b32 s4, s5, 13
	v_writelane_b32 v244, s4, 19
	s_lshl_b32 s4, s83, 5
	v_writelane_b32 v244, s4, 20
	s_and_b32 s4, s4, 0x60
	s_lshl_b32 s33, s83, 10
	v_writelane_b32 v244, s4, 21
	s_lshr_b32 s4, s4, 3
	s_cmpk_lt_i32 s82, 0xb00
	v_writelane_b32 v244, s4, 22
	s_cselect_b64 s[4:5], -1, 0
	v_writelane_b32 v244, s4, 23
	s_cmpk_gt_i32 s82, 0xaff
	s_waitcnt lgkmcnt(0)
	s_barrier
	v_writelane_b32 v244, s5, 24
	v_mbcnt_lo_u32_b32 v10, -1, 0
	v_mbcnt_hi_u32_b32 v10, -1, v10
	s_cbranch_scc1 .LBB0_157
	v_lshl_add_u32 v0, v10, 4, s33
	v_add_u32_e32 v1, 0x2000, v0
	v_ashrrev_i32_e32 v2, 31, v1
	v_lshrrev_b32_e32 v2, 22, v2
	v_add_u32_e32 v2, v1, v2
	v_ashrrev_i32_e32 v8, 10, v2
	v_mul_i32_i24_e32 v2, 0x400, v8
	v_sub_u32_e32 v1, v1, v2
	v_lshrrev_b32_e32 v2, 4, v1
	v_bitop3_b32 v1, v2, v1, 32 bitop3:0x6c
	v_ashrrev_i32_e32 v2, 31, v1
	v_lshrrev_b32_e32 v2, 26, v2
	v_add_u32_e32 v2, v1, v2
	v_ashrrev_i32_e32 v9, 6, v2
	v_lshlrev_b32_e32 v3, 3, v8
	v_and_b32_e32 v2, 0xffc0, v2
	v_and_b32_e32 v3, -16, v3
	v_sub_u32_e32 v1, v1, v2
	v_add_u32_e32 v3, v9, v3
	v_lshrrev_b16_e32 v2, 7, v1
	v_and_b32_e32 v4, 3, v9
	s_mov_b32 s4, 0x1fffe0
	v_lshrrev_b32_e32 v5, 2, v3
	v_lshlrev_b32_e32 v6, 1, v3
	v_and_b32_e32 v2, 1, v2
	v_and_or_b32 v4, v3, s4, v4
	v_and_b32_e32 v5, 4, v5
	v_and_b32_e32 v6, 24, v6
	v_add_u16_e32 v1, v1, v2
	v_mov_b32_e32 v2, 1
	v_or3_b32 v4, v4, v5, v6
	v_lshlrev_b32_e32 v5, 5, v8
	v_ashrrev_i16_sdwa v1, v2, sext(v1) dst_sel:DWORD dst_unused:UNUSED_PAD src0_sel:DWORD src1_sel:BYTE_0
	v_and_b32_e32 v5, 32, v5
	v_bfe_i32 v11, v1, 0, 16
	v_add_lshl_u32 v1, v5, v11, 1
	v_lshl_add_u32 v128, v4, 11, v1
	v_lshl_add_u32 v130, v3, 11, v1
	v_ashrrev_i32_e32 v1, 31, v0
	v_lshrrev_b32_e32 v1, 22, v1
	v_add_u32_e32 v1, v0, v1
	v_ashrrev_i32_e32 v12, 10, v1
	v_mul_i32_i24_e32 v1, 0x400, v12
	v_sub_u32_e32 v0, v0, v1
	v_lshrrev_b32_e32 v1, 4, v0
	v_bitop3_b32 v0, v1, v0, 32 bitop3:0x6c
	v_ashrrev_i32_e32 v1, 31, v0
	v_lshrrev_b32_e32 v1, 26, v1
	v_add_u32_e32 v1, v0, v1
	v_lshlrev_b32_e32 v3, 3, v12
	s_add_u32 s40, s92, 0x100000
	v_ashrrev_i32_e32 v13, 6, v1
	v_and_b32_e32 v3, -16, v3
	s_addc_u32 s41, s93, 0
	v_add_u32_e32 v3, v13, v3
	v_and_b32_e32 v4, 3, v13
	s_ashr_i32 s42, s82, 31
	v_and_or_b32 v4, v3, s4, v4
	s_lshr_b32 s4, s42, 29
	s_add_i32 s4, s82, s4
	s_ashr_i32 s5, s4, 3
	s_and_b32 s4, s4, -8
	s_sub_i32 s4, s82, s4
	s_cmp_lt_i32 s4, 0
	s_movk_i32 s43, 0x161
	s_cselect_b32 s6, s43, 0x160
	s_mul_i32 s4, s4, s6
	s_add_i32 s4, s4, s5
	s_mul_hi_i32 s5, s4, 0x2e8ba2e9
	s_lshr_b32 s6, s5, 31
	s_ashr_i32 s5, s5, 4
	s_add_i32 s5, s5, s6
	s_lshl_b32 s6, s5, 2
	s_mulk_i32 s5, 0x58
	s_sub_i32 s5, s4, s5
	s_bfe_i32 s4, s5, 0x80000
	s_bfe_u32 s4, s4, 0x2000d
	s_add_i32 s7, s5, s4
	s_bfe_i32 s4, s7, 0x80000
	s_and_b32 s7, s7, 0xfc
	s_sub_i32 s5, s5, s7
	s_sext_i32_i16 s4, s4
	s_sext_i32_i8 s5, s5
	v_lshrrev_b32_e32 v5, 2, v3
	v_lshlrev_b32_e32 v6, 1, v3
	v_and_b32_e32 v1, 0xc0, v1
	s_lshr_b32 s4, s4, 2
	s_add_i32 s28, s6, s5
	v_and_b32_e32 v5, 4, v5
	v_and_b32_e32 v6, 24, v6
	v_sub_u32_e32 v0, v0, v1
	s_ashr_i32 s29, s28, 31
	s_bfe_i64 s[10:11], s[4:5], 0x100000
	v_or3_b32 v4, v4, v5, v6
	v_lshlrev_b32_e32 v5, 5, v12
	v_ashrrev_i16_sdwa v0, v2, sext(v0) dst_sel:DWORD dst_unused:UNUSED_PAD src0_sel:DWORD src1_sel:BYTE_0
	s_lshl_b64 s[6:7], s[28:29], 19
	s_lshl_b64 s[10:11], s[10:11], 19
	v_and_b32_e32 v5, 32, v5
	v_bfe_i32 v14, v0, 0, 16
	s_add_u32 s34, s40, s10
	v_add_lshl_u32 v0, v5, v14, 1
	s_addc_u32 s35, s41, s11
	s_add_i32 s29, s33, 0
	v_lshl_add_u32 v132, v4, 11, v0
	s_add_i32 m0, s29, 0x10000
	v_lshl_add_u32 v134, v3, 11, v0
	global_load_lds_dwordx4 v132, s[34:35]
	s_add_i32 m0, s29, 0x12000
	s_add_u32 s10, s34, 0x40000
	global_load_lds_dwordx4 v128, s[34:35]
	s_addc_u32 s11, s35, 0
	s_add_i32 m0, s29, 0x14000
	v_mov_b32_e32 v133, 0
	global_load_lds_dwordx4 v132, s[10:11]
	s_add_i32 m0, s29, 0x16000
	s_add_u32 s30, s2, s6
	s_addc_u32 s31, s3, s7
	s_add_i32 s44, s29, 0x2000
	global_load_lds_dwordx4 v128, s[10:11]
	s_mov_b32 m0, s29
	s_add_u32 s6, s30, 0x40000
	global_load_lds_dwordx4 v134, s[30:31]
	s_mov_b32 m0, s44
	s_addc_u32 s7, s31, 0
	s_add_i32 s45, s29, 0x4000
	global_load_lds_dwordx4 v130, s[30:31]
	s_mov_b32 m0, s45
	s_add_i32 s46, s29, 0x6000
	global_load_lds_dwordx4 v134, s[6:7]
	s_mov_b32 m0, s46
	v_readlane_b32 s5, v244, 18
	global_load_lds_dwordx4 v130, s[6:7]
	v_mov_b32_e32 v129, v133
	v_mov_b32_e32 v135, v133
	v_mov_b32_e32 v131, v133
	s_cmp_eq_u32 s5, 1
	s_mov_b32 s47, 0
	v_lshl_add_u64 v[4:5], s[34:35], 0, v[132:133]
	v_lshl_add_u64 v[2:3], s[34:35], 0, v[128:129]
	v_lshl_add_u64 v[0:1], s[30:31], 0, v[134:135]
	s_cselect_b64 s[6:7], -1, 0
	s_cmp_lg_u32 s5, 1
	v_lshl_add_u64 v[6:7], s[30:31], 0, v[130:131]
	s_cbranch_scc1 .LBB0_144
	s_barrier
	s_setprio 1

; #define PG8_STAGE(bufoff, gbase, voff) do { _Pragma("unroll") for (int _i = 0; _i < 2; ++_i) \
;         __builtin_amdgcn_global_load_lds((const unsigned*)((const char*)(gbase) + (voff)[_i]), (PG8_LAS unsigned*)(lds + (bufoff) + ldsw + _i * 8192), 16, 0, 0); } while (0)
; #define PG8_LDA(dst, b, h) do { _Pragma("unroll") for (int m = 0; m < 4; ++m) _Pragma("unroll") for (int k = 0; k < 2; ++k) dst[m][k] = *(const PG8_LAS bf16x8*)(lds + PG8_SA(b, h) + aoff + m * 2048 + k * 1024); } while (0)
; #define PG8_LDB(dst, b, h) do { _Pragma("unroll") for (int n = 0; n < 2; ++n) _Pragma("unroll") for (int k = 0; k < 2; ++k) dst[n][k] = *(const PG8_LAS bf16x8*)(lds + PG8_SB(b, h) + boff + n * 2048 + k * 1024); } while (0)
; #define PG8_MMA(ai, bj, At, Bt) do { __builtin_amdgcn_s_setprio(1); _Pragma("unroll") for (int m = 0; m < 4; ++m) _Pragma("unroll") for (int n = 0; n < 2; ++n) _Pragma("unroll") for (int k = 0; k < 2; ++k) \
;         acc[ai][bj][m][n] = __builtin_amdgcn_mfma_f32_16x16x32_bf16(Bt[n][k], At[m][k], acc[ai][bj][m][n], 0, 0, 0); __builtin_amdgcn_s_setprio(0); } while (0)
; template <class Epi, class Sched, bool ALIGN_EPI = false, bool SP2 = false>
; __device__ __forceinline__ void gemm_phase(PG8_LAS unsigned char* lds, const Gemm g, const Sched& S, const Epi& E, const int wid) {
;     ...
;             if constexpr (SP2) {
;             PG8_LDB(B0, 0, 0); PG8_LDB(B1, 0, 1); PG8_SCHED; PG8_LDA(At, 0, 0); PG8_STAGE(PG8_SA(1, 1), a1 + hstep, voffA);
;             PG8_WAIT_V(8); PG8_WAIT_L(0); PG8_BAR; PG8_MMA(0, 0, At, B0); PG8_MMA(0, 1, At, B1); PG8_BAR; PG8_SCHED;
;             PG8_LDA(At, 0, 1); PG8_STAGE(PG8_SB(0, 0), b2, voffB); PG8_STAGE(PG8_SB(0, 1), b2 + hstep, voffB); PG8_STAGE(PG8_SA(0, 0), a2, voffA);
;             PG8_WAIT_V(8); PG8_WAIT_L(0); PG8_BAR; PG8_MMA(1, 0, At, B0); PG8_MMA(1, 1, At, B1); PG8_BAR; PG8_SCHED;
;             PG8_LDB(B0, 1, 0); PG8_LDB(B1, 1, 1); PG8_SCHED; PG8_LDA(At, 1, 0); PG8_STAGE(PG8_SA(0, 1), a2 + hstep, voffA);
;             PG8_WAIT_V(8); PG8_WAIT_L(0); PG8_BAR; PG8_MMA(0, 0, At, B0); PG8_MMA(0, 1, At, B1); PG8_BAR; PG8_SCHED;
;             PG8_LDA(At, 1, 1); PG8_STAGE(PG8_SB(1, 0), b3, voffB); PG8_STAGE(PG8_SB(1, 1), b3 + hstep, voffB); PG8_STAGE(PG8_SA(1, 0), a3, voffA);
;             PG8_WAIT_V(8); PG8_WAIT_L(0); PG8_BAR; PG8_MMA(1, 0, At, B0); PG8_MMA(1, 1, At, B1); PG8_BAR; PG8_SCHED;
.LBB0_150:
	ds_read_b128 v[144:147], v151
	ds_read_b128 v[154:157], v151 offset:1024
	ds_read_b128 v[158:161], v151 offset:2048
	ds_read_b128 v[162:165], v151 offset:3072
	ds_read_b128 v[166:169], v152
	ds_read_b128 v[170:173], v152 offset:1024
	ds_read_b128 v[174:177], v152 offset:2048
	ds_read_b128 v[178:181], v152 offset:3072
	s_add_u32 s34, s30, 0xfffc0080
	s_addc_u32 s35, s31, -1
	s_cmp_eq_u32 s77, 12
	s_cselect_b32 s39, s23, s35
	s_cselect_b32 s38, s72, s34
	s_cselect_b32 s35, s21, s76
	s_cselect_b32 s34, s73, s75
	v_lshl_add_u64 v[202:203], s[30:31], 0, v[136:137]
	s_add_i32 m0, s29, 0xc000
	ds_read_b128 v[182:185], v153
	ds_read_b128 v[186:189], v153 offset:1024
	ds_read_b128 v[190:193], v153 offset:2048
	ds_read_b128 v[194:197], v153 offset:3072
	ds_read_b128 v[198:201], v153 offset:4096
	ds_read_b128 v[206:209], v153 offset:5120
	ds_read_b128 v[210:213], v153 offset:6144
	ds_read_b128 v[214:217], v153 offset:7168
	global_load_lds_dwordx4 v[202:203], off
	v_lshl_add_u64 v[202:203], s[30:31], 0, v[138:139]
	s_add_i32 m0, s29, 0xe000
	s_nop 0
	global_load_lds_dwordx4 v[202:203], off
	s_waitcnt vmcnt(8)
	s_waitcnt lgkmcnt(0)
	s_barrier
	s_waitcnt lgkmcnt(0)
	v_mfma_f32_16x16x32_bf16 v[124:127], v[144:147], v[182:185], v[124:127]
	v_mfma_f32_16x16x32_bf16 v[116:119], v[158:161], v[182:185], v[116:119]
	v_mfma_f32_16x16x32_bf16 v[108:111], v[144:147], v[190:193], v[108:111]
	v_mfma_f32_16x16x32_bf16 v[100:103], v[158:161], v[190:193], v[100:103]
	v_mfma_f32_16x16x32_bf16 v[92:95], v[144:147], v[198:201], v[92:95]
	v_mfma_f32_16x16x32_bf16 v[84:87], v[158:161], v[198:201], v[84:87]
	v_mfma_f32_16x16x32_bf16 v[76:79], v[144:147], v[210:213], v[76:79]
	v_mfma_f32_16x16x32_bf16 v[68:71], v[158:161], v[210:213], v[68:71]
	v_mfma_f32_16x16x32_bf16 v[124:127], v[154:157], v[186:189], v[124:127]
	v_mfma_f32_16x16x32_bf16 v[116:119], v[162:165], v[186:189], v[116:119]
	v_mfma_f32_16x16x32_bf16 v[108:111], v[154:157], v[194:197], v[108:111]
	v_mfma_f32_16x16x32_bf16 v[100:103], v[162:165], v[194:197], v[100:103]
	v_mfma_f32_16x16x32_bf16 v[92:95], v[154:157], v[206:209], v[92:95]
	v_mfma_f32_16x16x32_bf16 v[84:87], v[162:165], v[206:209], v[84:87]
	v_mfma_f32_16x16x32_bf16 v[76:79], v[154:157], v[214:217], v[76:79]
	v_mfma_f32_16x16x32_bf16 v[68:71], v[162:165], v[214:217], v[68:71]
	v_mfma_f32_16x16x32_bf16 v[120:123], v[166:169], v[182:185], v[120:123]
	v_mfma_f32_16x16x32_bf16 v[112:115], v[174:177], v[182:185], v[112:115]
	v_mfma_f32_16x16x32_bf16 v[104:107], v[166:169], v[190:193], v[104:107]
	v_mfma_f32_16x16x32_bf16 v[96:99], v[174:177], v[190:193], v[96:99]
	v_mfma_f32_16x16x32_bf16 v[88:91], v[166:169], v[198:201], v[88:91]
	v_mfma_f32_16x16x32_bf16 v[80:83], v[174:177], v[198:201], v[80:83]
	v_mfma_f32_16x16x32_bf16 v[72:75], v[166:169], v[210:213], v[72:75]
	v_mfma_f32_16x16x32_bf16 v[64:67], v[174:177], v[210:213], v[64:67]
	v_mfma_f32_16x16x32_bf16 v[120:123], v[170:173], v[186:189], v[120:123]
	v_mfma_f32_16x16x32_bf16 v[112:115], v[178:181], v[186:189], v[112:115]
	v_mfma_f32_16x16x32_bf16 v[104:107], v[170:173], v[194:197], v[104:107]
	v_mfma_f32_16x16x32_bf16 v[96:99], v[178:181], v[194:197], v[96:99]
	v_mfma_f32_16x16x32_bf16 v[88:91], v[170:173], v[206:209], v[88:91]
	v_mfma_f32_16x16x32_bf16 v[80:83], v[178:181], v[206:209], v[80:83]
	v_mfma_f32_16x16x32_bf16 v[72:75], v[170:173], v[214:217], v[72:75]
	v_mfma_f32_16x16x32_bf16 v[64:67], v[178:181], v[214:217], v[64:67]
	s_barrier
	s_add_i32 s79, s68, s33
	v_lshl_add_u64 v[202:203], s[34:35], 0, v[132:133]
	s_mov_b32 m0, s79
	ds_read_b128 v[182:185], v153 offset:16384
	ds_read_b128 v[186:189], v153 offset:17408
	ds_read_b128 v[190:193], v153 offset:18432
	ds_read_b128 v[194:197], v153 offset:19456
	ds_read_b128 v[198:201], v153 offset:20480
	ds_read_b128 v[206:209], v153 offset:21504
	ds_read_b128 v[210:213], v153 offset:22528
	ds_read_b128 v[214:217], v153 offset:23552
	global_load_lds_dwordx4 v[202:203], off
	s_add_i32 m0, s79, 0x2000
	s_add_u32 s80, s34, 0x40000
	v_lshl_add_u64 v[218:219], s[34:35], 0, v[128:129]
	s_addc_u32 s81, s35, 0
	s_add_i32 s79, s69, s33
	global_load_lds_dwordx4 v[218:219], off
	v_lshl_add_u64 v[220:221], s[80:81], 0, v[132:133]
	s_mov_b32 m0, s79
	v_lshl_add_u64 v[222:223], s[38:39], 0, v[130:131]
	global_load_lds_dwordx4 v[220:221], off
	v_lshl_add_u64 v[220:221], s[80:81], 0, v[128:129]
	s_add_i32 m0, s79, 0x2000
	s_nop 0
	global_load_lds_dwordx4 v[220:221], off
	v_lshl_add_u64 v[220:221], s[38:39], 0, v[134:135]
	s_mov_b32 m0, s29
	s_nop 0
	global_load_lds_dwordx4 v[220:221], off
	s_mov_b32 m0, s44
	s_nop 0
	global_load_lds_dwordx4 v[222:223], off
	s_waitcnt vmcnt(8)
	s_waitcnt lgkmcnt(0)
	s_barrier
; #define PG8_STAGE(bufoff, gbase, voff) do { _Pragma("unroll") for (int _i = 0; _i < 2; ++_i) \
;         __builtin_amdgcn_global_load_lds((const unsigned*)((const char*)(gbase) + (voff)[_i]), (PG8_LAS unsigned*)(lds + (bufoff) + ldsw + _i * 8192), 16, 0, 0); } while (0)
; #define PG8_LDA(dst, b, h) do { _Pragma("unroll") for (int m = 0; m < 4; ++m) _Pragma("unroll") for (int k = 0; k < 2; ++k) dst[m][k] = *(const PG8_LAS bf16x8*)(lds + PG8_SA(b, h) + aoff + m * 2048 + k * 1024); } while (0)
; #define PG8_LDB(dst, b, h) do { _Pragma("unroll") for (int n = 0; n < 2; ++n) _Pragma("unroll") for (int k = 0; k < 2; ++k) dst[n][k] = *(const PG8_LAS bf16x8*)(lds + PG8_SB(b, h) + boff + n * 2048 + k * 1024); } while (0)
; #define PG8_MMA(ai, bj, At, Bt) do { __builtin_amdgcn_s_setprio(1); _Pragma("unroll") for (int m = 0; m < 4; ++m) _Pragma("unroll") for (int n = 0; n < 2; ++n) _Pragma("unroll") for (int k = 0; k < 2; ++k) \
;         acc[ai][bj][m][n] = __builtin_amdgcn_mfma_f32_16x16x32_bf16(Bt[n][k], At[m][k], acc[ai][bj][m][n], 0, 0, 0); __builtin_amdgcn_s_setprio(0); } while (0)
; template <class Epi, class Sched, bool ALIGN_EPI = false, bool SP2 = false>
; __device__ __forceinline__ void gemm_phase(PG8_LAS unsigned char* lds, const Gemm g, const Sched& S, const Epi& E, const int wid) {
;     ...
;             if constexpr (SP2) {
;             PG8_LDB(B0, 0, 0); PG8_LDB(B1, 0, 1); PG8_SCHED; PG8_LDA(At, 0, 0); PG8_STAGE(PG8_SA(1, 1), a1 + hstep, voffA);
;             PG8_WAIT_V(8); PG8_WAIT_L(0); PG8_BAR; PG8_MMA(0, 0, At, B0); PG8_MMA(0, 1, At, B1); PG8_BAR; PG8_SCHED;
;             PG8_LDA(At, 0, 1); PG8_STAGE(PG8_SB(0, 0), b2, voffB); PG8_STAGE(PG8_SB(0, 1), b2 + hstep, voffB); PG8_STAGE(PG8_SA(0, 0), a2, voffA);
;             PG8_WAIT_V(8); PG8_WAIT_L(0); PG8_BAR; PG8_MMA(1, 0, At, B0); PG8_MMA(1, 1, At, B1); PG8_BAR; PG8_SCHED;
;             PG8_LDB(B0, 1, 0); PG8_LDB(B1, 1, 1); PG8_SCHED; PG8_LDA(At, 1, 0); PG8_STAGE(PG8_SA(0, 1), a2 + hstep, voffA);
;             PG8_WAIT_V(8); PG8_WAIT_L(0); PG8_BAR; PG8_MMA(0, 0, At, B0); PG8_MMA(0, 1, At, B1); PG8_BAR; PG8_SCHED;
;             PG8_LDA(At, 1, 1); PG8_STAGE(PG8_SB(1, 0), b3, voffB); PG8_STAGE(PG8_SB(1, 1), b3 + hstep, voffB); PG8_STAGE(PG8_SA(1, 0), a3, voffA);
;             PG8_WAIT_V(8); PG8_WAIT_L(0); PG8_BAR; PG8_MMA(1, 0, At, B0); PG8_MMA(1, 1, At, B1); PG8_BAR; PG8_SCHED;
	s_waitcnt lgkmcnt(0)
	v_mfma_f32_16x16x32_bf16 v[60:63], v[144:147], v[182:185], v[60:63]
	v_mfma_f32_16x16x32_bf16 v[52:55], v[158:161], v[182:185], v[52:55]
	v_mfma_f32_16x16x32_bf16 v[44:47], v[144:147], v[190:193], v[44:47]
	v_mfma_f32_16x16x32_bf16 v[36:39], v[158:161], v[190:193], v[36:39]
	v_mfma_f32_16x16x32_bf16 v[28:31], v[144:147], v[198:201], v[28:31]
	v_mfma_f32_16x16x32_bf16 v[20:23], v[158:161], v[198:201], v[20:23]
	v_mfma_f32_16x16x32_bf16 v[12:15], v[144:147], v[210:213], v[12:15]
	v_mfma_f32_16x16x32_bf16 v[4:7], v[158:161], v[210:213], v[4:7]
	v_mfma_f32_16x16x32_bf16 v[60:63], v[154:157], v[186:189], v[60:63]
	v_mfma_f32_16x16x32_bf16 v[52:55], v[162:165], v[186:189], v[52:55]
	v_mfma_f32_16x16x32_bf16 v[44:47], v[154:157], v[194:197], v[44:47]
	v_mfma_f32_16x16x32_bf16 v[36:39], v[162:165], v[194:197], v[36:39]
	v_mfma_f32_16x16x32_bf16 v[28:31], v[154:157], v[206:209], v[28:31]
	v_mfma_f32_16x16x32_bf16 v[20:23], v[162:165], v[206:209], v[20:23]
	v_mfma_f32_16x16x32_bf16 v[12:15], v[154:157], v[214:217], v[12:15]
	v_mfma_f32_16x16x32_bf16 v[4:7], v[162:165], v[214:217], v[4:7]
	v_mfma_f32_16x16x32_bf16 v[56:59], v[166:169], v[182:185], v[56:59]
	v_mfma_f32_16x16x32_bf16 v[48:51], v[174:177], v[182:185], v[48:51]
	v_mfma_f32_16x16x32_bf16 v[40:43], v[166:169], v[190:193], v[40:43]
	v_mfma_f32_16x16x32_bf16 v[32:35], v[174:177], v[190:193], v[32:35]
	v_mfma_f32_16x16x32_bf16 v[24:27], v[166:169], v[198:201], v[24:27]
	v_mfma_f32_16x16x32_bf16 v[16:19], v[174:177], v[198:201], v[16:19]
	v_mfma_f32_16x16x32_bf16 v[8:11], v[166:169], v[210:213], v[8:11]
	v_mfma_f32_16x16x32_bf16 v[0:3], v[174:177], v[210:213], v[0:3]
	v_mfma_f32_16x16x32_bf16 v[56:59], v[170:173], v[186:189], v[56:59]
	v_mfma_f32_16x16x32_bf16 v[48:51], v[178:181], v[186:189], v[48:51]
	v_mfma_f32_16x16x32_bf16 v[40:43], v[170:173], v[194:197], v[40:43]
	v_mfma_f32_16x16x32_bf16 v[32:35], v[178:181], v[194:197], v[32:35]
	v_mfma_f32_16x16x32_bf16 v[24:27], v[170:173], v[206:209], v[24:27]
	v_mfma_f32_16x16x32_bf16 v[16:19], v[178:181], v[206:209], v[16:19]
	v_mfma_f32_16x16x32_bf16 v[8:11], v[170:173], v[214:217], v[8:11]
	v_mfma_f32_16x16x32_bf16 v[0:3], v[178:181], v[214:217], v[0:3]
	s_barrier
	s_add_i32 s79, 0, 0x18000
	s_add_i32 s80, 0, 0x1c000
	v_add_u32_e32 v162, s79, v149
	v_add_u32_e32 v178, s80, v149
	ds_read_b128 v[144:147], v162
	ds_read_b128 v[154:157], v162 offset:1024
	ds_read_b128 v[158:161], v162 offset:2048
	ds_read_b128 v[162:165], v162 offset:3072
	ds_read_b128 v[166:169], v178
	ds_read_b128 v[170:173], v178 offset:1024
	ds_read_b128 v[174:177], v178 offset:2048
	ds_read_b128 v[178:181], v178 offset:3072
	s_add_u32 s38, s38, 0x40000
	s_addc_u32 s39, s39, 0
	s_mov_b32 m0, s45
	v_lshl_add_u64 v[224:225], s[38:39], 0, v[134:135]
	ds_read_b128 v[182:185], v153 offset:32768
	ds_read_b128 v[186:189], v153 offset:33792
	ds_read_b128 v[190:193], v153 offset:34816
	ds_read_b128 v[194:197], v153 offset:35840
	ds_read_b128 v[198:201], v153 offset:36864
	ds_read_b128 v[206:209], v153 offset:37888
	ds_read_b128 v[210:213], v153 offset:38912
	ds_read_b128 v[214:217], v153 offset:39936
	global_load_lds_dwordx4 v[224:225], off
	v_lshl_add_u64 v[224:225], s[38:39], 0, v[130:131]
	s_mov_b32 m0, s46
	s_nop 0
	global_load_lds_dwordx4 v[224:225], off
	s_waitcnt vmcnt(8)
	s_waitcnt lgkmcnt(0)
	s_barrier
	s_waitcnt lgkmcnt(0)
	v_mfma_f32_16x16x32_bf16 v[124:127], v[144:147], v[182:185], v[124:127]
	v_mfma_f32_16x16x32_bf16 v[116:119], v[158:161], v[182:185], v[116:119]
	v_mfma_f32_16x16x32_bf16 v[108:111], v[144:147], v[190:193], v[108:111]
	v_mfma_f32_16x16x32_bf16 v[100:103], v[158:161], v[190:193], v[100:103]
	v_mfma_f32_16x16x32_bf16 v[92:95], v[144:147], v[198:201], v[92:95]
	v_mfma_f32_16x16x32_bf16 v[84:87], v[158:161], v[198:201], v[84:87]
	v_mfma_f32_16x16x32_bf16 v[76:79], v[144:147], v[210:213], v[76:79]
	v_mfma_f32_16x16x32_bf16 v[68:71], v[158:161], v[210:213], v[68:71]
	v_mfma_f32_16x16x32_bf16 v[124:127], v[154:157], v[186:189], v[124:127]
	v_mfma_f32_16x16x32_bf16 v[116:119], v[162:165], v[186:189], v[116:119]
	v_mfma_f32_16x16x32_bf16 v[108:111], v[154:157], v[194:197], v[108:111]
	v_mfma_f32_16x16x32_bf16 v[100:103], v[162:165], v[194:197], v[100:103]
	v_mfma_f32_16x16x32_bf16 v[92:95], v[154:157], v[206:209], v[92:95]
	v_mfma_f32_16x16x32_bf16 v[84:87], v[162:165], v[206:209], v[84:87]
	v_mfma_f32_16x16x32_bf16 v[76:79], v[154:157], v[214:217], v[76:79]
	v_mfma_f32_16x16x32_bf16 v[68:71], v[162:165], v[214:217], v[68:71]
	v_mfma_f32_16x16x32_bf16 v[120:123], v[166:169], v[182:185], v[120:123]
	v_mfma_f32_16x16x32_bf16 v[112:115], v[174:177], v[182:185], v[112:115]
	v_mfma_f32_16x16x32_bf16 v[104:107], v[166:169], v[190:193], v[104:107]
	v_mfma_f32_16x16x32_bf16 v[96:99], v[174:177], v[190:193], v[96:99]
	v_mfma_f32_16x16x32_bf16 v[88:91], v[166:169], v[198:201], v[88:91]
	v_mfma_f32_16x16x32_bf16 v[80:83], v[174:177], v[198:201], v[80:83]
	v_mfma_f32_16x16x32_bf16 v[72:75], v[166:169], v[210:213], v[72:75]
	v_mfma_f32_16x16x32_bf16 v[64:67], v[174:177], v[210:213], v[64:67]
	v_mfma_f32_16x16x32_bf16 v[120:123], v[170:173], v[186:189], v[120:123]
	v_mfma_f32_16x16x32_bf16 v[112:115], v[178:181], v[186:189], v[112:115]
	v_mfma_f32_16x16x32_bf16 v[104:107], v[170:173], v[194:197], v[104:107]
	v_mfma_f32_16x16x32_bf16 v[96:99], v[178:181], v[194:197], v[96:99]
	v_mfma_f32_16x16x32_bf16 v[88:91], v[170:173], v[206:209], v[88:91]
	v_mfma_f32_16x16x32_bf16 v[80:83], v[178:181], v[206:209], v[80:83]
	v_mfma_f32_16x16x32_bf16 v[72:75], v[170:173], v[214:217], v[72:75]
	v_mfma_f32_16x16x32_bf16 v[64:67], v[178:181], v[214:217], v[64:67]
	s_barrier
; #define PG8_STAGE(bufoff, gbase, voff) do { _Pragma("unroll") for (int _i = 0; _i < 2; ++_i) \
;         __builtin_amdgcn_global_load_lds((const unsigned*)((const char*)(gbase) + (voff)[_i]), (PG8_LAS unsigned*)(lds + (bufoff) + ldsw + _i * 8192), 16, 0, 0); } while (0)
; #define PG8_LDA(dst, b, h) do { _Pragma("unroll") for (int m = 0; m < 4; ++m) _Pragma("unroll") for (int k = 0; k < 2; ++k) dst[m][k] = *(const PG8_LAS bf16x8*)(lds + PG8_SA(b, h) + aoff + m * 2048 + k * 1024); } while (0)
; #define PG8_LDB(dst, b, h) do { _Pragma("unroll") for (int n = 0; n < 2; ++n) _Pragma("unroll") for (int k = 0; k < 2; ++k) dst[n][k] = *(const PG8_LAS bf16x8*)(lds + PG8_SB(b, h) + boff + n * 2048 + k * 1024); } while (0)
; #define PG8_MMA(ai, bj, At, Bt) do { __builtin_amdgcn_s_setprio(1); _Pragma("unroll") for (int m = 0; m < 4; ++m) _Pragma("unroll") for (int n = 0; n < 2; ++n) _Pragma("unroll") for (int k = 0; k < 2; ++k) \
;         acc[ai][bj][m][n] = __builtin_amdgcn_mfma_f32_16x16x32_bf16(Bt[n][k], At[m][k], acc[ai][bj][m][n], 0, 0, 0); __builtin_amdgcn_s_setprio(0); } while (0)
; template <class Epi, class Sched, bool ALIGN_EPI = false, bool SP2 = false>
; __device__ __forceinline__ void gemm_phase(PG8_LAS unsigned char* lds, const Gemm g, const Sched& S, const Epi& E, const int wid) {
;     ...
;             if constexpr (SP2) {
;             PG8_LDB(B0, 0, 0); PG8_LDB(B1, 0, 1); PG8_SCHED; PG8_LDA(At, 0, 0); PG8_STAGE(PG8_SA(1, 1), a1 + hstep, voffA);
;             PG8_WAIT_V(8); PG8_WAIT_L(0); PG8_BAR; PG8_MMA(0, 0, At, B0); PG8_MMA(0, 1, At, B1); PG8_BAR; PG8_SCHED;
;             PG8_LDA(At, 0, 1); PG8_STAGE(PG8_SB(0, 0), b2, voffB); PG8_STAGE(PG8_SB(0, 1), b2 + hstep, voffB); PG8_STAGE(PG8_SA(0, 0), a2, voffA);
;             PG8_WAIT_V(8); PG8_WAIT_L(0); PG8_BAR; PG8_MMA(1, 0, At, B0); PG8_MMA(1, 1, At, B1); PG8_BAR; PG8_SCHED;
;             PG8_LDB(B0, 1, 0); PG8_LDB(B1, 1, 1); PG8_SCHED; PG8_LDA(At, 1, 0); PG8_STAGE(PG8_SA(0, 1), a2 + hstep, voffA);
;             PG8_WAIT_V(8); PG8_WAIT_L(0); PG8_BAR; PG8_MMA(0, 0, At, B0); PG8_MMA(0, 1, At, B1); PG8_BAR; PG8_SCHED;
;             PG8_LDA(At, 1, 1); PG8_STAGE(PG8_SB(1, 0), b3, voffB); PG8_STAGE(PG8_SB(1, 1), b3 + hstep, voffB); PG8_STAGE(PG8_SA(1, 0), a3, voffA);
;             PG8_WAIT_V(8); PG8_WAIT_L(0); PG8_BAR; PG8_MMA(1, 0, At, B0); PG8_MMA(1, 1, At, B1); PG8_BAR; PG8_SCHED;
	s_add_i32 s38, s79, s33
	v_lshl_add_u64 v[202:203], v[202:203], 0, s[10:11]
	s_mov_b32 m0, s38
	ds_read_b128 v[182:185], v153 offset:49152
	ds_read_b128 v[186:189], v153 offset:50176
	ds_read_b128 v[190:193], v153 offset:51200
	ds_read_b128 v[194:197], v153 offset:52224
	ds_read_b128 v[198:201], v153 offset:53248
	ds_read_b128 v[206:209], v153 offset:54272
	ds_read_b128 v[210:213], v153 offset:55296
	ds_read_b128 v[214:217], v153 offset:56320
	global_load_lds_dwordx4 v[202:203], off
	s_add_i32 m0, s38, 0x2000
	s_add_u32 s34, s34, 0x40080
	v_lshl_add_u64 v[202:203], v[218:219], 0, s[10:11]
	s_addc_u32 s35, s35, 0
	s_add_i32 s38, s80, s33
	global_load_lds_dwordx4 v[202:203], off
	v_lshl_add_u64 v[202:203], s[34:35], 0, v[132:133]
	s_mov_b32 m0, s38
	s_nop 0
	global_load_lds_dwordx4 v[202:203], off
	v_lshl_add_u64 v[202:203], s[34:35], 0, v[128:129]
	s_add_i32 m0, s38, 0x2000
	s_nop 0
	global_load_lds_dwordx4 v[202:203], off
	v_lshl_add_u64 v[202:203], v[220:221], 0, s[10:11]
	s_mov_b32 m0, s48
	s_nop 0
	global_load_lds_dwordx4 v[202:203], off
	v_lshl_add_u64 v[202:203], v[222:223], 0, s[10:11]
	s_mov_b32 m0, s49
	s_nop 0
	global_load_lds_dwordx4 v[202:203], off
	s_waitcnt vmcnt(8)
	s_waitcnt lgkmcnt(0)
	s_barrier
	s_waitcnt lgkmcnt(0)
	v_mfma_f32_16x16x32_bf16 v[60:63], v[144:147], v[182:185], v[60:63]
	v_mfma_f32_16x16x32_bf16 v[52:55], v[158:161], v[182:185], v[52:55]
	v_mfma_f32_16x16x32_bf16 v[44:47], v[144:147], v[190:193], v[44:47]
	v_mfma_f32_16x16x32_bf16 v[36:39], v[158:161], v[190:193], v[36:39]
	v_mfma_f32_16x16x32_bf16 v[28:31], v[144:147], v[198:201], v[28:31]
	v_mfma_f32_16x16x32_bf16 v[20:23], v[158:161], v[198:201], v[20:23]
	v_mfma_f32_16x16x32_bf16 v[12:15], v[144:147], v[210:213], v[12:15]
	v_mfma_f32_16x16x32_bf16 v[4:7], v[158:161], v[210:213], v[4:7]
	v_mfma_f32_16x16x32_bf16 v[60:63], v[154:157], v[186:189], v[60:63]
	v_mfma_f32_16x16x32_bf16 v[52:55], v[162:165], v[186:189], v[52:55]
	v_mfma_f32_16x16x32_bf16 v[44:47], v[154:157], v[194:197], v[44:47]
	v_mfma_f32_16x16x32_bf16 v[36:39], v[162:165], v[194:197], v[36:39]
	v_mfma_f32_16x16x32_bf16 v[28:31], v[154:157], v[206:209], v[28:31]
	v_mfma_f32_16x16x32_bf16 v[20:23], v[162:165], v[206:209], v[20:23]
	v_mfma_f32_16x16x32_bf16 v[12:15], v[154:157], v[214:217], v[12:15]
	v_mfma_f32_16x16x32_bf16 v[4:7], v[162:165], v[214:217], v[4:7]
	v_mfma_f32_16x16x32_bf16 v[56:59], v[166:169], v[182:185], v[56:59]
	v_mfma_f32_16x16x32_bf16 v[48:51], v[174:177], v[182:185], v[48:51]
	v_mfma_f32_16x16x32_bf16 v[40:43], v[166:169], v[190:193], v[40:43]
	v_mfma_f32_16x16x32_bf16 v[32:35], v[174:177], v[190:193], v[32:35]
	v_mfma_f32_16x16x32_bf16 v[24:27], v[166:169], v[198:201], v[24:27]
	v_mfma_f32_16x16x32_bf16 v[16:19], v[174:177], v[198:201], v[16:19]
	v_mfma_f32_16x16x32_bf16 v[8:11], v[166:169], v[210:213], v[8:11]
	v_mfma_f32_16x16x32_bf16 v[0:3], v[174:177], v[210:213], v[0:3]
	v_mfma_f32_16x16x32_bf16 v[56:59], v[170:173], v[186:189], v[56:59]
	v_mfma_f32_16x16x32_bf16 v[48:51], v[178:181], v[186:189], v[48:51]
	v_mfma_f32_16x16x32_bf16 v[40:43], v[170:173], v[194:197], v[40:43]
	v_mfma_f32_16x16x32_bf16 v[32:35], v[178:181], v[194:197], v[32:35]
	v_mfma_f32_16x16x32_bf16 v[24:27], v[170:173], v[206:209], v[24:27]
	v_mfma_f32_16x16x32_bf16 v[16:19], v[178:181], v[206:209], v[16:19]
	v_mfma_f32_16x16x32_bf16 v[8:11], v[170:173], v[214:217], v[8:11]
	v_mfma_f32_16x16x32_bf16 v[0:3], v[178:181], v[214:217], v[0:3]
	s_barrier
	s_add_i32 s77, s77, 2
	s_add_u32 s30, s30, 0x100
	s_addc_u32 s31, s31, 0
	s_add_u32 s75, s75, 0x100
	s_addc_u32 s76, s76, 0
	s_cmp_gt_u32 s77, 13
	s_cbranch_scc0 .LBB0_150
	s_and_b64 vcc, exec, s[16:17]
	s_cbranch_vccz .LBB0_153
	s_barrier

; #define PG8_WAIT_V(n) asm volatile("s_waitcnt vmcnt(" #n ")" ::: "memory")
; #define PG8_BAR __builtin_amdgcn_s_barrier()
; template <class Epi, class Sched, bool ALIGN_EPI = false, bool SP2 = false>
; __device__ __forceinline__ void gemm_phase(PG8_LAS unsigned char* lds, const Gemm g, const Sched& S, const Epi& E, const int wid) {
;     ...
;     PG8_WAIT_V(0);
;     if constexpr (!ALIGN_EPI) { if (wr == 0) PG8_BAR; }
;     PG8_BAR;
.LBB0_156:
	s_setprio 0
	s_waitcnt vmcnt(0)
	s_barrier

; __device__ __forceinline__ int lane_now() { int l; asm volatile("v_mbcnt_lo_u32_b32 %0, -1, 0\n\tv_mbcnt_hi_u32_b32 %0, -1, %0" : "=v"(l)); return l; }
; #define PG8_STAGE(bufoff, gbase, voff) do { _Pragma("unroll") for (int _i = 0; _i < 2; ++_i) \
;         __builtin_amdgcn_global_load_lds((const unsigned*)((const char*)(gbase) + (voff)[_i]), (PG8_LAS unsigned*)(lds + (bufoff) + ldsw + _i * 8192), 16, 0, 0); } while (0)
; #define PG8_BAR __builtin_amdgcn_s_barrier()
; #define lane (lane_now())
; template <class Epi, class Sched, bool ALIGN_EPI = false, bool SP2 = false>
; __device__ __forceinline__ void gemm_phase(PG8_LAS unsigned char* lds, const Gemm g, const Sched& S, const Epi& E, const int wid) {
;     const int lane = lane_now(), tid = wid * 64 + lane, wr = wid >> 2, wc = wid & 3, fr = lane & 15, fq = lane >> 4;
;     const int K = g.K, nt = K / BK;
;     unsigned voffA[2], voffB[2];
; #pragma unroll
;     for (int i = 0; i < 2; ++i) { int R, C; stage_rc(tid * 16 + i * 8192, R, C); const int Rb = Epi::PERM ? ((R & ~31) + perm32(R & 31)) : R;
;         voffA[i] = (unsigned)(R * K + C) * 2u; voffB[i] = (unsigned)(Rb * K + C) * 2u; }
;     const size_t kstep = (size_t)(BK * 2);
;     const size_t hstep = (size_t)HALF * K * 2;
;     const size_t tstep = 2 * hstep;
;     const unsigned ldsw = (unsigned)wid * 1024u;
;     const int aoff = lds_byte(wr * 64 + fr, fq * 8), boff = lds_byte(wc * 32 + fr, fq * 8);
;     ...
;     Unit cur, nxt; int ui = 0;
;     if (!S.next(0, cur)) return;
;     f32x4 acc[2][2][4][2];
; #pragma unroll
;     for (int a = 0; a < 2; ++a)
; #pragma unroll
;         for (int b = 0; b < 2; ++b)
; #pragma unroll
;             for (int m = 0; m < 4; ++m)
; #pragma unroll
;                 for (int n = 0; n < 2; ++n) acc[a][b][m][n] = (f32x4){0.f, 0.f, 0.f, 0.f};
;     bf16x8 At[4][2], B0[2][2], B1[2][2];
;     const char* cA = (const char*)g.A + (size_t)cur.pm * tstep; const char* cB = (const char*)g.Bt + (size_t)cur.pn * tstep;
;     S.a_ready(cur);
;     if constexpr (SP2) {
;         PG8_STAGE(PG8_SB(0, 0), cB, voffB); PG8_STAGE(PG8_SB(0, 1), cB + hstep, voffB); PG8_STAGE(PG8_SA(0, 0), cA, voffA); PG8_STAGE(PG8_SA(0, 1), cA + hstep, voffA);
;         if (wr == 1) PG8_BAR;
.LBB0_216:
	v_lshl_add_u32 v0, v13, 4, s33
	v_ashrrev_i32_e32 v1, 31, v0
	v_lshrrev_b32_e32 v1, 22, v1
	v_add_u32_e32 v1, v0, v1
	v_ashrrev_i32_e32 v8, 10, v1
	v_mul_i32_i24_e32 v1, 0x400, v8
	v_sub_u32_e32 v1, v0, v1
	v_lshrrev_b32_e32 v2, 4, v1
	v_bitop3_b32 v1, v2, v1, 32 bitop3:0x6c
	v_ashrrev_i32_e32 v3, 31, v1
	v_lshrrev_b32_e32 v3, 26, v3
	v_lshlrev_b32_e32 v2, 3, v8
	v_add_u32_e32 v3, v1, v3
	v_and_b32_e32 v2, -16, v2
	v_ashrrev_i32_e32 v10, 6, v3
	v_and_b32_e32 v3, 0xc0, v3
	v_add_u32_e32 v2, v10, v2
	v_lshlrev_b32_e32 v4, 5, v8
	v_sub_u32_e32 v1, v1, v3
	v_mov_b32_e32 v3, 1
	s_ashr_i32 s5, s7, 3
	v_and_b32_e32 v9, 32, v4
	v_ashrrev_i16_sdwa v1, v3, sext(v1) dst_sel:DWORD dst_unused:UNUSED_PAD src0_sel:DWORD src1_sel:BYTE_0
	v_lshlrev_b32_e32 v4, 1, v2
	v_lshrrev_b32_e32 v5, 2, v2
	v_and_b32_e32 v6, 3, v10
	s_mov_b32 s7, 0xffffe0
	v_bfe_i32 v11, v1, 0, 16
	v_and_b32_e32 v4, 24, v4
	v_and_b32_e32 v5, 4, v5
	v_and_or_b32 v6, v2, s7, v6
	s_movk_i32 s4, 0xb00
	v_add_u32_e32 v1, v9, v11
	v_or3_b32 v4, v6, v5, v4
	v_mul_lo_u32 v2, v2, s4
	v_add_lshl_u32 v128, v1, v2, 1
	v_mul_u32_u24_e32 v2, 0xb00, v4
	v_add_u32_e32 v0, 0x2000, v0
	v_add_lshl_u32 v130, v2, v1, 1
	v_ashrrev_i32_e32 v1, 31, v0
	v_lshrrev_b32_e32 v1, 22, v1
	v_add_u32_e32 v1, v0, v1
	v_ashrrev_i32_e32 v12, 10, v1
	v_mul_i32_i24_e32 v1, 0x400, v12
	v_sub_u32_e32 v0, v0, v1
	v_lshrrev_b32_e32 v1, 4, v0
	v_bitop3_b32 v0, v1, v0, 32 bitop3:0x6c
	s_add_u32 s35, s92, 0xc00000
	v_ashrrev_i32_e32 v2, 31, v0
	s_addc_u32 s38, s93, 0
	v_lshrrev_b32_e32 v2, 26, v2
	s_add_i32 s5, s6, s5
	v_lshlrev_b32_e32 v1, 3, v12
	v_add_u32_e32 v2, v0, v2
	s_ashr_i32 s6, s5, 31
	v_and_b32_e32 v1, -16, v1
	v_ashrrev_i32_e32 v14, 6, v2
	v_lshlrev_b32_e32 v4, 5, v12
	s_lshr_b32 s6, s6, 28
	v_add_u32_e32 v1, v14, v1
	v_and_b32_e32 v15, 32, v4
	v_and_b32_e32 v4, 3, v14
	s_add_i32 s6, s5, s6
	v_and_or_b32 v4, v1, s7, v4
	s_ashr_i32 s7, s6, 4
	s_and_b32 s6, s6, -16
	s_sub_i32 s6, s5, s6
	s_bfe_i32 s5, s6, 0x80000
	s_bfe_u32 s5, s5, 0x2000d
	s_add_i32 s10, s6, s5
	v_and_b32_e32 v2, 0xffc0, v2
	s_bfe_i32 s5, s10, 0x80000
	s_and_b32 s10, s10, 0xfc
	v_sub_u32_e32 v0, v0, v2
	s_sub_i32 s6, s6, s10
	v_lshrrev_b16_e32 v2, 7, v0
	s_lshl_b32 s7, s7, 2
	s_sext_i32_i16 s11, s5
	s_sext_i32_i8 s6, s6
	v_and_b32_e32 v2, 1, v2
	s_add_i32 s70, s7, s6
	s_ashr_i32 s6, s11, 2
	v_add_u16_e32 v0, v0, v2
	s_lshr_b32 s5, s11, 2
	s_mul_hi_i32 s7, s6, 0x160000
	s_mul_i32 s6, s6, 0x160000
	v_ashrrev_i16_sdwa v0, v3, sext(v0) dst_sel:DWORD dst_unused:UNUSED_PAD src0_sel:DWORD src1_sel:BYTE_0
	v_lshlrev_b32_e32 v2, 1, v1
	v_lshrrev_b32_e32 v3, 2, v1
	s_add_u32 s26, s35, s6
	v_bfe_i32 v16, v0, 0, 16
	v_and_b32_e32 v2, 24, v2
	v_and_b32_e32 v3, 4, v3
	s_addc_u32 s27, s38, s7
	s_add_i32 s39, s33, 0
	v_add_u32_e32 v0, v15, v16
	v_or3_b32 v2, v4, v3, v2
	v_mul_lo_u32 v1, v1, s4
	s_add_i32 m0, s39, 0x10000
	v_add_lshl_u32 v132, v0, v1, 1
	v_mul_u32_u24_e32 v1, 0xb00, v2
	global_load_lds_dwordx4 v130, s[26:27]
	s_add_i32 m0, s39, 0x12000
	v_add_lshl_u32 v134, v1, v0, 1
	s_add_u32 s6, s26, 0xb0000
	global_load_lds_dwordx4 v134, s[26:27]
	s_addc_u32 s7, s27, 0
	s_add_i32 m0, s39, 0x14000
	s_mul_i32 s16, s70, 0x160000
	global_load_lds_dwordx4 v130, s[6:7]
	s_add_i32 m0, s39, 0x16000
	s_mul_hi_i32 s10, s70, 0x160000
	s_add_u32 s24, s96, s16
	s_addc_u32 s25, s97, s10
	s_add_i32 s40, s39, 0x2000
	global_load_lds_dwordx4 v134, s[6:7]
	s_mov_b32 m0, s39
	s_add_u32 s6, s24, 0xb0000
	global_load_lds_dwordx4 v128, s[24:25]
	s_mov_b32 m0, s40
	s_addc_u32 s7, s25, 0
	s_add_i32 s41, s39, 0x4000
	global_load_lds_dwordx4 v132, s[24:25]
	s_mov_b32 m0, s41
	s_add_i32 s42, s39, 0x6000
	global_load_lds_dwordx4 v128, s[6:7]
	s_mov_b32 m0, s42
	v_mov_b32_e32 v131, 0
	global_load_lds_dwordx4 v132, s[6:7]
	v_readlane_b32 s6, v244, 18
	v_mov_b32_e32 v135, v131
	v_mov_b32_e32 v129, v131
	v_mov_b32_e32 v133, v131
	s_cmp_eq_u32 s6, 1
	s_mov_b32 s43, 0
	v_lshl_add_u64 v[4:5], s[26:27], 0, v[130:131]
	v_lshl_add_u64 v[2:3], s[26:27], 0, v[134:135]
	v_lshl_add_u64 v[0:1], s[24:25], 0, v[128:129]
	s_cselect_b64 s[10:11], -1, 0
	s_cmp_lg_u32 s6, 1
	v_lshl_add_u64 v[6:7], s[24:25], 0, v[132:133]
	s_cbranch_scc1 .LBB0_218
	s_barrier
	s_setprio 1

; #define PG8_STAGE(bufoff, gbase, voff) do { _Pragma("unroll") for (int _i = 0; _i < 2; ++_i) \
;         __builtin_amdgcn_global_load_lds((const unsigned*)((const char*)(gbase) + (voff)[_i]), (PG8_LAS unsigned*)(lds + (bufoff) + ldsw + _i * 8192), 16, 0, 0); } while (0)
; #define PG8_LDA(dst, b, h) do { _Pragma("unroll") for (int m = 0; m < 4; ++m) _Pragma("unroll") for (int k = 0; k < 2; ++k) dst[m][k] = *(const PG8_LAS bf16x8*)(lds + PG8_SA(b, h) + aoff + m * 2048 + k * 1024); } while (0)
; #define PG8_LDB(dst, b, h) do { _Pragma("unroll") for (int n = 0; n < 2; ++n) _Pragma("unroll") for (int k = 0; k < 2; ++k) dst[n][k] = *(const PG8_LAS bf16x8*)(lds + PG8_SB(b, h) + boff + n * 2048 + k * 1024); } while (0)
; #define PG8_MMA(ai, bj, At, Bt) do { __builtin_amdgcn_s_setprio(1); _Pragma("unroll") for (int m = 0; m < 4; ++m) _Pragma("unroll") for (int n = 0; n < 2; ++n) _Pragma("unroll") for (int k = 0; k < 2; ++k) \
;         acc[ai][bj][m][n] = __builtin_amdgcn_mfma_f32_16x16x32_bf16(Bt[n][k], At[m][k], acc[ai][bj][m][n], 0, 0, 0); __builtin_amdgcn_s_setprio(0); } while (0)
; template <class Epi, class Sched, bool ALIGN_EPI = false, bool SP2 = false>
; __device__ __forceinline__ void gemm_phase(PG8_LAS unsigned char* lds, const Gemm g, const Sched& S, const Epi& E, const int wid) {
;     ...
;             if constexpr (SP2) {
;             PG8_LDB(B0, 0, 0); PG8_LDB(B1, 0, 1); PG8_SCHED; PG8_LDA(At, 0, 0); PG8_STAGE(PG8_SA(1, 1), a1 + hstep, voffA);
;             PG8_WAIT_V(8); PG8_WAIT_L(0); PG8_BAR; PG8_MMA(0, 0, At, B0); PG8_MMA(0, 1, At, B1); PG8_BAR; PG8_SCHED;
;             PG8_LDA(At, 0, 1); PG8_STAGE(PG8_SB(0, 0), b2, voffB); PG8_STAGE(PG8_SB(0, 1), b2 + hstep, voffB); PG8_STAGE(PG8_SA(0, 0), a2, voffA);
;             PG8_WAIT_V(8); PG8_WAIT_L(0); PG8_BAR; PG8_MMA(1, 0, At, B0); PG8_MMA(1, 1, At, B1); PG8_BAR; PG8_SCHED;
;             PG8_LDB(B0, 1, 0); PG8_LDB(B1, 1, 1); PG8_SCHED; PG8_LDA(At, 1, 0); PG8_STAGE(PG8_SA(0, 1), a2 + hstep, voffA);
;             PG8_WAIT_V(8); PG8_WAIT_L(0); PG8_BAR; PG8_MMA(0, 0, At, B0); PG8_MMA(0, 1, At, B1); PG8_BAR; PG8_SCHED;
;             PG8_LDA(At, 1, 1); PG8_STAGE(PG8_SB(1, 0), b3, voffB); PG8_STAGE(PG8_SB(1, 1), b3 + hstep, voffB); PG8_STAGE(PG8_SA(1, 0), a3, voffA);
;             PG8_WAIT_V(8); PG8_WAIT_L(0); PG8_BAR; PG8_MMA(1, 0, At, B0); PG8_MMA(1, 1, At, B1); PG8_BAR; PG8_SCHED;
.LBB0_232:
	ds_read_b128 v[144:147], v163
	ds_read_b128 v[148:151], v163 offset:1024
	ds_read_b128 v[152:155], v163 offset:2048
	ds_read_b128 v[156:159], v163 offset:3072
	ds_read_b128 v[166:169], v164
	ds_read_b128 v[170:173], v164 offset:1024
	ds_read_b128 v[174:177], v164 offset:2048
	ds_read_b128 v[178:181], v164 offset:3072
	s_add_u32 s26, s24, 0x100
	s_addc_u32 s27, s25, 0
	s_cmp_eq_u32 s75, 40
	s_cselect_b32 s31, s5, s27
	s_cselect_b32 s30, s4, s26
	s_cselect_b32 s29, s23, s73
	s_cselect_b32 s28, s22, s72
	v_lshl_add_u64 v[202:203], s[24:25], 0, v[136:137]
	s_add_i32 m0, s39, 0xc000
	ds_read_b128 v[182:185], v165
	ds_read_b128 v[186:189], v165 offset:1024
	ds_read_b128 v[190:193], v165 offset:2048
	ds_read_b128 v[194:197], v165 offset:3072
	ds_read_b128 v[198:201], v165 offset:4096
	ds_read_b128 v[206:209], v165 offset:5120
	ds_read_b128 v[210:213], v165 offset:6144
	ds_read_b128 v[214:217], v165 offset:7168
	global_load_lds_dwordx4 v[202:203], off
	v_lshl_add_u64 v[202:203], s[24:25], 0, v[138:139]
	s_add_i32 m0, s39, 0xe000
	s_nop 0
	global_load_lds_dwordx4 v[202:203], off
	s_waitcnt vmcnt(8)
	s_waitcnt lgkmcnt(0)
	s_barrier
	s_waitcnt lgkmcnt(0)
	v_mfma_f32_16x16x32_bf16 v[124:127], v[144:147], v[182:185], v[124:127]
	v_mfma_f32_16x16x32_bf16 v[120:123], v[152:155], v[182:185], v[120:123]
	v_mfma_f32_16x16x32_bf16 v[116:119], v[144:147], v[190:193], v[116:119]
	v_mfma_f32_16x16x32_bf16 v[112:115], v[152:155], v[190:193], v[112:115]
	v_mfma_f32_16x16x32_bf16 v[108:111], v[144:147], v[198:201], v[108:111]
	v_mfma_f32_16x16x32_bf16 v[104:107], v[152:155], v[198:201], v[104:107]
	v_mfma_f32_16x16x32_bf16 v[100:103], v[144:147], v[210:213], v[100:103]
	v_mfma_f32_16x16x32_bf16 v[96:99], v[152:155], v[210:213], v[96:99]
	v_mfma_f32_16x16x32_bf16 v[124:127], v[148:151], v[186:189], v[124:127]
	v_mfma_f32_16x16x32_bf16 v[120:123], v[156:159], v[186:189], v[120:123]
	v_mfma_f32_16x16x32_bf16 v[116:119], v[148:151], v[194:197], v[116:119]
	v_mfma_f32_16x16x32_bf16 v[112:115], v[156:159], v[194:197], v[112:115]
	v_mfma_f32_16x16x32_bf16 v[108:111], v[148:151], v[206:209], v[108:111]
	v_mfma_f32_16x16x32_bf16 v[104:107], v[156:159], v[206:209], v[104:107]
	v_mfma_f32_16x16x32_bf16 v[100:103], v[148:151], v[214:217], v[100:103]
	v_mfma_f32_16x16x32_bf16 v[96:99], v[156:159], v[214:217], v[96:99]
	v_mfma_f32_16x16x32_bf16 v[60:63], v[166:169], v[182:185], v[60:63]
	v_mfma_f32_16x16x32_bf16 v[56:59], v[174:177], v[182:185], v[56:59]
	v_mfma_f32_16x16x32_bf16 v[52:55], v[166:169], v[190:193], v[52:55]
	v_mfma_f32_16x16x32_bf16 v[48:51], v[174:177], v[190:193], v[48:51]
	v_mfma_f32_16x16x32_bf16 v[44:47], v[166:169], v[198:201], v[44:47]
	v_mfma_f32_16x16x32_bf16 v[40:43], v[174:177], v[198:201], v[40:43]
	v_mfma_f32_16x16x32_bf16 v[36:39], v[166:169], v[210:213], v[36:39]
	v_mfma_f32_16x16x32_bf16 v[32:35], v[174:177], v[210:213], v[32:35]
	v_mfma_f32_16x16x32_bf16 v[60:63], v[170:173], v[186:189], v[60:63]
	v_mfma_f32_16x16x32_bf16 v[56:59], v[178:181], v[186:189], v[56:59]
	v_mfma_f32_16x16x32_bf16 v[52:55], v[170:173], v[194:197], v[52:55]
	v_mfma_f32_16x16x32_bf16 v[48:51], v[178:181], v[194:197], v[48:51]
	v_mfma_f32_16x16x32_bf16 v[44:47], v[170:173], v[206:209], v[44:47]
	v_mfma_f32_16x16x32_bf16 v[40:43], v[178:181], v[206:209], v[40:43]
	v_mfma_f32_16x16x32_bf16 v[36:39], v[170:173], v[214:217], v[36:39]
	v_mfma_f32_16x16x32_bf16 v[32:35], v[178:181], v[214:217], v[32:35]
	s_barrier
	s_add_i32 s24, s50, s33
	v_lshl_add_u64 v[202:203], s[28:29], 0, v[130:131]
	s_mov_b32 m0, s24
	ds_read_b128 v[182:185], v165 offset:16384
	ds_read_b128 v[186:189], v165 offset:17408
	ds_read_b128 v[190:193], v165 offset:18432
	ds_read_b128 v[194:197], v165 offset:19456
	ds_read_b128 v[198:201], v165 offset:20480
	ds_read_b128 v[206:209], v165 offset:21504
	ds_read_b128 v[210:213], v165 offset:22528
	ds_read_b128 v[214:217], v165 offset:23552
	global_load_lds_dwordx4 v[202:203], off
	s_add_i32 m0, s24, 0x2000
	s_add_u32 s24, s28, 0xb0000
	v_lshl_add_u64 v[218:219], s[28:29], 0, v[134:135]
	s_addc_u32 s25, s29, 0
	s_add_i32 s76, s51, s33
	global_load_lds_dwordx4 v[218:219], off
	v_lshl_add_u64 v[220:221], s[24:25], 0, v[130:131]
	s_mov_b32 m0, s76
	v_lshl_add_u64 v[222:223], s[30:31], 0, v[132:133]
	global_load_lds_dwordx4 v[220:221], off
	v_lshl_add_u64 v[220:221], s[24:25], 0, v[134:135]
	s_add_i32 m0, s76, 0x2000
	s_nop 0
	global_load_lds_dwordx4 v[220:221], off
	v_lshl_add_u64 v[220:221], s[30:31], 0, v[128:129]
	s_mov_b32 m0, s39
	s_nop 0
	global_load_lds_dwordx4 v[220:221], off
	s_mov_b32 m0, s40
	s_nop 0
	global_load_lds_dwordx4 v[222:223], off
	s_waitcnt vmcnt(8)
	s_waitcnt lgkmcnt(0)
	s_barrier
; #define PG8_STAGE(bufoff, gbase, voff) do { _Pragma("unroll") for (int _i = 0; _i < 2; ++_i) \
;         __builtin_amdgcn_global_load_lds((const unsigned*)((const char*)(gbase) + (voff)[_i]), (PG8_LAS unsigned*)(lds + (bufoff) + ldsw + _i * 8192), 16, 0, 0); } while (0)
; #define PG8_LDA(dst, b, h) do { _Pragma("unroll") for (int m = 0; m < 4; ++m) _Pragma("unroll") for (int k = 0; k < 2; ++k) dst[m][k] = *(const PG8_LAS bf16x8*)(lds + PG8_SA(b, h) + aoff + m * 2048 + k * 1024); } while (0)
; #define PG8_LDB(dst, b, h) do { _Pragma("unroll") for (int n = 0; n < 2; ++n) _Pragma("unroll") for (int k = 0; k < 2; ++k) dst[n][k] = *(const PG8_LAS bf16x8*)(lds + PG8_SB(b, h) + boff + n * 2048 + k * 1024); } while (0)
; #define PG8_MMA(ai, bj, At, Bt) do { __builtin_amdgcn_s_setprio(1); _Pragma("unroll") for (int m = 0; m < 4; ++m) _Pragma("unroll") for (int n = 0; n < 2; ++n) _Pragma("unroll") for (int k = 0; k < 2; ++k) \
;         acc[ai][bj][m][n] = __builtin_amdgcn_mfma_f32_16x16x32_bf16(Bt[n][k], At[m][k], acc[ai][bj][m][n], 0, 0, 0); __builtin_amdgcn_s_setprio(0); } while (0)
; template <class Epi, class Sched, bool ALIGN_EPI = false, bool SP2 = false>
; __device__ __forceinline__ void gemm_phase(PG8_LAS unsigned char* lds, const Gemm g, const Sched& S, const Epi& E, const int wid) {
;     ...
;             if constexpr (SP2) {
;             PG8_LDB(B0, 0, 0); PG8_LDB(B1, 0, 1); PG8_SCHED; PG8_LDA(At, 0, 0); PG8_STAGE(PG8_SA(1, 1), a1 + hstep, voffA);
;             PG8_WAIT_V(8); PG8_WAIT_L(0); PG8_BAR; PG8_MMA(0, 0, At, B0); PG8_MMA(0, 1, At, B1); PG8_BAR; PG8_SCHED;
;             PG8_LDA(At, 0, 1); PG8_STAGE(PG8_SB(0, 0), b2, voffB); PG8_STAGE(PG8_SB(0, 1), b2 + hstep, voffB); PG8_STAGE(PG8_SA(0, 0), a2, voffA);
;             PG8_WAIT_V(8); PG8_WAIT_L(0); PG8_BAR; PG8_MMA(1, 0, At, B0); PG8_MMA(1, 1, At, B1); PG8_BAR; PG8_SCHED;
;             PG8_LDB(B0, 1, 0); PG8_LDB(B1, 1, 1); PG8_SCHED; PG8_LDA(At, 1, 0); PG8_STAGE(PG8_SA(0, 1), a2 + hstep, voffA);
;             PG8_WAIT_V(8); PG8_WAIT_L(0); PG8_BAR; PG8_MMA(0, 0, At, B0); PG8_MMA(0, 1, At, B1); PG8_BAR; PG8_SCHED;
;             PG8_LDA(At, 1, 1); PG8_STAGE(PG8_SB(1, 0), b3, voffB); PG8_STAGE(PG8_SB(1, 1), b3 + hstep, voffB); PG8_STAGE(PG8_SA(1, 0), a3, voffA);
;             PG8_WAIT_V(8); PG8_WAIT_L(0); PG8_BAR; PG8_MMA(1, 0, At, B0); PG8_MMA(1, 1, At, B1); PG8_BAR; PG8_SCHED;
	s_waitcnt lgkmcnt(0)
	v_mfma_f32_16x16x32_bf16 v[92:95], v[144:147], v[182:185], v[92:95]
	v_mfma_f32_16x16x32_bf16 v[88:91], v[152:155], v[182:185], v[88:91]
	v_mfma_f32_16x16x32_bf16 v[84:87], v[144:147], v[190:193], v[84:87]
	v_mfma_f32_16x16x32_bf16 v[80:83], v[152:155], v[190:193], v[80:83]
	v_mfma_f32_16x16x32_bf16 v[76:79], v[144:147], v[198:201], v[76:79]
	v_mfma_f32_16x16x32_bf16 v[72:75], v[152:155], v[198:201], v[72:75]
	v_mfma_f32_16x16x32_bf16 v[68:71], v[144:147], v[210:213], v[68:71]
	v_mfma_f32_16x16x32_bf16 v[64:67], v[152:155], v[210:213], v[64:67]
	v_mfma_f32_16x16x32_bf16 v[92:95], v[148:151], v[186:189], v[92:95]
	v_mfma_f32_16x16x32_bf16 v[88:91], v[156:159], v[186:189], v[88:91]
	v_mfma_f32_16x16x32_bf16 v[84:87], v[148:151], v[194:197], v[84:87]
	v_mfma_f32_16x16x32_bf16 v[80:83], v[156:159], v[194:197], v[80:83]
	v_mfma_f32_16x16x32_bf16 v[76:79], v[148:151], v[206:209], v[76:79]
	v_mfma_f32_16x16x32_bf16 v[72:75], v[156:159], v[206:209], v[72:75]
	v_mfma_f32_16x16x32_bf16 v[68:71], v[148:151], v[214:217], v[68:71]
	v_mfma_f32_16x16x32_bf16 v[64:67], v[156:159], v[214:217], v[64:67]
	v_mfma_f32_16x16x32_bf16 v[28:31], v[166:169], v[182:185], v[28:31]
	v_mfma_f32_16x16x32_bf16 v[24:27], v[174:177], v[182:185], v[24:27]
	v_mfma_f32_16x16x32_bf16 v[20:23], v[166:169], v[190:193], v[20:23]
	v_mfma_f32_16x16x32_bf16 v[16:19], v[174:177], v[190:193], v[16:19]
	v_mfma_f32_16x16x32_bf16 v[12:15], v[166:169], v[198:201], v[12:15]
	v_mfma_f32_16x16x32_bf16 v[8:11], v[174:177], v[198:201], v[8:11]
	v_mfma_f32_16x16x32_bf16 v[4:7], v[166:169], v[210:213], v[4:7]
	v_mfma_f32_16x16x32_bf16 v[0:3], v[174:177], v[210:213], v[0:3]
	v_mfma_f32_16x16x32_bf16 v[28:31], v[170:173], v[186:189], v[28:31]
	v_mfma_f32_16x16x32_bf16 v[24:27], v[178:181], v[186:189], v[24:27]
	v_mfma_f32_16x16x32_bf16 v[20:23], v[170:173], v[194:197], v[20:23]
	v_mfma_f32_16x16x32_bf16 v[16:19], v[178:181], v[194:197], v[16:19]
	v_mfma_f32_16x16x32_bf16 v[12:15], v[170:173], v[206:209], v[12:15]
	v_mfma_f32_16x16x32_bf16 v[8:11], v[178:181], v[206:209], v[8:11]
	v_mfma_f32_16x16x32_bf16 v[4:7], v[170:173], v[214:217], v[4:7]
	v_mfma_f32_16x16x32_bf16 v[0:3], v[178:181], v[214:217], v[0:3]
	s_barrier
	s_add_i32 s76, 0, 0x18000
	s_add_i32 s77, 0, 0x1c000
	v_add_u32_e32 v156, s76, v161
	v_add_u32_e32 v178, s77, v161
	ds_read_b128 v[144:147], v156
	ds_read_b128 v[148:151], v156 offset:1024
	ds_read_b128 v[152:155], v156 offset:2048
	ds_read_b128 v[156:159], v156 offset:3072
	ds_read_b128 v[166:169], v178
	ds_read_b128 v[170:173], v178 offset:1024
	ds_read_b128 v[174:177], v178 offset:2048
	ds_read_b128 v[178:181], v178 offset:3072
	s_add_u32 s24, s30, 0xb0000
	s_addc_u32 s25, s31, 0
	s_mov_b32 m0, s41
	v_lshl_add_u64 v[224:225], s[24:25], 0, v[128:129]
	ds_read_b128 v[182:185], v165 offset:32768
	ds_read_b128 v[186:189], v165 offset:33792
	ds_read_b128 v[190:193], v165 offset:34816
	ds_read_b128 v[194:197], v165 offset:35840
	ds_read_b128 v[198:201], v165 offset:36864
	ds_read_b128 v[206:209], v165 offset:37888
	ds_read_b128 v[210:213], v165 offset:38912
	ds_read_b128 v[214:217], v165 offset:39936
	global_load_lds_dwordx4 v[224:225], off
	v_lshl_add_u64 v[224:225], s[24:25], 0, v[132:133]
	s_mov_b32 m0, s42
	s_nop 0
	global_load_lds_dwordx4 v[224:225], off
	s_waitcnt vmcnt(8)
	s_waitcnt lgkmcnt(0)
	s_barrier
	s_waitcnt lgkmcnt(0)
	v_mfma_f32_16x16x32_bf16 v[124:127], v[144:147], v[182:185], v[124:127]
	v_mfma_f32_16x16x32_bf16 v[120:123], v[152:155], v[182:185], v[120:123]
	v_mfma_f32_16x16x32_bf16 v[116:119], v[144:147], v[190:193], v[116:119]
	v_mfma_f32_16x16x32_bf16 v[112:115], v[152:155], v[190:193], v[112:115]
	v_mfma_f32_16x16x32_bf16 v[108:111], v[144:147], v[198:201], v[108:111]
	v_mfma_f32_16x16x32_bf16 v[104:107], v[152:155], v[198:201], v[104:107]
	v_mfma_f32_16x16x32_bf16 v[100:103], v[144:147], v[210:213], v[100:103]
	v_mfma_f32_16x16x32_bf16 v[96:99], v[152:155], v[210:213], v[96:99]
	v_mfma_f32_16x16x32_bf16 v[124:127], v[148:151], v[186:189], v[124:127]
	v_mfma_f32_16x16x32_bf16 v[120:123], v[156:159], v[186:189], v[120:123]
	v_mfma_f32_16x16x32_bf16 v[116:119], v[148:151], v[194:197], v[116:119]
	v_mfma_f32_16x16x32_bf16 v[112:115], v[156:159], v[194:197], v[112:115]
	v_mfma_f32_16x16x32_bf16 v[108:111], v[148:151], v[206:209], v[108:111]
	v_mfma_f32_16x16x32_bf16 v[104:107], v[156:159], v[206:209], v[104:107]
	v_mfma_f32_16x16x32_bf16 v[100:103], v[148:151], v[214:217], v[100:103]
	v_mfma_f32_16x16x32_bf16 v[96:99], v[156:159], v[214:217], v[96:99]
	v_mfma_f32_16x16x32_bf16 v[60:63], v[166:169], v[182:185], v[60:63]
	v_mfma_f32_16x16x32_bf16 v[56:59], v[174:177], v[182:185], v[56:59]
	v_mfma_f32_16x16x32_bf16 v[52:55], v[166:169], v[190:193], v[52:55]
	v_mfma_f32_16x16x32_bf16 v[48:51], v[174:177], v[190:193], v[48:51]
	v_mfma_f32_16x16x32_bf16 v[44:47], v[166:169], v[198:201], v[44:47]
	v_mfma_f32_16x16x32_bf16 v[40:43], v[174:177], v[198:201], v[40:43]
	v_mfma_f32_16x16x32_bf16 v[36:39], v[166:169], v[210:213], v[36:39]
	v_mfma_f32_16x16x32_bf16 v[32:35], v[174:177], v[210:213], v[32:35]
	v_mfma_f32_16x16x32_bf16 v[60:63], v[170:173], v[186:189], v[60:63]
	v_mfma_f32_16x16x32_bf16 v[56:59], v[178:181], v[186:189], v[56:59]
	v_mfma_f32_16x16x32_bf16 v[52:55], v[170:173], v[194:197], v[52:55]
	v_mfma_f32_16x16x32_bf16 v[48:51], v[178:181], v[194:197], v[48:51]
	v_mfma_f32_16x16x32_bf16 v[44:47], v[170:173], v[206:209], v[44:47]
	v_mfma_f32_16x16x32_bf16 v[40:43], v[178:181], v[206:209], v[40:43]
	v_mfma_f32_16x16x32_bf16 v[36:39], v[170:173], v[214:217], v[36:39]
	v_mfma_f32_16x16x32_bf16 v[32:35], v[178:181], v[214:217], v[32:35]
	s_barrier
; #define PG8_STAGE(bufoff, gbase, voff) do { _Pragma("unroll") for (int _i = 0; _i < 2; ++_i) \
;         __builtin_amdgcn_global_load_lds((const unsigned*)((const char*)(gbase) + (voff)[_i]), (PG8_LAS unsigned*)(lds + (bufoff) + ldsw + _i * 8192), 16, 0, 0); } while (0)
; #define PG8_LDA(dst, b, h) do { _Pragma("unroll") for (int m = 0; m < 4; ++m) _Pragma("unroll") for (int k = 0; k < 2; ++k) dst[m][k] = *(const PG8_LAS bf16x8*)(lds + PG8_SA(b, h) + aoff + m * 2048 + k * 1024); } while (0)
; #define PG8_LDB(dst, b, h) do { _Pragma("unroll") for (int n = 0; n < 2; ++n) _Pragma("unroll") for (int k = 0; k < 2; ++k) dst[n][k] = *(const PG8_LAS bf16x8*)(lds + PG8_SB(b, h) + boff + n * 2048 + k * 1024); } while (0)
; #define PG8_MMA(ai, bj, At, Bt) do { __builtin_amdgcn_s_setprio(1); _Pragma("unroll") for (int m = 0; m < 4; ++m) _Pragma("unroll") for (int n = 0; n < 2; ++n) _Pragma("unroll") for (int k = 0; k < 2; ++k) \
;         acc[ai][bj][m][n] = __builtin_amdgcn_mfma_f32_16x16x32_bf16(Bt[n][k], At[m][k], acc[ai][bj][m][n], 0, 0, 0); __builtin_amdgcn_s_setprio(0); } while (0)
; template <class Epi, class Sched, bool ALIGN_EPI = false, bool SP2 = false>
; __device__ __forceinline__ void gemm_phase(PG8_LAS unsigned char* lds, const Gemm g, const Sched& S, const Epi& E, const int wid) {
;     ...
;             if constexpr (SP2) {
;             PG8_LDB(B0, 0, 0); PG8_LDB(B1, 0, 1); PG8_SCHED; PG8_LDA(At, 0, 0); PG8_STAGE(PG8_SA(1, 1), a1 + hstep, voffA);
;             PG8_WAIT_V(8); PG8_WAIT_L(0); PG8_BAR; PG8_MMA(0, 0, At, B0); PG8_MMA(0, 1, At, B1); PG8_BAR; PG8_SCHED;
;             PG8_LDA(At, 0, 1); PG8_STAGE(PG8_SB(0, 0), b2, voffB); PG8_STAGE(PG8_SB(0, 1), b2 + hstep, voffB); PG8_STAGE(PG8_SA(0, 0), a2, voffA);
;             PG8_WAIT_V(8); PG8_WAIT_L(0); PG8_BAR; PG8_MMA(1, 0, At, B0); PG8_MMA(1, 1, At, B1); PG8_BAR; PG8_SCHED;
;             PG8_LDB(B0, 1, 0); PG8_LDB(B1, 1, 1); PG8_SCHED; PG8_LDA(At, 1, 0); PG8_STAGE(PG8_SA(0, 1), a2 + hstep, voffA);
;             PG8_WAIT_V(8); PG8_WAIT_L(0); PG8_BAR; PG8_MMA(0, 0, At, B0); PG8_MMA(0, 1, At, B1); PG8_BAR; PG8_SCHED;
;             PG8_LDA(At, 1, 1); PG8_STAGE(PG8_SB(1, 0), b3, voffB); PG8_STAGE(PG8_SB(1, 1), b3 + hstep, voffB); PG8_STAGE(PG8_SA(1, 0), a3, voffA);
;             PG8_WAIT_V(8); PG8_WAIT_L(0); PG8_BAR; PG8_MMA(1, 0, At, B0); PG8_MMA(1, 1, At, B1); PG8_BAR; PG8_SCHED;
	s_add_i32 s24, s76, s33
	v_lshl_add_u64 v[202:203], v[202:203], 0, s[16:17]
	s_mov_b32 m0, s24
	ds_read_b128 v[182:185], v165 offset:49152
	ds_read_b128 v[186:189], v165 offset:50176
	ds_read_b128 v[190:193], v165 offset:51200
	ds_read_b128 v[194:197], v165 offset:52224
	ds_read_b128 v[198:201], v165 offset:53248
	ds_read_b128 v[206:209], v165 offset:54272
	ds_read_b128 v[210:213], v165 offset:55296
	ds_read_b128 v[214:217], v165 offset:56320
	global_load_lds_dwordx4 v[202:203], off
	s_add_i32 m0, s24, 0x2000
	s_add_u32 s24, s28, 0xb0080
	v_lshl_add_u64 v[202:203], v[218:219], 0, s[16:17]
	s_addc_u32 s25, s29, 0
	s_add_i32 s28, s77, s33
	global_load_lds_dwordx4 v[202:203], off
	v_lshl_add_u64 v[202:203], s[24:25], 0, v[130:131]
	s_mov_b32 m0, s28
	s_nop 0
	global_load_lds_dwordx4 v[202:203], off
	v_lshl_add_u64 v[202:203], s[24:25], 0, v[134:135]
	s_add_i32 m0, s28, 0x2000
	s_nop 0
	global_load_lds_dwordx4 v[202:203], off
	v_lshl_add_u64 v[202:203], v[220:221], 0, s[16:17]
	s_mov_b32 m0, s46
	s_nop 0
	global_load_lds_dwordx4 v[202:203], off
	v_lshl_add_u64 v[202:203], v[222:223], 0, s[16:17]
	s_mov_b32 m0, s47
	s_nop 0
	global_load_lds_dwordx4 v[202:203], off
	s_waitcnt vmcnt(8)
	s_waitcnt lgkmcnt(0)
	s_barrier
	s_waitcnt lgkmcnt(0)
	v_mfma_f32_16x16x32_bf16 v[92:95], v[144:147], v[182:185], v[92:95]
	v_mfma_f32_16x16x32_bf16 v[88:91], v[152:155], v[182:185], v[88:91]
	v_mfma_f32_16x16x32_bf16 v[84:87], v[144:147], v[190:193], v[84:87]
	v_mfma_f32_16x16x32_bf16 v[80:83], v[152:155], v[190:193], v[80:83]
	v_mfma_f32_16x16x32_bf16 v[76:79], v[144:147], v[198:201], v[76:79]
	v_mfma_f32_16x16x32_bf16 v[72:75], v[152:155], v[198:201], v[72:75]
	v_mfma_f32_16x16x32_bf16 v[68:71], v[144:147], v[210:213], v[68:71]
	v_mfma_f32_16x16x32_bf16 v[64:67], v[152:155], v[210:213], v[64:67]
	v_mfma_f32_16x16x32_bf16 v[92:95], v[148:151], v[186:189], v[92:95]
	v_mfma_f32_16x16x32_bf16 v[88:91], v[156:159], v[186:189], v[88:91]
	v_mfma_f32_16x16x32_bf16 v[84:87], v[148:151], v[194:197], v[84:87]
	v_mfma_f32_16x16x32_bf16 v[80:83], v[156:159], v[194:197], v[80:83]
	v_mfma_f32_16x16x32_bf16 v[76:79], v[148:151], v[206:209], v[76:79]
	v_mfma_f32_16x16x32_bf16 v[72:75], v[156:159], v[206:209], v[72:75]
	v_mfma_f32_16x16x32_bf16 v[68:71], v[148:151], v[214:217], v[68:71]
	v_mfma_f32_16x16x32_bf16 v[64:67], v[156:159], v[214:217], v[64:67]
	v_mfma_f32_16x16x32_bf16 v[28:31], v[166:169], v[182:185], v[28:31]
	v_mfma_f32_16x16x32_bf16 v[24:27], v[174:177], v[182:185], v[24:27]
	v_mfma_f32_16x16x32_bf16 v[20:23], v[166:169], v[190:193], v[20:23]
	v_mfma_f32_16x16x32_bf16 v[16:19], v[174:177], v[190:193], v[16:19]
	v_mfma_f32_16x16x32_bf16 v[12:15], v[166:169], v[198:201], v[12:15]
	v_mfma_f32_16x16x32_bf16 v[8:11], v[174:177], v[198:201], v[8:11]
	v_mfma_f32_16x16x32_bf16 v[4:7], v[166:169], v[210:213], v[4:7]
	v_mfma_f32_16x16x32_bf16 v[0:3], v[174:177], v[210:213], v[0:3]
	v_mfma_f32_16x16x32_bf16 v[28:31], v[170:173], v[186:189], v[28:31]
	v_mfma_f32_16x16x32_bf16 v[24:27], v[178:181], v[186:189], v[24:27]
	v_mfma_f32_16x16x32_bf16 v[20:23], v[170:173], v[194:197], v[20:23]
	v_mfma_f32_16x16x32_bf16 v[16:19], v[178:181], v[194:197], v[16:19]
	v_mfma_f32_16x16x32_bf16 v[12:15], v[170:173], v[206:209], v[12:15]
	v_mfma_f32_16x16x32_bf16 v[8:11], v[178:181], v[206:209], v[8:11]
	v_mfma_f32_16x16x32_bf16 v[4:7], v[170:173], v[214:217], v[4:7]
	v_mfma_f32_16x16x32_bf16 v[0:3], v[178:181], v[214:217], v[0:3]
	s_barrier
	s_add_i32 s75, s75, 2
	s_add_u32 s72, s72, 0x100
	s_addc_u32 s73, s73, 0
	s_cmp_gt_u32 s75, 41
	s_mov_b64 s[24:25], s[26:27]
	s_cbranch_scc0 .LBB0_232
	s_and_b64 vcc, exec, s[20:21]
	s_cbranch_vccz .LBB0_235
	s_barrier

; __device__ __forceinline__ int lane_now() { int l; asm volatile("v_mbcnt_lo_u32_b32 %0, -1, 0\n\tv_mbcnt_hi_u32_b32 %0, -1, %0" : "=v"(l)); return l; }
; #define PG8_STAGE(bufoff, gbase, voff) do { _Pragma("unroll") for (int _i = 0; _i < 2; ++_i) \
;         __builtin_amdgcn_global_load_lds((const unsigned*)((const char*)(gbase) + (voff)[_i]), (PG8_LAS unsigned*)(lds + (bufoff) + ldsw + _i * 8192), 16, 0, 0); } while (0)
; #define PG8_BAR __builtin_amdgcn_s_barrier()
; #define lane (lane_now())
; template <class Epi, class Sched, bool ALIGN_EPI = false, bool SP2 = false>
; __device__ __forceinline__ void gemm_phase(PG8_LAS unsigned char* lds, const Gemm g, const Sched& S, const Epi& E, const int wid) {
;     const int lane = lane_now(), tid = wid * 64 + lane, wr = wid >> 2, wc = wid & 3, fr = lane & 15, fq = lane >> 4;
;     const int K = g.K, nt = K / BK;
;     unsigned voffA[2], voffB[2];
; #pragma unroll
;     for (int i = 0; i < 2; ++i) { int R, C; stage_rc(tid * 16 + i * 8192, R, C); const int Rb = Epi::PERM ? ((R & ~31) + perm32(R & 31)) : R;
;         voffA[i] = (unsigned)(R * K + C) * 2u; voffB[i] = (unsigned)(Rb * K + C) * 2u; }
;     const size_t kstep = (size_t)(BK * 2);
;     const size_t hstep = (size_t)HALF * K * 2;
;     const size_t tstep = 2 * hstep;
;     const unsigned ldsw = (unsigned)wid * 1024u;
;     const int aoff = lds_byte(wr * 64 + fr, fq * 8), boff = lds_byte(wc * 32 + fr, fq * 8);
;     ...
;     Unit cur, nxt; int ui = 0;
;     if (!S.next(0, cur)) return;
;     f32x4 acc[2][2][4][2];
; #pragma unroll
;     for (int a = 0; a < 2; ++a)
; #pragma unroll
;         for (int b = 0; b < 2; ++b)
; #pragma unroll
;             for (int m = 0; m < 4; ++m)
; #pragma unroll
;                 for (int n = 0; n < 2; ++n) acc[a][b][m][n] = (f32x4){0.f, 0.f, 0.f, 0.f};
;     bf16x8 At[4][2], B0[2][2], B1[2][2];
;     const char* cA = (const char*)g.A + (size_t)cur.pm * tstep; const char* cB = (const char*)g.Bt + (size_t)cur.pn * tstep;
;     S.a_ready(cur);
;     if constexpr (SP2) {
;         PG8_STAGE(PG8_SB(0, 0), cB, voffB); PG8_STAGE(PG8_SB(0, 1), cB + hstep, voffB); PG8_STAGE(PG8_SA(0, 0), cA, voffA); PG8_STAGE(PG8_SA(0, 1), cA + hstep, voffA);
;         if (wr == 1) PG8_BAR;
.LBB0_364:
	s_add_u32 s0, s92, 0xdb00000
	s_addc_u32 s1, s93, 0
	v_writelane_b32 v244, s0, 29
	s_cmpk_gt_i32 s82, 0x67f
	s_waitcnt lgkmcnt(0)
	s_barrier
	v_writelane_b32 v244, s1, 30
	v_mbcnt_lo_u32_b32 v10, -1, 0
	v_mbcnt_hi_u32_b32 v10, -1, v10
	s_cbranch_scc1 .LBB0_380
	v_lshl_add_u32 v0, v10, 4, s33
	v_add_u32_e32 v1, 0x2000, v0
	v_ashrrev_i32_e32 v2, 31, v1
	v_lshrrev_b32_e32 v2, 22, v2
	v_add_u32_e32 v2, v1, v2
	v_ashrrev_i32_e32 v8, 10, v2
	v_mul_i32_i24_e32 v2, 0x400, v8
	v_sub_u32_e32 v1, v1, v2
	v_lshrrev_b32_e32 v2, 4, v1
	v_bitop3_b32 v1, v2, v1, 32 bitop3:0x6c
	v_ashrrev_i32_e32 v2, 31, v1
	v_lshrrev_b32_e32 v2, 26, v2
	v_add_u32_e32 v2, v1, v2
	v_ashrrev_i32_e32 v9, 6, v2
	v_lshlrev_b32_e32 v3, 3, v8
	v_and_b32_e32 v2, 0xffc0, v2
	v_and_b32_e32 v3, -16, v3
	v_sub_u32_e32 v1, v1, v2
	v_add_u32_e32 v3, v9, v3
	v_lshrrev_b16_e32 v2, 7, v1
	v_and_b32_e32 v4, 3, v9
	s_mov_b32 s0, 0x1fffe0
	v_lshrrev_b32_e32 v5, 2, v3
	v_lshlrev_b32_e32 v6, 1, v3
	v_and_b32_e32 v2, 1, v2
	v_and_or_b32 v4, v3, s0, v4
	v_and_b32_e32 v5, 4, v5
	v_and_b32_e32 v6, 24, v6
	v_add_u16_e32 v1, v1, v2
	v_mov_b32_e32 v2, 1
	v_or3_b32 v4, v4, v5, v6
	v_lshlrev_b32_e32 v5, 5, v8
	v_ashrrev_i16_sdwa v1, v2, sext(v1) dst_sel:DWORD dst_unused:UNUSED_PAD src0_sel:DWORD src1_sel:BYTE_0
	v_and_b32_e32 v5, 32, v5
	v_bfe_i32 v11, v1, 0, 16
	v_add_lshl_u32 v1, v5, v11, 1
	v_lshl_add_u32 v128, v4, 11, v1
	v_lshl_add_u32 v130, v3, 11, v1
	v_ashrrev_i32_e32 v1, 31, v0
	v_lshrrev_b32_e32 v1, 22, v1
	v_add_u32_e32 v1, v0, v1
	v_ashrrev_i32_e32 v12, 10, v1
	v_mul_i32_i24_e32 v1, 0x400, v12
	v_sub_u32_e32 v0, v0, v1
	v_lshrrev_b32_e32 v1, 4, v0
	v_bitop3_b32 v0, v1, v0, 32 bitop3:0x6c
	v_ashrrev_i32_e32 v1, 31, v0
	v_lshrrev_b32_e32 v1, 26, v1
	v_add_u32_e32 v1, v0, v1
	v_lshlrev_b32_e32 v3, 3, v12
	s_add_u32 s34, s92, 0x2200000
	v_ashrrev_i32_e32 v13, 6, v1
	v_and_b32_e32 v3, -16, v3
	s_addc_u32 s35, s93, 0
	v_add_u32_e32 v3, v13, v3
	v_and_b32_e32 v4, 3, v13
	s_ashr_i32 s36, s82, 31
	v_and_or_b32 v4, v3, s0, v4
	s_lshr_b32 s0, s36, 29
	s_add_i32 s0, s82, s0
	s_ashr_i32 s1, s0, 3
	s_and_b32 s0, s0, -8
	s_sub_i32 s0, s82, s0
	s_cmp_lt_i32 s0, 0
	s_movk_i32 s37, 0xd1
	s_cselect_b32 s4, s37, 0xd0
	s_mul_i32 s0, s0, s4
	s_add_i32 s0, s0, s1
	s_mul_hi_i32 s1, s0, 0x4ec4ec4f
	s_lshr_b32 s4, s1, 31
	s_ashr_i32 s1, s1, 4
	s_add_i32 s1, s1, s4
	s_lshl_b32 s5, s1, 2
	s_mul_i32 s1, s1, 52
	s_sub_i32 s0, s0, s1
	s_bfe_i32 s1, s0, 0x80000
	s_bfe_u32 s1, s1, 0x2000d
	s_add_i32 s1, s0, s1
	s_bfe_i32 s4, s1, 0x80000
	s_and_b32 s1, s1, 0xfc
	s_sub_i32 s0, s0, s1
	s_sext_i32_i16 s4, s4
	s_sext_i32_i8 s0, s0
	v_lshrrev_b32_e32 v5, 2, v3
	v_lshlrev_b32_e32 v6, 1, v3
	v_and_b32_e32 v1, 0xc0, v1
	s_lshr_b32 s4, s4, 2
	s_add_i32 s10, s5, s0
	v_and_b32_e32 v5, 4, v5
	v_and_b32_e32 v6, 24, v6
	v_sub_u32_e32 v0, v0, v1
	s_ashr_i32 s11, s10, 31
	s_bfe_i64 s[6:7], s[4:5], 0x100000
	v_or3_b32 v4, v4, v5, v6
	v_lshlrev_b32_e32 v5, 5, v12
	v_ashrrev_i16_sdwa v0, v2, sext(v0) dst_sel:DWORD dst_unused:UNUSED_PAD src0_sel:DWORD src1_sel:BYTE_0
	s_lshl_b64 s[0:1], s[10:11], 19
	s_lshl_b64 s[6:7], s[6:7], 19
	v_and_b32_e32 v5, 32, v5
	v_bfe_i32 v14, v0, 0, 16
	s_add_u32 s28, s34, s6
	v_add_lshl_u32 v0, v5, v14, 1
	s_addc_u32 s29, s35, s7
	s_add_i32 s11, s33, 0
	v_lshl_add_u32 v132, v4, 11, v0
	s_add_i32 m0, s11, 0x10000
	v_lshl_add_u32 v134, v3, 11, v0
	global_load_lds_dwordx4 v132, s[28:29]
	s_add_i32 m0, s11, 0x12000
	s_add_u32 s6, s28, 0x40000
	global_load_lds_dwordx4 v128, s[28:29]
	s_addc_u32 s7, s29, 0
	s_add_i32 m0, s11, 0x14000
	v_mov_b32_e32 v133, 0
	global_load_lds_dwordx4 v132, s[6:7]
	s_add_i32 m0, s11, 0x16000
	s_add_u32 s26, s2, s0
	s_addc_u32 s27, s3, s1
	s_add_i32 s38, s11, 0x2000
	global_load_lds_dwordx4 v128, s[6:7]
	s_mov_b32 m0, s11
	s_add_u32 s0, s26, 0x40000
	global_load_lds_dwordx4 v134, s[26:27]
	s_mov_b32 m0, s38
	s_addc_u32 s1, s27, 0
	s_add_i32 s39, s11, 0x4000
	global_load_lds_dwordx4 v130, s[26:27]
	s_mov_b32 m0, s39
	s_add_i32 s40, s11, 0x6000
	global_load_lds_dwordx4 v134, s[0:1]
	s_mov_b32 m0, s40
	v_readlane_b32 s5, v244, 18
	global_load_lds_dwordx4 v130, s[0:1]
	v_mov_b32_e32 v129, v133
	v_mov_b32_e32 v135, v133
	v_mov_b32_e32 v131, v133
	s_cmp_eq_u32 s5, 1
	s_mov_b32 s41, 0
	v_lshl_add_u64 v[4:5], s[28:29], 0, v[132:133]
	v_lshl_add_u64 v[2:3], s[28:29], 0, v[128:129]
	v_lshl_add_u64 v[0:1], s[26:27], 0, v[134:135]
	s_cselect_b64 s[0:1], -1, 0
	s_cmp_lg_u32 s5, 1
	v_lshl_add_u64 v[6:7], s[26:27], 0, v[130:131]
	s_cbranch_scc1 .LBB0_367
	s_barrier
	s_setprio 1

; #define PG8_STAGE(bufoff, gbase, voff) do { _Pragma("unroll") for (int _i = 0; _i < 2; ++_i) \
;         __builtin_amdgcn_global_load_lds((const unsigned*)((const char*)(gbase) + (voff)[_i]), (PG8_LAS unsigned*)(lds + (bufoff) + ldsw + _i * 8192), 16, 0, 0); } while (0)
; #define PG8_LDA(dst, b, h) do { _Pragma("unroll") for (int m = 0; m < 4; ++m) _Pragma("unroll") for (int k = 0; k < 2; ++k) dst[m][k] = *(const PG8_LAS bf16x8*)(lds + PG8_SA(b, h) + aoff + m * 2048 + k * 1024); } while (0)
; #define PG8_LDB(dst, b, h) do { _Pragma("unroll") for (int n = 0; n < 2; ++n) _Pragma("unroll") for (int k = 0; k < 2; ++k) dst[n][k] = *(const PG8_LAS bf16x8*)(lds + PG8_SB(b, h) + boff + n * 2048 + k * 1024); } while (0)
; #define PG8_MMA(ai, bj, At, Bt) do { __builtin_amdgcn_s_setprio(1); _Pragma("unroll") for (int m = 0; m < 4; ++m) _Pragma("unroll") for (int n = 0; n < 2; ++n) _Pragma("unroll") for (int k = 0; k < 2; ++k) \
;         acc[ai][bj][m][n] = __builtin_amdgcn_mfma_f32_16x16x32_bf16(Bt[n][k], At[m][k], acc[ai][bj][m][n], 0, 0, 0); __builtin_amdgcn_s_setprio(0); } while (0)
; template <class Epi, class Sched, bool ALIGN_EPI = false, bool SP2 = false>
; __device__ __forceinline__ void gemm_phase(PG8_LAS unsigned char* lds, const Gemm g, const Sched& S, const Epi& E, const int wid) {
;     ...
;             if constexpr (SP2) {
;             PG8_LDB(B0, 0, 0); PG8_LDB(B1, 0, 1); PG8_SCHED; PG8_LDA(At, 0, 0); PG8_STAGE(PG8_SA(1, 1), a1 + hstep, voffA);
;             PG8_WAIT_V(8); PG8_WAIT_L(0); PG8_BAR; PG8_MMA(0, 0, At, B0); PG8_MMA(0, 1, At, B1); PG8_BAR; PG8_SCHED;
;             PG8_LDA(At, 0, 1); PG8_STAGE(PG8_SB(0, 0), b2, voffB); PG8_STAGE(PG8_SB(0, 1), b2 + hstep, voffB); PG8_STAGE(PG8_SA(0, 0), a2, voffA);
;             PG8_WAIT_V(8); PG8_WAIT_L(0); PG8_BAR; PG8_MMA(1, 0, At, B0); PG8_MMA(1, 1, At, B1); PG8_BAR; PG8_SCHED;
;             PG8_LDB(B0, 1, 0); PG8_LDB(B1, 1, 1); PG8_SCHED; PG8_LDA(At, 1, 0); PG8_STAGE(PG8_SA(0, 1), a2 + hstep, voffA);
;             PG8_WAIT_V(8); PG8_WAIT_L(0); PG8_BAR; PG8_MMA(0, 0, At, B0); PG8_MMA(0, 1, At, B1); PG8_BAR; PG8_SCHED;
;             PG8_LDA(At, 1, 1); PG8_STAGE(PG8_SB(1, 0), b3, voffB); PG8_STAGE(PG8_SB(1, 1), b3 + hstep, voffB); PG8_STAGE(PG8_SA(1, 0), a3, voffA);
;             PG8_WAIT_V(8); PG8_WAIT_L(0); PG8_BAR; PG8_MMA(1, 0, At, B0); PG8_MMA(1, 1, At, B1); PG8_BAR; PG8_SCHED;
.LBB0_373:
	ds_read_b128 v[150:153], v147
	ds_read_b128 v[154:157], v147 offset:1024
	ds_read_b128 v[158:161], v147 offset:2048
	ds_read_b128 v[162:165], v147 offset:3072
	ds_read_b128 v[166:169], v148
	ds_read_b128 v[170:173], v148 offset:1024
	ds_read_b128 v[174:177], v148 offset:2048
	ds_read_b128 v[178:181], v148 offset:3072
	s_add_u32 s28, s26, 0xfffc0080
	s_addc_u32 s29, s27, -1
	s_cmp_eq_u32 s69, 12
	s_cselect_b32 s31, s21, s29
	s_cselect_b32 s30, s49, s28
	s_cselect_b32 s29, s17, s68
	s_cselect_b32 s28, s50, s51
	v_lshl_add_u64 v[202:203], s[26:27], 0, v[136:137]
	s_add_i32 m0, s11, 0xc000
	ds_read_b128 v[182:185], v149
	ds_read_b128 v[186:189], v149 offset:1024
	ds_read_b128 v[190:193], v149 offset:2048
	ds_read_b128 v[194:197], v149 offset:3072
	ds_read_b128 v[198:201], v149 offset:4096
	ds_read_b128 v[206:209], v149 offset:5120
	ds_read_b128 v[210:213], v149 offset:6144
	ds_read_b128 v[214:217], v149 offset:7168
	global_load_lds_dwordx4 v[202:203], off
	v_lshl_add_u64 v[202:203], s[26:27], 0, v[138:139]
	s_add_i32 m0, s11, 0xe000
	s_nop 0
	global_load_lds_dwordx4 v[202:203], off
	s_waitcnt vmcnt(8)
	s_waitcnt lgkmcnt(0)
	s_barrier
	s_waitcnt lgkmcnt(0)
	v_mfma_f32_16x16x32_bf16 v[124:127], v[150:153], v[182:185], v[124:127]
	v_mfma_f32_16x16x32_bf16 v[120:123], v[158:161], v[182:185], v[120:123]
	v_mfma_f32_16x16x32_bf16 v[116:119], v[150:153], v[190:193], v[116:119]
	v_mfma_f32_16x16x32_bf16 v[112:115], v[158:161], v[190:193], v[112:115]
	v_mfma_f32_16x16x32_bf16 v[100:103], v[150:153], v[198:201], v[100:103]
	v_mfma_f32_16x16x32_bf16 v[96:99], v[158:161], v[198:201], v[96:99]
	v_mfma_f32_16x16x32_bf16 v[84:87], v[150:153], v[210:213], v[84:87]
	v_mfma_f32_16x16x32_bf16 v[80:83], v[158:161], v[210:213], v[80:83]
	v_mfma_f32_16x16x32_bf16 v[124:127], v[154:157], v[186:189], v[124:127]
	v_mfma_f32_16x16x32_bf16 v[120:123], v[162:165], v[186:189], v[120:123]
	v_mfma_f32_16x16x32_bf16 v[116:119], v[154:157], v[194:197], v[116:119]
	v_mfma_f32_16x16x32_bf16 v[112:115], v[162:165], v[194:197], v[112:115]
	v_mfma_f32_16x16x32_bf16 v[100:103], v[154:157], v[206:209], v[100:103]
	v_mfma_f32_16x16x32_bf16 v[96:99], v[162:165], v[206:209], v[96:99]
	v_mfma_f32_16x16x32_bf16 v[84:87], v[154:157], v[214:217], v[84:87]
	v_mfma_f32_16x16x32_bf16 v[80:83], v[162:165], v[214:217], v[80:83]
	v_mfma_f32_16x16x32_bf16 v[108:111], v[166:169], v[182:185], v[108:111]
	v_mfma_f32_16x16x32_bf16 v[104:107], v[174:177], v[182:185], v[104:107]
	v_mfma_f32_16x16x32_bf16 v[92:95], v[166:169], v[190:193], v[92:95]
	v_mfma_f32_16x16x32_bf16 v[88:91], v[174:177], v[190:193], v[88:91]
	v_mfma_f32_16x16x32_bf16 v[76:79], v[166:169], v[198:201], v[76:79]
	v_mfma_f32_16x16x32_bf16 v[72:75], v[174:177], v[198:201], v[72:75]
	v_mfma_f32_16x16x32_bf16 v[68:71], v[166:169], v[210:213], v[68:71]
	v_mfma_f32_16x16x32_bf16 v[64:67], v[174:177], v[210:213], v[64:67]
	v_mfma_f32_16x16x32_bf16 v[108:111], v[170:173], v[186:189], v[108:111]
	v_mfma_f32_16x16x32_bf16 v[104:107], v[178:181], v[186:189], v[104:107]
	v_mfma_f32_16x16x32_bf16 v[92:95], v[170:173], v[194:197], v[92:95]
	v_mfma_f32_16x16x32_bf16 v[88:91], v[178:181], v[194:197], v[88:91]
	v_mfma_f32_16x16x32_bf16 v[76:79], v[170:173], v[206:209], v[76:79]
	v_mfma_f32_16x16x32_bf16 v[72:75], v[178:181], v[206:209], v[72:75]
	v_mfma_f32_16x16x32_bf16 v[68:71], v[170:173], v[214:217], v[68:71]
	v_mfma_f32_16x16x32_bf16 v[64:67], v[178:181], v[214:217], v[64:67]
	s_barrier
	s_add_i32 s70, s46, s33
	v_lshl_add_u64 v[202:203], s[28:29], 0, v[132:133]
	s_mov_b32 m0, s70
	ds_read_b128 v[182:185], v149 offset:16384
	ds_read_b128 v[186:189], v149 offset:17408
	ds_read_b128 v[190:193], v149 offset:18432
	ds_read_b128 v[194:197], v149 offset:19456
	ds_read_b128 v[198:201], v149 offset:20480
	ds_read_b128 v[206:209], v149 offset:21504
	ds_read_b128 v[210:213], v149 offset:22528
	ds_read_b128 v[214:217], v149 offset:23552
	global_load_lds_dwordx4 v[202:203], off
	s_add_i32 m0, s70, 0x2000
	s_add_u32 s70, s28, 0x40000
	v_lshl_add_u64 v[218:219], s[28:29], 0, v[128:129]
	s_addc_u32 s71, s29, 0
	s_add_i32 s72, s47, s33
	global_load_lds_dwordx4 v[218:219], off
	v_lshl_add_u64 v[220:221], s[70:71], 0, v[132:133]
	s_mov_b32 m0, s72
	v_lshl_add_u64 v[222:223], s[30:31], 0, v[130:131]
	global_load_lds_dwordx4 v[220:221], off
	v_lshl_add_u64 v[220:221], s[70:71], 0, v[128:129]
	s_add_i32 m0, s72, 0x2000
	s_nop 0
	global_load_lds_dwordx4 v[220:221], off
	v_lshl_add_u64 v[220:221], s[30:31], 0, v[134:135]
	s_mov_b32 m0, s11
	s_nop 0
	global_load_lds_dwordx4 v[220:221], off
	s_mov_b32 m0, s38
	s_nop 0
	global_load_lds_dwordx4 v[222:223], off
	s_waitcnt vmcnt(8)
	s_waitcnt lgkmcnt(0)
	s_barrier
; #define PG8_STAGE(bufoff, gbase, voff) do { _Pragma("unroll") for (int _i = 0; _i < 2; ++_i) \
;         __builtin_amdgcn_global_load_lds((const unsigned*)((const char*)(gbase) + (voff)[_i]), (PG8_LAS unsigned*)(lds + (bufoff) + ldsw + _i * 8192), 16, 0, 0); } while (0)
; #define PG8_LDA(dst, b, h) do { _Pragma("unroll") for (int m = 0; m < 4; ++m) _Pragma("unroll") for (int k = 0; k < 2; ++k) dst[m][k] = *(const PG8_LAS bf16x8*)(lds + PG8_SA(b, h) + aoff + m * 2048 + k * 1024); } while (0)
; #define PG8_LDB(dst, b, h) do { _Pragma("unroll") for (int n = 0; n < 2; ++n) _Pragma("unroll") for (int k = 0; k < 2; ++k) dst[n][k] = *(const PG8_LAS bf16x8*)(lds + PG8_SB(b, h) + boff + n * 2048 + k * 1024); } while (0)
; #define PG8_MMA(ai, bj, At, Bt) do { __builtin_amdgcn_s_setprio(1); _Pragma("unroll") for (int m = 0; m < 4; ++m) _Pragma("unroll") for (int n = 0; n < 2; ++n) _Pragma("unroll") for (int k = 0; k < 2; ++k) \
;         acc[ai][bj][m][n] = __builtin_amdgcn_mfma_f32_16x16x32_bf16(Bt[n][k], At[m][k], acc[ai][bj][m][n], 0, 0, 0); __builtin_amdgcn_s_setprio(0); } while (0)
; template <class Epi, class Sched, bool ALIGN_EPI = false, bool SP2 = false>
; __device__ __forceinline__ void gemm_phase(PG8_LAS unsigned char* lds, const Gemm g, const Sched& S, const Epi& E, const int wid) {
;     ...
;             if constexpr (SP2) {
;             PG8_LDB(B0, 0, 0); PG8_LDB(B1, 0, 1); PG8_SCHED; PG8_LDA(At, 0, 0); PG8_STAGE(PG8_SA(1, 1), a1 + hstep, voffA);
;             PG8_WAIT_V(8); PG8_WAIT_L(0); PG8_BAR; PG8_MMA(0, 0, At, B0); PG8_MMA(0, 1, At, B1); PG8_BAR; PG8_SCHED;
;             PG8_LDA(At, 0, 1); PG8_STAGE(PG8_SB(0, 0), b2, voffB); PG8_STAGE(PG8_SB(0, 1), b2 + hstep, voffB); PG8_STAGE(PG8_SA(0, 0), a2, voffA);
;             PG8_WAIT_V(8); PG8_WAIT_L(0); PG8_BAR; PG8_MMA(1, 0, At, B0); PG8_MMA(1, 1, At, B1); PG8_BAR; PG8_SCHED;
;             PG8_LDB(B0, 1, 0); PG8_LDB(B1, 1, 1); PG8_SCHED; PG8_LDA(At, 1, 0); PG8_STAGE(PG8_SA(0, 1), a2 + hstep, voffA);
;             PG8_WAIT_V(8); PG8_WAIT_L(0); PG8_BAR; PG8_MMA(0, 0, At, B0); PG8_MMA(0, 1, At, B1); PG8_BAR; PG8_SCHED;
;             PG8_LDA(At, 1, 1); PG8_STAGE(PG8_SB(1, 0), b3, voffB); PG8_STAGE(PG8_SB(1, 1), b3 + hstep, voffB); PG8_STAGE(PG8_SA(1, 0), a3, voffA);
;             PG8_WAIT_V(8); PG8_WAIT_L(0); PG8_BAR; PG8_MMA(1, 0, At, B0); PG8_MMA(1, 1, At, B1); PG8_BAR; PG8_SCHED;
	s_waitcnt lgkmcnt(0)
	v_mfma_f32_16x16x32_bf16 v[60:63], v[150:153], v[182:185], v[60:63]
	v_mfma_f32_16x16x32_bf16 v[56:59], v[158:161], v[182:185], v[56:59]
	v_mfma_f32_16x16x32_bf16 v[52:55], v[150:153], v[190:193], v[52:55]
	v_mfma_f32_16x16x32_bf16 v[48:51], v[158:161], v[190:193], v[48:51]
	v_mfma_f32_16x16x32_bf16 v[36:39], v[150:153], v[198:201], v[36:39]
	v_mfma_f32_16x16x32_bf16 v[32:35], v[158:161], v[198:201], v[32:35]
	v_mfma_f32_16x16x32_bf16 v[20:23], v[150:153], v[210:213], v[20:23]
	v_mfma_f32_16x16x32_bf16 v[16:19], v[158:161], v[210:213], v[16:19]
	v_mfma_f32_16x16x32_bf16 v[60:63], v[154:157], v[186:189], v[60:63]
	v_mfma_f32_16x16x32_bf16 v[56:59], v[162:165], v[186:189], v[56:59]
	v_mfma_f32_16x16x32_bf16 v[52:55], v[154:157], v[194:197], v[52:55]
	v_mfma_f32_16x16x32_bf16 v[48:51], v[162:165], v[194:197], v[48:51]
	v_mfma_f32_16x16x32_bf16 v[36:39], v[154:157], v[206:209], v[36:39]
	v_mfma_f32_16x16x32_bf16 v[32:35], v[162:165], v[206:209], v[32:35]
	v_mfma_f32_16x16x32_bf16 v[20:23], v[154:157], v[214:217], v[20:23]
	v_mfma_f32_16x16x32_bf16 v[16:19], v[162:165], v[214:217], v[16:19]
	v_mfma_f32_16x16x32_bf16 v[44:47], v[166:169], v[182:185], v[44:47]
	v_mfma_f32_16x16x32_bf16 v[40:43], v[174:177], v[182:185], v[40:43]
	v_mfma_f32_16x16x32_bf16 v[28:31], v[166:169], v[190:193], v[28:31]
	v_mfma_f32_16x16x32_bf16 v[24:27], v[174:177], v[190:193], v[24:27]
	v_mfma_f32_16x16x32_bf16 v[12:15], v[166:169], v[198:201], v[12:15]
	v_mfma_f32_16x16x32_bf16 v[8:11], v[174:177], v[198:201], v[8:11]
	v_mfma_f32_16x16x32_bf16 v[4:7], v[166:169], v[210:213], v[4:7]
	v_mfma_f32_16x16x32_bf16 v[0:3], v[174:177], v[210:213], v[0:3]
	v_mfma_f32_16x16x32_bf16 v[44:47], v[170:173], v[186:189], v[44:47]
	v_mfma_f32_16x16x32_bf16 v[40:43], v[178:181], v[186:189], v[40:43]
	v_mfma_f32_16x16x32_bf16 v[28:31], v[170:173], v[194:197], v[28:31]
	v_mfma_f32_16x16x32_bf16 v[24:27], v[178:181], v[194:197], v[24:27]
	v_mfma_f32_16x16x32_bf16 v[12:15], v[170:173], v[206:209], v[12:15]
	v_mfma_f32_16x16x32_bf16 v[8:11], v[178:181], v[206:209], v[8:11]
	v_mfma_f32_16x16x32_bf16 v[4:7], v[170:173], v[214:217], v[4:7]
	v_mfma_f32_16x16x32_bf16 v[0:3], v[178:181], v[214:217], v[0:3]
	s_barrier
	s_add_i32 s70, 0, 0x18000
	s_add_i32 s71, 0, 0x1c000
	v_add_u32_e32 v162, s70, v145
	v_add_u32_e32 v178, s71, v145
	ds_read_b128 v[150:153], v162
	ds_read_b128 v[154:157], v162 offset:1024
	ds_read_b128 v[158:161], v162 offset:2048
	ds_read_b128 v[162:165], v162 offset:3072
	ds_read_b128 v[166:169], v178
	ds_read_b128 v[170:173], v178 offset:1024
	ds_read_b128 v[174:177], v178 offset:2048
	ds_read_b128 v[178:181], v178 offset:3072
	s_add_u32 s30, s30, 0x40000
	s_addc_u32 s31, s31, 0
	s_mov_b32 m0, s39
	v_lshl_add_u64 v[224:225], s[30:31], 0, v[134:135]
	ds_read_b128 v[182:185], v149 offset:32768
	ds_read_b128 v[186:189], v149 offset:33792
	ds_read_b128 v[190:193], v149 offset:34816
	ds_read_b128 v[194:197], v149 offset:35840
	ds_read_b128 v[198:201], v149 offset:36864
	ds_read_b128 v[206:209], v149 offset:37888
	ds_read_b128 v[210:213], v149 offset:38912
	ds_read_b128 v[214:217], v149 offset:39936
	global_load_lds_dwordx4 v[224:225], off
	v_lshl_add_u64 v[224:225], s[30:31], 0, v[130:131]
	s_mov_b32 m0, s40
	s_nop 0
	global_load_lds_dwordx4 v[224:225], off
	s_waitcnt vmcnt(8)
	s_waitcnt lgkmcnt(0)
	s_barrier
	s_waitcnt lgkmcnt(0)
	v_mfma_f32_16x16x32_bf16 v[124:127], v[150:153], v[182:185], v[124:127]
	v_mfma_f32_16x16x32_bf16 v[120:123], v[158:161], v[182:185], v[120:123]
	v_mfma_f32_16x16x32_bf16 v[116:119], v[150:153], v[190:193], v[116:119]
	v_mfma_f32_16x16x32_bf16 v[112:115], v[158:161], v[190:193], v[112:115]
	v_mfma_f32_16x16x32_bf16 v[100:103], v[150:153], v[198:201], v[100:103]
	v_mfma_f32_16x16x32_bf16 v[96:99], v[158:161], v[198:201], v[96:99]
	v_mfma_f32_16x16x32_bf16 v[84:87], v[150:153], v[210:213], v[84:87]
	v_mfma_f32_16x16x32_bf16 v[80:83], v[158:161], v[210:213], v[80:83]
	v_mfma_f32_16x16x32_bf16 v[124:127], v[154:157], v[186:189], v[124:127]
	v_mfma_f32_16x16x32_bf16 v[120:123], v[162:165], v[186:189], v[120:123]
	v_mfma_f32_16x16x32_bf16 v[116:119], v[154:157], v[194:197], v[116:119]
	v_mfma_f32_16x16x32_bf16 v[112:115], v[162:165], v[194:197], v[112:115]
	v_mfma_f32_16x16x32_bf16 v[100:103], v[154:157], v[206:209], v[100:103]
	v_mfma_f32_16x16x32_bf16 v[96:99], v[162:165], v[206:209], v[96:99]
	v_mfma_f32_16x16x32_bf16 v[84:87], v[154:157], v[214:217], v[84:87]
	v_mfma_f32_16x16x32_bf16 v[80:83], v[162:165], v[214:217], v[80:83]
	v_mfma_f32_16x16x32_bf16 v[108:111], v[166:169], v[182:185], v[108:111]
	v_mfma_f32_16x16x32_bf16 v[104:107], v[174:177], v[182:185], v[104:107]
	v_mfma_f32_16x16x32_bf16 v[92:95], v[166:169], v[190:193], v[92:95]
	v_mfma_f32_16x16x32_bf16 v[88:91], v[174:177], v[190:193], v[88:91]
	v_mfma_f32_16x16x32_bf16 v[76:79], v[166:169], v[198:201], v[76:79]
	v_mfma_f32_16x16x32_bf16 v[72:75], v[174:177], v[198:201], v[72:75]
	v_mfma_f32_16x16x32_bf16 v[68:71], v[166:169], v[210:213], v[68:71]
	v_mfma_f32_16x16x32_bf16 v[64:67], v[174:177], v[210:213], v[64:67]
	v_mfma_f32_16x16x32_bf16 v[108:111], v[170:173], v[186:189], v[108:111]
	v_mfma_f32_16x16x32_bf16 v[104:107], v[178:181], v[186:189], v[104:107]
	v_mfma_f32_16x16x32_bf16 v[92:95], v[170:173], v[194:197], v[92:95]
	v_mfma_f32_16x16x32_bf16 v[88:91], v[178:181], v[194:197], v[88:91]
	v_mfma_f32_16x16x32_bf16 v[76:79], v[170:173], v[206:209], v[76:79]
	v_mfma_f32_16x16x32_bf16 v[72:75], v[178:181], v[206:209], v[72:75]
	v_mfma_f32_16x16x32_bf16 v[68:71], v[170:173], v[214:217], v[68:71]
	v_mfma_f32_16x16x32_bf16 v[64:67], v[178:181], v[214:217], v[64:67]
	s_barrier
; #define PG8_STAGE(bufoff, gbase, voff) do { _Pragma("unroll") for (int _i = 0; _i < 2; ++_i) \
;         __builtin_amdgcn_global_load_lds((const unsigned*)((const char*)(gbase) + (voff)[_i]), (PG8_LAS unsigned*)(lds + (bufoff) + ldsw + _i * 8192), 16, 0, 0); } while (0)
; #define PG8_LDA(dst, b, h) do { _Pragma("unroll") for (int m = 0; m < 4; ++m) _Pragma("unroll") for (int k = 0; k < 2; ++k) dst[m][k] = *(const PG8_LAS bf16x8*)(lds + PG8_SA(b, h) + aoff + m * 2048 + k * 1024); } while (0)
; #define PG8_LDB(dst, b, h) do { _Pragma("unroll") for (int n = 0; n < 2; ++n) _Pragma("unroll") for (int k = 0; k < 2; ++k) dst[n][k] = *(const PG8_LAS bf16x8*)(lds + PG8_SB(b, h) + boff + n * 2048 + k * 1024); } while (0)
; #define PG8_MMA(ai, bj, At, Bt) do { __builtin_amdgcn_s_setprio(1); _Pragma("unroll") for (int m = 0; m < 4; ++m) _Pragma("unroll") for (int n = 0; n < 2; ++n) _Pragma("unroll") for (int k = 0; k < 2; ++k) \
;         acc[ai][bj][m][n] = __builtin_amdgcn_mfma_f32_16x16x32_bf16(Bt[n][k], At[m][k], acc[ai][bj][m][n], 0, 0, 0); __builtin_amdgcn_s_setprio(0); } while (0)
; template <class Epi, class Sched, bool ALIGN_EPI = false, bool SP2 = false>
; __device__ __forceinline__ void gemm_phase(PG8_LAS unsigned char* lds, const Gemm g, const Sched& S, const Epi& E, const int wid) {
;     ...
;             if constexpr (SP2) {
;             PG8_LDB(B0, 0, 0); PG8_LDB(B1, 0, 1); PG8_SCHED; PG8_LDA(At, 0, 0); PG8_STAGE(PG8_SA(1, 1), a1 + hstep, voffA);
;             PG8_WAIT_V(8); PG8_WAIT_L(0); PG8_BAR; PG8_MMA(0, 0, At, B0); PG8_MMA(0, 1, At, B1); PG8_BAR; PG8_SCHED;
;             PG8_LDA(At, 0, 1); PG8_STAGE(PG8_SB(0, 0), b2, voffB); PG8_STAGE(PG8_SB(0, 1), b2 + hstep, voffB); PG8_STAGE(PG8_SA(0, 0), a2, voffA);
;             PG8_WAIT_V(8); PG8_WAIT_L(0); PG8_BAR; PG8_MMA(1, 0, At, B0); PG8_MMA(1, 1, At, B1); PG8_BAR; PG8_SCHED;
;             PG8_LDB(B0, 1, 0); PG8_LDB(B1, 1, 1); PG8_SCHED; PG8_LDA(At, 1, 0); PG8_STAGE(PG8_SA(0, 1), a2 + hstep, voffA);
;             PG8_WAIT_V(8); PG8_WAIT_L(0); PG8_BAR; PG8_MMA(0, 0, At, B0); PG8_MMA(0, 1, At, B1); PG8_BAR; PG8_SCHED;
;             PG8_LDA(At, 1, 1); PG8_STAGE(PG8_SB(1, 0), b3, voffB); PG8_STAGE(PG8_SB(1, 1), b3 + hstep, voffB); PG8_STAGE(PG8_SA(1, 0), a3, voffA);
;             PG8_WAIT_V(8); PG8_WAIT_L(0); PG8_BAR; PG8_MMA(1, 0, At, B0); PG8_MMA(1, 1, At, B1); PG8_BAR; PG8_SCHED;
	s_add_i32 s30, s70, s33
	v_lshl_add_u64 v[202:203], v[202:203], 0, s[6:7]
	s_mov_b32 m0, s30
	ds_read_b128 v[182:185], v149 offset:49152
	ds_read_b128 v[186:189], v149 offset:50176
	ds_read_b128 v[190:193], v149 offset:51200
	ds_read_b128 v[194:197], v149 offset:52224
	ds_read_b128 v[198:201], v149 offset:53248
	ds_read_b128 v[206:209], v149 offset:54272
	ds_read_b128 v[210:213], v149 offset:55296
	ds_read_b128 v[214:217], v149 offset:56320
	global_load_lds_dwordx4 v[202:203], off
	s_add_i32 m0, s30, 0x2000
	s_add_u32 s28, s28, 0x40080
	v_lshl_add_u64 v[202:203], v[218:219], 0, s[6:7]
	s_addc_u32 s29, s29, 0
	s_add_i32 s30, s71, s33
	global_load_lds_dwordx4 v[202:203], off
	v_lshl_add_u64 v[202:203], s[28:29], 0, v[132:133]
	s_mov_b32 m0, s30
	s_nop 0
	global_load_lds_dwordx4 v[202:203], off
	v_lshl_add_u64 v[202:203], s[28:29], 0, v[128:129]
	s_add_i32 m0, s30, 0x2000
	s_nop 0
	global_load_lds_dwordx4 v[202:203], off
	v_lshl_add_u64 v[202:203], v[220:221], 0, s[6:7]
	s_mov_b32 m0, s42
	s_nop 0
	global_load_lds_dwordx4 v[202:203], off
	v_lshl_add_u64 v[202:203], v[222:223], 0, s[6:7]
	s_mov_b32 m0, s43
	s_nop 0
	global_load_lds_dwordx4 v[202:203], off
	s_waitcnt vmcnt(8)
	s_waitcnt lgkmcnt(0)
	s_barrier
	s_waitcnt lgkmcnt(0)
	v_mfma_f32_16x16x32_bf16 v[60:63], v[150:153], v[182:185], v[60:63]
	v_mfma_f32_16x16x32_bf16 v[56:59], v[158:161], v[182:185], v[56:59]
	v_mfma_f32_16x16x32_bf16 v[52:55], v[150:153], v[190:193], v[52:55]
	v_mfma_f32_16x16x32_bf16 v[48:51], v[158:161], v[190:193], v[48:51]
	v_mfma_f32_16x16x32_bf16 v[36:39], v[150:153], v[198:201], v[36:39]
	v_mfma_f32_16x16x32_bf16 v[32:35], v[158:161], v[198:201], v[32:35]
	v_mfma_f32_16x16x32_bf16 v[20:23], v[150:153], v[210:213], v[20:23]
	v_mfma_f32_16x16x32_bf16 v[16:19], v[158:161], v[210:213], v[16:19]
	v_mfma_f32_16x16x32_bf16 v[60:63], v[154:157], v[186:189], v[60:63]
	v_mfma_f32_16x16x32_bf16 v[56:59], v[162:165], v[186:189], v[56:59]
	v_mfma_f32_16x16x32_bf16 v[52:55], v[154:157], v[194:197], v[52:55]
	v_mfma_f32_16x16x32_bf16 v[48:51], v[162:165], v[194:197], v[48:51]
	v_mfma_f32_16x16x32_bf16 v[36:39], v[154:157], v[206:209], v[36:39]
	v_mfma_f32_16x16x32_bf16 v[32:35], v[162:165], v[206:209], v[32:35]
	v_mfma_f32_16x16x32_bf16 v[20:23], v[154:157], v[214:217], v[20:23]
	v_mfma_f32_16x16x32_bf16 v[16:19], v[162:165], v[214:217], v[16:19]
	v_mfma_f32_16x16x32_bf16 v[44:47], v[166:169], v[182:185], v[44:47]
	v_mfma_f32_16x16x32_bf16 v[40:43], v[174:177], v[182:185], v[40:43]
	v_mfma_f32_16x16x32_bf16 v[28:31], v[166:169], v[190:193], v[28:31]
	v_mfma_f32_16x16x32_bf16 v[24:27], v[174:177], v[190:193], v[24:27]
	v_mfma_f32_16x16x32_bf16 v[12:15], v[166:169], v[198:201], v[12:15]
	v_mfma_f32_16x16x32_bf16 v[8:11], v[174:177], v[198:201], v[8:11]
	v_mfma_f32_16x16x32_bf16 v[4:7], v[166:169], v[210:213], v[4:7]
	v_mfma_f32_16x16x32_bf16 v[0:3], v[174:177], v[210:213], v[0:3]
	v_mfma_f32_16x16x32_bf16 v[44:47], v[170:173], v[186:189], v[44:47]
	v_mfma_f32_16x16x32_bf16 v[40:43], v[178:181], v[186:189], v[40:43]
	v_mfma_f32_16x16x32_bf16 v[28:31], v[170:173], v[194:197], v[28:31]
	v_mfma_f32_16x16x32_bf16 v[24:27], v[178:181], v[194:197], v[24:27]
	v_mfma_f32_16x16x32_bf16 v[12:15], v[170:173], v[206:209], v[12:15]
	v_mfma_f32_16x16x32_bf16 v[8:11], v[178:181], v[206:209], v[8:11]
	v_mfma_f32_16x16x32_bf16 v[4:7], v[170:173], v[214:217], v[4:7]
	v_mfma_f32_16x16x32_bf16 v[0:3], v[178:181], v[214:217], v[0:3]
	s_barrier
	s_add_i32 s69, s69, 2
	s_add_u32 s26, s26, 0x100
	s_addc_u32 s27, s27, 0
	s_add_u32 s51, s51, 0x100
	s_addc_u32 s68, s68, 0
	s_cmp_gt_u32 s69, 13
	s_cbranch_scc0 .LBB0_373
	s_and_b64 vcc, exec, s[8:9]
	s_cbranch_vccz .LBB0_376
	s_barrier

; #define PG8_WAIT_V(n) asm volatile("s_waitcnt vmcnt(" #n ")" ::: "memory")
; #define PG8_BAR __builtin_amdgcn_s_barrier()
;     __host__ __device__ bool next(int i, Unit& u) const {
;         const long L = (long)i * G + c; if (L >= nwg) return false;
;         int wgid = (int)L; { const int q = nwg / NXCD, r = nwg % NXCD, xcd = wgid % NXCD, off = wgid / NXCD; wgid = (xcd < r ? xcd * (q + 1) : r * (q + 1) + (xcd - r) * q) + off; }
;         const int nig = WGM * nN, gid = wgid / nig, fm = gid * WGM, gsz = (nM - fm) < WGM ? (nM - fm) : WGM;
;         u.pm = fm + ((wgid % nig) % gsz); u.pn = (wgid % nig) / gsz; return true;
; template <class Epi, class Sched, bool ALIGN_EPI = false, bool SP2 = false>
; __device__ __forceinline__ void gemm_phase(PG8_LAS unsigned char* lds, const Gemm g, const Sched& S, const Epi& E, const int wid) {
;     const int lane = lane_now(), tid = wid * 64 + lane, wr = wid >> 2, wc = wid & 3, fr = lane & 15, fq = lane >> 4;
;     const int K = g.K, nt = K / BK;
;     unsigned voffA[2], voffB[2];
; #pragma unroll
;     for (int i = 0; i < 2; ++i) { int R, C; stage_rc(tid * 16 + i * 8192, R, C); const int Rb = Epi::PERM ? ((R & ~31) + perm32(R & 31)) : R;
;         voffA[i] = (unsigned)(R * K + C) * 2u; voffB[i] = (unsigned)(Rb * K + C) * 2u; }
;     const size_t kstep = (size_t)(BK * 2);
;     const size_t hstep = (size_t)HALF * K * 2;
;     const size_t tstep = 2 * hstep;
;     const unsigned ldsw = (unsigned)wid * 1024u;
;     const int aoff = lds_byte(wr * 64 + fr, fq * 8), boff = lds_byte(wc * 32 + fr, fq * 8);
;     ...
;     Unit cur, nxt; int ui = 0;
;     if (!S.next(0, cur)) return;
;     f32x4 acc[2][2][4][2];
; #pragma unroll
;     for (int a = 0; a < 2; ++a)
; #pragma unroll
;         for (int b = 0; b < 2; ++b)
; #pragma unroll
;             for (int m = 0; m < 4; ++m)
; #pragma unroll
;                 for (int n = 0; n < 2; ++n) acc[a][b][m][n] = (f32x4){0.f, 0.f, 0.f, 0.f};
;     bf16x8 At[4][2], B0[2][2], B1[2][2];
;     const char* cA = (const char*)g.A + (size_t)cur.pm * tstep; const char* cB = (const char*)g.Bt + (size_t)cur.pn * tstep;
;     S.a_ready(cur);
;     if constexpr (SP2) {
;         PG8_STAGE(PG8_SB(0, 0), cB, voffB); PG8_STAGE(PG8_SB(0, 1), cB + hstep, voffB); PG8_STAGE(PG8_SA(0, 0), cA, voffA); PG8_STAGE(PG8_SA(0, 1), cA + hstep, voffA);
;         if (wr == 1) PG8_BAR;
;         PG8_WAIT_V(2); PG8_BAR;
.LBB0_1158:
	v_lshl_add_u32 v0, v8, 4, s33
	v_ashrrev_i32_e32 v1, 31, v0
	v_lshrrev_b32_e32 v1, 22, v1
	v_add_u32_e32 v1, v0, v1
	v_ashrrev_i32_e32 v9, 10, v1
	v_mul_i32_i24_e32 v1, 0x400, v9
	v_sub_u32_e32 v1, v0, v1
	v_lshrrev_b32_e32 v2, 4, v1
	v_bitop3_b32 v1, v2, v1, 32 bitop3:0x6c
	v_ashrrev_i32_e32 v3, 31, v1
	v_lshrrev_b32_e32 v3, 26, v3
	v_add_u32_e32 v3, v1, v3
	v_lshlrev_b32_e32 v2, 3, v9
	v_ashrrev_i32_e32 v10, 6, v3
	v_and_b32_e32 v3, 0xc0, v3
	v_and_b32_e32 v2, -16, v2
	v_sub_u32_e32 v1, v1, v3
	v_mov_b32_e32 v3, 1
	v_add_u32_e32 v2, v10, v2
	v_ashrrev_i16_sdwa v1, v3, sext(v1) dst_sel:DWORD dst_unused:UNUSED_PAD src0_sel:DWORD src1_sel:BYTE_0
	v_lshlrev_b32_e32 v4, 5, v9
	v_bfe_i32 v11, v1, 0, 16
	v_lshlrev_b32_e32 v1, 1, v2
	v_lshrrev_b32_e32 v5, 2, v2
	v_and_b32_e32 v6, 3, v10
	s_mov_b32 s1, 0x1fffe0
	v_and_b32_e32 v4, 32, v4
	v_and_b32_e32 v1, 24, v1
	v_and_b32_e32 v5, 4, v5
	v_and_or_b32 v6, v2, s1, v6
	v_or3_b32 v1, v6, v5, v1
	v_add_lshl_u32 v4, v4, v11, 1
	v_add_u32_e32 v0, 0x2000, v0
	v_lshl_add_u32 v138, v1, 11, v4
	v_ashrrev_i32_e32 v1, 31, v0
	v_lshrrev_b32_e32 v1, 22, v1
	v_add_u32_e32 v1, v0, v1
	v_ashrrev_i32_e32 v12, 10, v1
	v_mul_i32_i24_e32 v1, 0x400, v12
	v_sub_u32_e32 v0, v0, v1
	v_lshrrev_b32_e32 v1, 4, v0
	v_bitop3_b32 v0, v1, v0, 32 bitop3:0x6c
	v_lshl_add_u32 v136, v2, 11, v4
	v_ashrrev_i32_e32 v2, 31, v0
	v_lshrrev_b32_e32 v2, 26, v2
	v_add_u32_e32 v2, v0, v2
	v_ashrrev_i32_e32 v13, 6, v2
	v_and_b32_e32 v2, 0xffc0, v2
	v_sub_u32_e32 v0, v0, v2
	v_lshrrev_b16_e32 v2, 7, v0
	s_ashr_i32 s0, s7, 3
	v_lshlrev_b32_e32 v1, 3, v12
	v_and_b32_e32 v2, 1, v2
	s_add_u32 s39, s92, 0x2880000
	v_and_b32_e32 v1, -16, v1
	v_add_u16_e32 v0, v0, v2
	s_addc_u32 s40, s93, 0
	v_add_u32_e32 v1, v13, v1
	v_ashrrev_i16_sdwa v0, v3, sext(v0) dst_sel:DWORD dst_unused:UNUSED_PAD src0_sel:DWORD src1_sel:BYTE_0
	v_and_b32_e32 v3, 3, v13
	s_add_i32 s0, s6, s0
	v_and_or_b32 v3, v1, s1, v3
	s_ashr_i32 s1, s0, 31
	s_lshr_b32 s1, s1, 28
	s_add_i32 s1, s0, s1
	s_ashr_i32 s6, s1, 4
	s_and_b32 s1, s1, -16
	s_sub_i32 s0, s0, s1
	s_bfe_i32 s1, s0, 0x80000
	s_bfe_u32 s1, s1, 0x2000d
	s_add_i32 s1, s0, s1
	s_lshl_b32 s7, s6, 2
	s_bfe_i32 s6, s1, 0x80000
	s_and_b32 s1, s1, 0xfc
	s_sub_i32 s0, s0, s1
	s_sext_i32_i16 s6, s6
	s_sext_i32_i8 s0, s0
	s_lshr_b32 s6, s6, 2
	s_add_i32 s28, s7, s0
	s_ashr_i32 s29, s28, 31
	s_bfe_i64 s[8:9], s[6:7], 0x100000
	s_lshl_b64 s[0:1], s[28:29], 19
	s_lshl_b64 s[8:9], s[8:9], 19
	s_add_u32 s34, s39, s8
	v_lshlrev_b32_e32 v4, 5, v12
	v_bfe_i32 v14, v0, 0, 16
	v_lshlrev_b32_e32 v0, 1, v1
	v_lshrrev_b32_e32 v2, 2, v1
	s_addc_u32 s35, s40, s9
	s_add_i32 s29, s33, 0
	v_and_b32_e32 v4, 32, v4
	v_and_b32_e32 v0, 24, v0
	v_and_b32_e32 v2, 4, v2
	s_add_i32 m0, s29, 0x10000
	v_or3_b32 v0, v3, v2, v0
	v_add_lshl_u32 v2, v4, v14, 1
	global_load_lds_dwordx4 v138, s[34:35]
	s_add_i32 m0, s29, 0x12000
	v_lshl_add_u32 v142, v0, 11, v2
	s_add_u32 s8, s34, 0x40000
	global_load_lds_dwordx4 v142, s[34:35]
	s_addc_u32 s9, s35, 0
	s_add_i32 m0, s29, 0x14000
	v_lshl_add_u32 v140, v1, 11, v2
	global_load_lds_dwordx4 v138, s[8:9]
	s_add_i32 m0, s29, 0x16000
	s_add_u32 s30, s96, s0
	s_addc_u32 s31, s97, s1
	s_add_i32 s41, s29, 0x2000
	global_load_lds_dwordx4 v142, s[8:9]
	s_mov_b32 m0, s29
	s_add_u32 s0, s30, 0x40000
	global_load_lds_dwordx4 v136, s[30:31]
	s_mov_b32 m0, s41
	s_addc_u32 s1, s31, 0
	s_add_i32 s42, s29, 0x4000
	global_load_lds_dwordx4 v140, s[30:31]
	s_mov_b32 m0, s42
	s_add_i32 s43, s29, 0x6000
	global_load_lds_dwordx4 v136, s[0:1]
	s_mov_b32 m0, s43
	v_mov_b32_e32 v139, 0
	global_load_lds_dwordx4 v140, s[0:1]
	v_readlane_b32 s7, v244, 18
	v_mov_b32_e32 v143, v139
	v_mov_b32_e32 v137, v139
	v_mov_b32_e32 v141, v139
	s_cmp_eq_u32 s7, 1
	s_mov_b32 s44, 0
	v_lshl_add_u64 v[4:5], s[34:35], 0, v[138:139]
	v_lshl_add_u64 v[2:3], s[34:35], 0, v[142:143]
	v_lshl_add_u64 v[0:1], s[30:31], 0, v[136:137]
	s_cselect_b64 s[0:1], -1, 0
	s_cmp_lg_u32 s7, 1
	v_lshl_add_u64 v[6:7], s[30:31], 0, v[140:141]
	s_cbranch_scc1 .LBB0_1160
	s_barrier
	s_setprio 1

; #define PG8_STAGE(bufoff, gbase, voff) do { _Pragma("unroll") for (int _i = 0; _i < 2; ++_i) \
;         __builtin_amdgcn_global_load_lds((const unsigned*)((const char*)(gbase) + (voff)[_i]), (PG8_LAS unsigned*)(lds + (bufoff) + ldsw + _i * 8192), 16, 0, 0); } while (0)
; #define PG8_LDA(dst, b, h) do { _Pragma("unroll") for (int m = 0; m < 4; ++m) _Pragma("unroll") for (int k = 0; k < 2; ++k) dst[m][k] = *(const PG8_LAS bf16x8*)(lds + PG8_SA(b, h) + aoff + m * 2048 + k * 1024); } while (0)
; #define PG8_LDB(dst, b, h) do { _Pragma("unroll") for (int n = 0; n < 2; ++n) _Pragma("unroll") for (int k = 0; k < 2; ++k) dst[n][k] = *(const PG8_LAS bf16x8*)(lds + PG8_SB(b, h) + boff + n * 2048 + k * 1024); } while (0)
; #define PG8_MMA(ai, bj, At, Bt) do { __builtin_amdgcn_s_setprio(1); _Pragma("unroll") for (int m = 0; m < 4; ++m) _Pragma("unroll") for (int n = 0; n < 2; ++n) _Pragma("unroll") for (int k = 0; k < 2; ++k) \
;         acc[ai][bj][m][n] = __builtin_amdgcn_mfma_f32_16x16x32_bf16(Bt[n][k], At[m][k], acc[ai][bj][m][n], 0, 0, 0); __builtin_amdgcn_s_setprio(0); } while (0)
; #define PG8_WAIT_V(n) asm volatile("s_waitcnt vmcnt(" #n ")" ::: "memory")
; #define PG8_WAIT_L(n) asm volatile("s_waitcnt lgkmcnt(" #n ")" ::: "memory")
; #define PG8_BAR __builtin_amdgcn_s_barrier()
; #define PG8_SCHED __builtin_amdgcn_sched_barrier(0)
; template <class Epi, class Sched, bool ALIGN_EPI = false, bool SP2 = false>
; __device__ __forceinline__ void gemm_phase(PG8_LAS unsigned char* lds, const Gemm g, const Sched& S, const Epi& E, const int wid) {
;     ...
;             PG8_LDB(B0, 0, 0); PG8_LDB(B1, 0, 1); PG8_SCHED; PG8_LDA(At, 0, 0); PG8_STAGE(PG8_SA(1, 1), a1 + hstep, voffA);
;             PG8_WAIT_V(8); PG8_WAIT_L(0); PG8_BAR; PG8_MMA(0, 0, At, B0); PG8_MMA(0, 1, At, B1); PG8_BAR; PG8_SCHED;
;             PG8_LDA(At, 0, 1); PG8_STAGE(PG8_SB(0, 0), b2, voffB); PG8_STAGE(PG8_SB(0, 1), b2 + hstep, voffB); PG8_STAGE(PG8_SA(0, 0), a2, voffA);
;             PG8_WAIT_V(8); PG8_WAIT_L(0); PG8_BAR; PG8_MMA(1, 0, At, B0); PG8_MMA(1, 1, At, B1); PG8_BAR; PG8_SCHED;
.LBB0_1170:
	ds_read_b128 v[128:131], v168
	ds_read_b128 v[132:135], v168 offset:1024
	ds_read_b128 v[152:155], v168 offset:2048
	ds_read_b128 v[156:159], v168 offset:3072
	ds_read_b128 v[160:163], v169
	ds_read_b128 v[172:175], v169 offset:1024
	ds_read_b128 v[176:179], v169 offset:2048
	ds_read_b128 v[180:183], v169 offset:3072
	s_add_u32 s34, s30, 0xfffc0080
	s_addc_u32 s35, s31, -1
	s_cmp_eq_u32 s58, 12
	s_cselect_b32 s37, s23, s35
	s_cselect_b32 s36, s54, s34
	s_cselect_b32 s35, s21, s57
	s_cselect_b32 s34, s55, s56
	v_lshl_add_u64 v[216:217], s[30:31], 0, v[144:145]
	s_add_i32 m0, s29, 0xc000
	ds_read_b128 v[184:187], v170
	ds_read_b128 v[188:191], v170 offset:1024
	ds_read_b128 v[192:195], v170 offset:2048
	ds_read_b128 v[196:199], v170 offset:3072
	ds_read_b128 v[200:203], v170 offset:4096
	ds_read_b128 v[204:207], v170 offset:5120
	ds_read_b128 v[208:211], v170 offset:6144
	ds_read_b128 v[212:215], v170 offset:7168
	global_load_lds_dwordx4 v[216:217], off
	v_lshl_add_u64 v[216:217], s[30:31], 0, v[146:147]
	s_add_i32 m0, s29, 0xe000
	s_nop 0
	global_load_lds_dwordx4 v[216:217], off
	s_waitcnt vmcnt(8)
	s_waitcnt lgkmcnt(0)
	s_barrier
	s_waitcnt lgkmcnt(0)
	v_mfma_f32_16x16x32_bf16 v[124:127], v[128:131], v[184:187], v[124:127]
	v_mfma_f32_16x16x32_bf16 v[120:123], v[152:155], v[184:187], v[120:123]
	v_mfma_f32_16x16x32_bf16 v[116:119], v[128:131], v[192:195], v[116:119]
	v_mfma_f32_16x16x32_bf16 v[112:115], v[152:155], v[192:195], v[112:115]
	v_mfma_f32_16x16x32_bf16 v[108:111], v[128:131], v[200:203], v[108:111]
	v_mfma_f32_16x16x32_bf16 v[104:107], v[152:155], v[200:203], v[104:107]
	v_mfma_f32_16x16x32_bf16 v[100:103], v[128:131], v[208:211], v[100:103]
	v_mfma_f32_16x16x32_bf16 v[96:99], v[152:155], v[208:211], v[96:99]
	v_mfma_f32_16x16x32_bf16 v[124:127], v[132:135], v[188:191], v[124:127]
	v_mfma_f32_16x16x32_bf16 v[120:123], v[156:159], v[188:191], v[120:123]
	v_mfma_f32_16x16x32_bf16 v[116:119], v[132:135], v[196:199], v[116:119]
	v_mfma_f32_16x16x32_bf16 v[112:115], v[156:159], v[196:199], v[112:115]
	v_mfma_f32_16x16x32_bf16 v[108:111], v[132:135], v[204:207], v[108:111]
	v_mfma_f32_16x16x32_bf16 v[104:107], v[156:159], v[204:207], v[104:107]
	v_mfma_f32_16x16x32_bf16 v[100:103], v[132:135], v[212:215], v[100:103]
	v_mfma_f32_16x16x32_bf16 v[96:99], v[156:159], v[212:215], v[96:99]
	v_mfma_f32_16x16x32_bf16 v[60:63], v[160:163], v[184:187], v[60:63]
	v_mfma_f32_16x16x32_bf16 v[56:59], v[176:179], v[184:187], v[56:59]
	v_mfma_f32_16x16x32_bf16 v[52:55], v[160:163], v[192:195], v[52:55]
	v_mfma_f32_16x16x32_bf16 v[48:51], v[176:179], v[192:195], v[48:51]
	v_mfma_f32_16x16x32_bf16 v[44:47], v[160:163], v[200:203], v[44:47]
	v_mfma_f32_16x16x32_bf16 v[40:43], v[176:179], v[200:203], v[40:43]
	v_mfma_f32_16x16x32_bf16 v[36:39], v[160:163], v[208:211], v[36:39]
	v_mfma_f32_16x16x32_bf16 v[32:35], v[176:179], v[208:211], v[32:35]
	v_mfma_f32_16x16x32_bf16 v[60:63], v[172:175], v[188:191], v[60:63]
	v_mfma_f32_16x16x32_bf16 v[56:59], v[180:183], v[188:191], v[56:59]
	v_mfma_f32_16x16x32_bf16 v[52:55], v[172:175], v[196:199], v[52:55]
	v_mfma_f32_16x16x32_bf16 v[48:51], v[180:183], v[196:199], v[48:51]
	v_mfma_f32_16x16x32_bf16 v[44:47], v[172:175], v[204:207], v[44:47]
	v_mfma_f32_16x16x32_bf16 v[40:43], v[180:183], v[204:207], v[40:43]
	v_mfma_f32_16x16x32_bf16 v[36:39], v[172:175], v[212:215], v[36:39]
	v_mfma_f32_16x16x32_bf16 v[32:35], v[180:183], v[212:215], v[32:35]
	s_barrier
	s_add_i32 s59, s51, s33
	v_lshl_add_u64 v[216:217], s[34:35], 0, v[138:139]
	s_mov_b32 m0, s59
	ds_read_b128 v[184:187], v170 offset:16384
	ds_read_b128 v[188:191], v170 offset:17408
	ds_read_b128 v[192:195], v170 offset:18432
	ds_read_b128 v[196:199], v170 offset:19456
	ds_read_b128 v[200:203], v170 offset:20480
	ds_read_b128 v[204:207], v170 offset:21504
	ds_read_b128 v[208:211], v170 offset:22528
	ds_read_b128 v[212:215], v170 offset:23552
	global_load_lds_dwordx4 v[216:217], off
	s_add_i32 m0, s59, 0x2000
	s_add_u32 s60, s34, 0x40000
	v_lshl_add_u64 v[218:219], s[34:35], 0, v[142:143]
	s_addc_u32 s61, s35, 0
	s_add_i32 s59, s52, s33
	global_load_lds_dwordx4 v[218:219], off
	v_lshl_add_u64 v[220:221], s[60:61], 0, v[138:139]
	s_mov_b32 m0, s59
	v_lshl_add_u64 v[222:223], s[36:37], 0, v[140:141]
	global_load_lds_dwordx4 v[220:221], off
	v_lshl_add_u64 v[220:221], s[60:61], 0, v[142:143]
	s_add_i32 m0, s59, 0x2000
	s_nop 0
	global_load_lds_dwordx4 v[220:221], off
	v_lshl_add_u64 v[220:221], s[36:37], 0, v[136:137]
	s_mov_b32 m0, s29
	s_nop 0
	global_load_lds_dwordx4 v[220:221], off
	s_mov_b32 m0, s41
	s_nop 0
	global_load_lds_dwordx4 v[222:223], off
	s_waitcnt vmcnt(8)
	s_waitcnt lgkmcnt(0)
	s_barrier
; #define PG8_STAGE(bufoff, gbase, voff) do { _Pragma("unroll") for (int _i = 0; _i < 2; ++_i) \
;         __builtin_amdgcn_global_load_lds((const unsigned*)((const char*)(gbase) + (voff)[_i]), (PG8_LAS unsigned*)(lds + (bufoff) + ldsw + _i * 8192), 16, 0, 0); } while (0)
; #define PG8_LDA(dst, b, h) do { _Pragma("unroll") for (int m = 0; m < 4; ++m) _Pragma("unroll") for (int k = 0; k < 2; ++k) dst[m][k] = *(const PG8_LAS bf16x8*)(lds + PG8_SA(b, h) + aoff + m * 2048 + k * 1024); } while (0)
; #define PG8_LDB(dst, b, h) do { _Pragma("unroll") for (int n = 0; n < 2; ++n) _Pragma("unroll") for (int k = 0; k < 2; ++k) dst[n][k] = *(const PG8_LAS bf16x8*)(lds + PG8_SB(b, h) + boff + n * 2048 + k * 1024); } while (0)
; #define PG8_MMA(ai, bj, At, Bt) do { __builtin_amdgcn_s_setprio(1); _Pragma("unroll") for (int m = 0; m < 4; ++m) _Pragma("unroll") for (int n = 0; n < 2; ++n) _Pragma("unroll") for (int k = 0; k < 2; ++k) \
;         acc[ai][bj][m][n] = __builtin_amdgcn_mfma_f32_16x16x32_bf16(Bt[n][k], At[m][k], acc[ai][bj][m][n], 0, 0, 0); __builtin_amdgcn_s_setprio(0); } while (0)
; #define PG8_WAIT_V(n) asm volatile("s_waitcnt vmcnt(" #n ")" ::: "memory")
; #define PG8_WAIT_L(n) asm volatile("s_waitcnt lgkmcnt(" #n ")" ::: "memory")
; #define PG8_BAR __builtin_amdgcn_s_barrier()
; #define PG8_SCHED __builtin_amdgcn_sched_barrier(0)
; template <class Epi, class Sched, bool ALIGN_EPI = false, bool SP2 = false>
; __device__ __forceinline__ void gemm_phase(PG8_LAS unsigned char* lds, const Gemm g, const Sched& S, const Epi& E, const int wid) {
;     ...
;             PG8_WAIT_V(8); PG8_WAIT_L(0); PG8_BAR; PG8_MMA(1, 0, At, B0); PG8_MMA(1, 1, At, B1); PG8_BAR; PG8_SCHED;
;             PG8_LDB(B0, 1, 0); PG8_LDB(B1, 1, 1); PG8_SCHED; PG8_LDA(At, 1, 0); PG8_STAGE(PG8_SA(0, 1), a2 + hstep, voffA);
;             PG8_WAIT_V(8); PG8_WAIT_L(0); PG8_BAR; PG8_MMA(0, 0, At, B0); PG8_MMA(0, 1, At, B1); PG8_BAR; PG8_SCHED;
	s_waitcnt lgkmcnt(0)
	v_mfma_f32_16x16x32_bf16 v[92:95], v[128:131], v[184:187], v[92:95]
	v_mfma_f32_16x16x32_bf16 v[88:91], v[152:155], v[184:187], v[88:91]
	v_mfma_f32_16x16x32_bf16 v[84:87], v[128:131], v[192:195], v[84:87]
	v_mfma_f32_16x16x32_bf16 v[80:83], v[152:155], v[192:195], v[80:83]
	v_mfma_f32_16x16x32_bf16 v[76:79], v[128:131], v[200:203], v[76:79]
	v_mfma_f32_16x16x32_bf16 v[72:75], v[152:155], v[200:203], v[72:75]
	v_mfma_f32_16x16x32_bf16 v[68:71], v[128:131], v[208:211], v[68:71]
	v_mfma_f32_16x16x32_bf16 v[64:67], v[152:155], v[208:211], v[64:67]
	v_mfma_f32_16x16x32_bf16 v[92:95], v[132:135], v[188:191], v[92:95]
	v_mfma_f32_16x16x32_bf16 v[88:91], v[156:159], v[188:191], v[88:91]
	v_mfma_f32_16x16x32_bf16 v[84:87], v[132:135], v[196:199], v[84:87]
	v_mfma_f32_16x16x32_bf16 v[80:83], v[156:159], v[196:199], v[80:83]
	v_mfma_f32_16x16x32_bf16 v[76:79], v[132:135], v[204:207], v[76:79]
	v_mfma_f32_16x16x32_bf16 v[72:75], v[156:159], v[204:207], v[72:75]
	v_mfma_f32_16x16x32_bf16 v[68:71], v[132:135], v[212:215], v[68:71]
	v_mfma_f32_16x16x32_bf16 v[64:67], v[156:159], v[212:215], v[64:67]
	v_mfma_f32_16x16x32_bf16 v[28:31], v[160:163], v[184:187], v[28:31]
	v_mfma_f32_16x16x32_bf16 v[24:27], v[176:179], v[184:187], v[24:27]
	v_mfma_f32_16x16x32_bf16 v[20:23], v[160:163], v[192:195], v[20:23]
	v_mfma_f32_16x16x32_bf16 v[16:19], v[176:179], v[192:195], v[16:19]
	v_mfma_f32_16x16x32_bf16 v[12:15], v[160:163], v[200:203], v[12:15]
	v_mfma_f32_16x16x32_bf16 v[8:11], v[176:179], v[200:203], v[8:11]
	v_mfma_f32_16x16x32_bf16 v[4:7], v[160:163], v[208:211], v[4:7]
	v_mfma_f32_16x16x32_bf16 v[0:3], v[176:179], v[208:211], v[0:3]
	v_mfma_f32_16x16x32_bf16 v[28:31], v[172:175], v[188:191], v[28:31]
	v_mfma_f32_16x16x32_bf16 v[24:27], v[180:183], v[188:191], v[24:27]
	v_mfma_f32_16x16x32_bf16 v[20:23], v[172:175], v[196:199], v[20:23]
	v_mfma_f32_16x16x32_bf16 v[16:19], v[180:183], v[196:199], v[16:19]
	v_mfma_f32_16x16x32_bf16 v[12:15], v[172:175], v[204:207], v[12:15]
	v_mfma_f32_16x16x32_bf16 v[8:11], v[180:183], v[204:207], v[8:11]
	v_mfma_f32_16x16x32_bf16 v[4:7], v[172:175], v[212:215], v[4:7]
	v_mfma_f32_16x16x32_bf16 v[0:3], v[180:183], v[212:215], v[0:3]
	s_barrier
	s_add_i32 s59, 0, 0x18000
	s_add_i32 s60, 0, 0x1c000
	v_add_u32_e32 v156, s59, v165
	v_add_u32_e32 v171, s60, v165
	ds_read_b128 v[128:131], v156
	ds_read_b128 v[132:135], v156 offset:1024
	ds_read_b128 v[152:155], v156 offset:2048
	ds_read_b128 v[156:159], v156 offset:3072
	ds_read_b128 v[160:163], v171
	ds_read_b128 v[172:175], v171 offset:1024
	ds_read_b128 v[176:179], v171 offset:2048
	ds_read_b128 v[180:183], v171 offset:3072
	s_add_u32 s36, s36, 0x40000
	s_addc_u32 s37, s37, 0
	s_mov_b32 m0, s42
	v_lshl_add_u64 v[224:225], s[36:37], 0, v[136:137]
	ds_read_b128 v[184:187], v170 offset:32768
	ds_read_b128 v[188:191], v170 offset:33792
	ds_read_b128 v[192:195], v170 offset:34816
	ds_read_b128 v[196:199], v170 offset:35840
	ds_read_b128 v[200:203], v170 offset:36864
	ds_read_b128 v[204:207], v170 offset:37888
	ds_read_b128 v[208:211], v170 offset:38912
	ds_read_b128 v[212:215], v170 offset:39936
	global_load_lds_dwordx4 v[224:225], off
	v_lshl_add_u64 v[224:225], s[36:37], 0, v[140:141]
	s_mov_b32 m0, s43
	s_nop 0
	global_load_lds_dwordx4 v[224:225], off
	s_waitcnt vmcnt(8)
	s_waitcnt lgkmcnt(0)
	s_barrier
	s_waitcnt lgkmcnt(0)
	v_mfma_f32_16x16x32_bf16 v[124:127], v[128:131], v[184:187], v[124:127]
	v_mfma_f32_16x16x32_bf16 v[120:123], v[152:155], v[184:187], v[120:123]
	v_mfma_f32_16x16x32_bf16 v[116:119], v[128:131], v[192:195], v[116:119]
	v_mfma_f32_16x16x32_bf16 v[112:115], v[152:155], v[192:195], v[112:115]
	v_mfma_f32_16x16x32_bf16 v[108:111], v[128:131], v[200:203], v[108:111]
	v_mfma_f32_16x16x32_bf16 v[104:107], v[152:155], v[200:203], v[104:107]
	v_mfma_f32_16x16x32_bf16 v[100:103], v[128:131], v[208:211], v[100:103]
	v_mfma_f32_16x16x32_bf16 v[96:99], v[152:155], v[208:211], v[96:99]
	v_mfma_f32_16x16x32_bf16 v[124:127], v[132:135], v[188:191], v[124:127]
	v_mfma_f32_16x16x32_bf16 v[120:123], v[156:159], v[188:191], v[120:123]
	v_mfma_f32_16x16x32_bf16 v[116:119], v[132:135], v[196:199], v[116:119]
	v_mfma_f32_16x16x32_bf16 v[112:115], v[156:159], v[196:199], v[112:115]
	v_mfma_f32_16x16x32_bf16 v[108:111], v[132:135], v[204:207], v[108:111]
	v_mfma_f32_16x16x32_bf16 v[104:107], v[156:159], v[204:207], v[104:107]
	v_mfma_f32_16x16x32_bf16 v[100:103], v[132:135], v[212:215], v[100:103]
	v_mfma_f32_16x16x32_bf16 v[96:99], v[156:159], v[212:215], v[96:99]
	v_mfma_f32_16x16x32_bf16 v[60:63], v[160:163], v[184:187], v[60:63]
	v_mfma_f32_16x16x32_bf16 v[56:59], v[176:179], v[184:187], v[56:59]
	v_mfma_f32_16x16x32_bf16 v[52:55], v[160:163], v[192:195], v[52:55]
	v_mfma_f32_16x16x32_bf16 v[48:51], v[176:179], v[192:195], v[48:51]
	v_mfma_f32_16x16x32_bf16 v[44:47], v[160:163], v[200:203], v[44:47]
	v_mfma_f32_16x16x32_bf16 v[40:43], v[176:179], v[200:203], v[40:43]
	v_mfma_f32_16x16x32_bf16 v[36:39], v[160:163], v[208:211], v[36:39]
	v_mfma_f32_16x16x32_bf16 v[32:35], v[176:179], v[208:211], v[32:35]
	v_mfma_f32_16x16x32_bf16 v[60:63], v[172:175], v[188:191], v[60:63]
	v_mfma_f32_16x16x32_bf16 v[56:59], v[180:183], v[188:191], v[56:59]
	v_mfma_f32_16x16x32_bf16 v[52:55], v[172:175], v[196:199], v[52:55]
	v_mfma_f32_16x16x32_bf16 v[48:51], v[180:183], v[196:199], v[48:51]
	v_mfma_f32_16x16x32_bf16 v[44:47], v[172:175], v[204:207], v[44:47]
	v_mfma_f32_16x16x32_bf16 v[40:43], v[180:183], v[204:207], v[40:43]
	v_mfma_f32_16x16x32_bf16 v[36:39], v[172:175], v[212:215], v[36:39]
	v_mfma_f32_16x16x32_bf16 v[32:35], v[180:183], v[212:215], v[32:35]
	s_barrier
; #define PG8_STAGE(bufoff, gbase, voff) do { _Pragma("unroll") for (int _i = 0; _i < 2; ++_i) \
;         __builtin_amdgcn_global_load_lds((const unsigned*)((const char*)(gbase) + (voff)[_i]), (PG8_LAS unsigned*)(lds + (bufoff) + ldsw + _i * 8192), 16, 0, 0); } while (0)
; #define PG8_LDA(dst, b, h) do { _Pragma("unroll") for (int m = 0; m < 4; ++m) _Pragma("unroll") for (int k = 0; k < 2; ++k) dst[m][k] = *(const PG8_LAS bf16x8*)(lds + PG8_SA(b, h) + aoff + m * 2048 + k * 1024); } while (0)
; #define PG8_MMA(ai, bj, At, Bt) do { __builtin_amdgcn_s_setprio(1); _Pragma("unroll") for (int m = 0; m < 4; ++m) _Pragma("unroll") for (int n = 0; n < 2; ++n) _Pragma("unroll") for (int k = 0; k < 2; ++k) \
;         acc[ai][bj][m][n] = __builtin_amdgcn_mfma_f32_16x16x32_bf16(Bt[n][k], At[m][k], acc[ai][bj][m][n], 0, 0, 0); __builtin_amdgcn_s_setprio(0); } while (0)
; #define PG8_WAIT_V(n) asm volatile("s_waitcnt vmcnt(" #n ")" ::: "memory")
; #define PG8_WAIT_L(n) asm volatile("s_waitcnt lgkmcnt(" #n ")" ::: "memory")
; #define PG8_BAR __builtin_amdgcn_s_barrier()
; #define PG8_SCHED __builtin_amdgcn_sched_barrier(0)
; template <class Epi, class Sched, bool ALIGN_EPI = false, bool SP2 = false>
; __device__ __forceinline__ void gemm_phase(PG8_LAS unsigned char* lds, const Gemm g, const Sched& S, const Epi& E, const int wid) {
;     ...
;         for (int t = 0; t < nt; t += 2) {
;     ...
;             PG8_LDA(At, 1, 1); PG8_STAGE(PG8_SB(1, 0), b3, voffB); PG8_STAGE(PG8_SB(1, 1), b3 + hstep, voffB); PG8_STAGE(PG8_SA(1, 0), a3, voffA);
;             PG8_WAIT_V(8); PG8_WAIT_L(0); PG8_BAR; PG8_MMA(1, 0, At, B0); PG8_MMA(1, 1, At, B1); PG8_BAR; PG8_SCHED;
	s_add_i32 s36, s59, s33
	v_lshl_add_u64 v[216:217], v[216:217], 0, s[8:9]
	s_mov_b32 m0, s36
	ds_read_b128 v[184:187], v170 offset:49152
	ds_read_b128 v[188:191], v170 offset:50176
	ds_read_b128 v[192:195], v170 offset:51200
	ds_read_b128 v[196:199], v170 offset:52224
	ds_read_b128 v[200:203], v170 offset:53248
	ds_read_b128 v[204:207], v170 offset:54272
	ds_read_b128 v[208:211], v170 offset:55296
	ds_read_b128 v[212:215], v170 offset:56320
	global_load_lds_dwordx4 v[216:217], off
	s_add_i32 m0, s36, 0x2000
	s_add_u32 s34, s34, 0x40080
	v_lshl_add_u64 v[216:217], v[218:219], 0, s[8:9]
	s_addc_u32 s35, s35, 0
	s_add_i32 s36, s60, s33
	global_load_lds_dwordx4 v[216:217], off
	v_lshl_add_u64 v[216:217], s[34:35], 0, v[138:139]
	s_mov_b32 m0, s36
	s_nop 0
	global_load_lds_dwordx4 v[216:217], off
	v_lshl_add_u64 v[216:217], s[34:35], 0, v[142:143]
	s_add_i32 m0, s36, 0x2000
	s_nop 0
	global_load_lds_dwordx4 v[216:217], off
	v_lshl_add_u64 v[216:217], v[220:221], 0, s[8:9]
	s_mov_b32 m0, s47
	s_nop 0
	global_load_lds_dwordx4 v[216:217], off
	v_lshl_add_u64 v[216:217], v[222:223], 0, s[8:9]
	s_mov_b32 m0, s48
	s_nop 0
	global_load_lds_dwordx4 v[216:217], off
	s_waitcnt vmcnt(8)
	s_waitcnt lgkmcnt(0)
	s_barrier
	s_waitcnt lgkmcnt(0)
	v_mfma_f32_16x16x32_bf16 v[92:95], v[128:131], v[184:187], v[92:95]
	v_mfma_f32_16x16x32_bf16 v[88:91], v[152:155], v[184:187], v[88:91]
	v_mfma_f32_16x16x32_bf16 v[84:87], v[128:131], v[192:195], v[84:87]
	v_mfma_f32_16x16x32_bf16 v[80:83], v[152:155], v[192:195], v[80:83]
	v_mfma_f32_16x16x32_bf16 v[76:79], v[128:131], v[200:203], v[76:79]
	v_mfma_f32_16x16x32_bf16 v[72:75], v[152:155], v[200:203], v[72:75]
	v_mfma_f32_16x16x32_bf16 v[68:71], v[128:131], v[208:211], v[68:71]
	v_mfma_f32_16x16x32_bf16 v[64:67], v[152:155], v[208:211], v[64:67]
	v_mfma_f32_16x16x32_bf16 v[92:95], v[132:135], v[188:191], v[92:95]
	v_mfma_f32_16x16x32_bf16 v[88:91], v[156:159], v[188:191], v[88:91]
	v_mfma_f32_16x16x32_bf16 v[84:87], v[132:135], v[196:199], v[84:87]
	v_mfma_f32_16x16x32_bf16 v[80:83], v[156:159], v[196:199], v[80:83]
	v_mfma_f32_16x16x32_bf16 v[76:79], v[132:135], v[204:207], v[76:79]
	v_mfma_f32_16x16x32_bf16 v[72:75], v[156:159], v[204:207], v[72:75]
	v_mfma_f32_16x16x32_bf16 v[68:71], v[132:135], v[212:215], v[68:71]
	v_mfma_f32_16x16x32_bf16 v[64:67], v[156:159], v[212:215], v[64:67]
	v_mfma_f32_16x16x32_bf16 v[28:31], v[160:163], v[184:187], v[28:31]
	v_mfma_f32_16x16x32_bf16 v[24:27], v[176:179], v[184:187], v[24:27]
	v_mfma_f32_16x16x32_bf16 v[20:23], v[160:163], v[192:195], v[20:23]
	v_mfma_f32_16x16x32_bf16 v[16:19], v[176:179], v[192:195], v[16:19]
	v_mfma_f32_16x16x32_bf16 v[12:15], v[160:163], v[200:203], v[12:15]
	v_mfma_f32_16x16x32_bf16 v[8:11], v[176:179], v[200:203], v[8:11]
	v_mfma_f32_16x16x32_bf16 v[4:7], v[160:163], v[208:211], v[4:7]
	v_mfma_f32_16x16x32_bf16 v[0:3], v[176:179], v[208:211], v[0:3]
	v_mfma_f32_16x16x32_bf16 v[28:31], v[172:175], v[188:191], v[28:31]
	v_mfma_f32_16x16x32_bf16 v[24:27], v[180:183], v[188:191], v[24:27]
	v_mfma_f32_16x16x32_bf16 v[20:23], v[172:175], v[196:199], v[20:23]
	v_mfma_f32_16x16x32_bf16 v[16:19], v[180:183], v[196:199], v[16:19]
	v_mfma_f32_16x16x32_bf16 v[12:15], v[172:175], v[204:207], v[12:15]
	v_mfma_f32_16x16x32_bf16 v[8:11], v[180:183], v[204:207], v[8:11]
	v_mfma_f32_16x16x32_bf16 v[4:7], v[172:175], v[212:215], v[4:7]
	v_mfma_f32_16x16x32_bf16 v[0:3], v[180:183], v[212:215], v[0:3]
	s_barrier
	s_add_i32 s58, s58, 2
	s_add_u32 s30, s30, 0x100
	s_addc_u32 s31, s31, 0
	s_add_u32 s56, s56, 0x100
	s_addc_u32 s57, s57, 0
	s_cmp_gt_u32 s58, 13
	s_cbranch_scc0 .LBB0_1170
	s_and_b64 vcc, exec, s[10:11]
	s_cbranch_vccz .LBB0_1173
	s_barrier

; #define PG8_WAIT_V(n) asm volatile("s_waitcnt vmcnt(" #n ")" ::: "memory")
; #define PG8_BAR __builtin_amdgcn_s_barrier()
;     __host__ __device__ bool next(int i, Unit& u) const {
;         const long L = (long)i * G + c; if (L >= nwg) return false;
;         int wgid = (int)L; { const int q = nwg / NXCD, r = nwg % NXCD, xcd = wgid % NXCD, off = wgid / NXCD; wgid = (xcd < r ? xcd * (q + 1) : r * (q + 1) + (xcd - r) * q) + off; }
;         const int nig = WGM * nN, gid = wgid / nig, fm = gid * WGM, gsz = (nM - fm) < WGM ? (nM - fm) : WGM;
;         u.pm = fm + ((wgid % nig) % gsz); u.pn = (wgid % nig) / gsz; return true;
; template <class Epi, class Sched, bool ALIGN_EPI = false, bool SP2 = false>
; __device__ __forceinline__ void gemm_phase(PG8_LAS unsigned char* lds, const Gemm g, const Sched& S, const Epi& E, const int wid) {
;     const int lane = lane_now(), tid = wid * 64 + lane, wr = wid >> 2, wc = wid & 3, fr = lane & 15, fq = lane >> 4;
;     const int K = g.K, nt = K / BK;
;     unsigned voffA[2], voffB[2];
; #pragma unroll
;     for (int i = 0; i < 2; ++i) { int R, C; stage_rc(tid * 16 + i * 8192, R, C); const int Rb = Epi::PERM ? ((R & ~31) + perm32(R & 31)) : R;
;         voffA[i] = (unsigned)(R * K + C) * 2u; voffB[i] = (unsigned)(Rb * K + C) * 2u; }
;     const size_t kstep = (size_t)(BK * 2);
;     const size_t hstep = (size_t)HALF * K * 2;
;     const size_t tstep = 2 * hstep;
;     const unsigned ldsw = (unsigned)wid * 1024u;
;     const int aoff = lds_byte(wr * 64 + fr, fq * 8), boff = lds_byte(wc * 32 + fr, fq * 8);
;     ...
;     Unit cur, nxt; int ui = 0;
;     if (!S.next(0, cur)) return;
;     f32x4 acc[2][2][4][2];
; #pragma unroll
;     for (int a = 0; a < 2; ++a)
; #pragma unroll
;         for (int b = 0; b < 2; ++b)
; #pragma unroll
;             for (int m = 0; m < 4; ++m)
; #pragma unroll
;                 for (int n = 0; n < 2; ++n) acc[a][b][m][n] = (f32x4){0.f, 0.f, 0.f, 0.f};
;     bf16x8 At[4][2], B0[2][2], B1[2][2];
;     const char* cA = (const char*)g.A + (size_t)cur.pm * tstep; const char* cB = (const char*)g.Bt + (size_t)cur.pn * tstep;
;     S.a_ready(cur);
;     if constexpr (SP2) {
;         PG8_STAGE(PG8_SB(0, 0), cB, voffB); PG8_STAGE(PG8_SB(0, 1), cB + hstep, voffB); PG8_STAGE(PG8_SA(0, 0), cA, voffA); PG8_STAGE(PG8_SA(0, 1), cA + hstep, voffA);
;         if (wr == 1) PG8_BAR;
;         PG8_WAIT_V(2); PG8_BAR;
.LBB0_1302:
	v_readlane_b32 s0, v244, 23
	v_readlane_b32 s1, v244, 24
	s_andn2_b64 vcc, exec, s[0:1]
	s_waitcnt lgkmcnt(0)
	s_barrier
	v_mbcnt_lo_u32_b32 v10, -1, 0
	v_mbcnt_hi_u32_b32 v10, -1, v10
	s_cbranch_vccnz .LBB0_1318
	v_lshl_add_u32 v0, v10, 4, s33
	v_add_u32_e32 v1, 0x2000, v0
	v_ashrrev_i32_e32 v2, 31, v1
	v_lshrrev_b32_e32 v2, 22, v2
	v_add_u32_e32 v2, v1, v2
	v_ashrrev_i32_e32 v8, 10, v2
	v_mul_i32_i24_e32 v2, 0x400, v8
	v_sub_u32_e32 v1, v1, v2
	v_lshrrev_b32_e32 v2, 4, v1
	v_bitop3_b32 v1, v2, v1, 32 bitop3:0x6c
	v_ashrrev_i32_e32 v2, 31, v1
	v_lshrrev_b32_e32 v2, 26, v2
	v_add_u32_e32 v2, v1, v2
	v_ashrrev_i32_e32 v9, 6, v2
	v_lshlrev_b32_e32 v3, 3, v8
	v_and_b32_e32 v2, 0xffc0, v2
	v_and_b32_e32 v3, -16, v3
	v_sub_u32_e32 v1, v1, v2
	v_add_u32_e32 v3, v9, v3
	v_lshrrev_b16_e32 v2, 7, v1
	v_and_b32_e32 v4, 3, v9
	s_mov_b32 s0, 0x1fffe0
	v_lshrrev_b32_e32 v5, 2, v3
	v_lshlrev_b32_e32 v6, 1, v3
	v_and_b32_e32 v2, 1, v2
	v_and_or_b32 v4, v3, s0, v4
	v_and_b32_e32 v5, 4, v5
	v_and_b32_e32 v6, 24, v6
	v_add_u16_e32 v1, v1, v2
	v_mov_b32_e32 v2, 1
	v_or3_b32 v4, v4, v5, v6
	v_lshlrev_b32_e32 v5, 5, v8
	v_ashrrev_i16_sdwa v1, v2, sext(v1) dst_sel:DWORD dst_unused:UNUSED_PAD src0_sel:DWORD src1_sel:BYTE_0
	v_and_b32_e32 v5, 32, v5
	v_bfe_i32 v11, v1, 0, 16
	v_add_lshl_u32 v1, v5, v11, 1
	v_lshl_add_u32 v128, v4, 11, v1
	v_lshl_add_u32 v130, v3, 11, v1
	v_ashrrev_i32_e32 v1, 31, v0
	v_lshrrev_b32_e32 v1, 22, v1
	v_add_u32_e32 v1, v0, v1
	v_ashrrev_i32_e32 v12, 10, v1
	v_mul_i32_i24_e32 v1, 0x400, v12
	v_sub_u32_e32 v0, v0, v1
	v_lshrrev_b32_e32 v1, 4, v0
	v_bitop3_b32 v0, v1, v0, 32 bitop3:0x6c
	v_ashrrev_i32_e32 v1, 31, v0
	v_lshrrev_b32_e32 v1, 26, v1
	v_add_u32_e32 v1, v0, v1
	v_lshlrev_b32_e32 v3, 3, v12
	s_add_u32 s28, s92, 0x1180000
	v_ashrrev_i32_e32 v13, 6, v1
	v_and_b32_e32 v3, -16, v3
	s_addc_u32 s29, s93, 0
	v_add_u32_e32 v3, v13, v3
	v_and_b32_e32 v4, 3, v13
	s_ashr_i32 s30, s68, 31
	v_and_or_b32 v4, v3, s0, v4
	s_lshr_b32 s0, s30, 29
	s_add_i32 s0, s68, s0
	s_ashr_i32 s1, s0, 3
	s_and_b32 s0, s0, -8
	s_sub_i32 s0, s68, s0
	s_cmp_lt_i32 s0, 0
	s_movk_i32 s31, 0x161
	s_cselect_b32 s6, s31, 0x160
	s_mul_i32 s0, s0, s6
	s_add_i32 s0, s0, s1
	s_mul_hi_i32 s1, s0, 0x2e8ba2e9
	s_lshr_b32 s6, s1, 31
	s_ashr_i32 s1, s1, 4
	s_add_i32 s1, s1, s6
	s_lshl_b32 s7, s1, 2
	s_mulk_i32 s1, 0x58
	s_sub_i32 s0, s0, s1
	s_bfe_i32 s1, s0, 0x80000
	s_bfe_u32 s1, s1, 0x2000d
	s_add_i32 s1, s0, s1
	s_bfe_i32 s6, s1, 0x80000
	s_and_b32 s1, s1, 0xfc
	s_sub_i32 s0, s0, s1
	s_sext_i32_i16 s6, s6
	s_sext_i32_i8 s0, s0
	v_lshrrev_b32_e32 v5, 2, v3
	v_lshlrev_b32_e32 v6, 1, v3
	v_and_b32_e32 v1, 0xc0, v1
	s_lshr_b32 s6, s6, 2
	s_add_i32 s20, s7, s0
	v_and_b32_e32 v5, 4, v5
	v_and_b32_e32 v6, 24, v6
	v_sub_u32_e32 v0, v0, v1
	s_ashr_i32 s21, s20, 31
	s_bfe_i64 s[8:9], s[6:7], 0x100000
	v_or3_b32 v4, v4, v5, v6
	v_lshlrev_b32_e32 v5, 5, v12
	v_ashrrev_i16_sdwa v0, v2, sext(v0) dst_sel:DWORD dst_unused:UNUSED_PAD src0_sel:DWORD src1_sel:BYTE_0
	s_lshl_b64 s[0:1], s[20:21], 19
	s_lshl_b64 s[8:9], s[8:9], 19
	v_and_b32_e32 v5, 32, v5
	v_bfe_i32 v14, v0, 0, 16
	s_add_u32 s24, s28, s8
	v_add_lshl_u32 v0, v5, v14, 1
	s_addc_u32 s25, s29, s9
	s_add_i32 s21, s33, 0
	v_lshl_add_u32 v132, v4, 11, v0
	s_add_i32 m0, s21, 0x10000
	v_lshl_add_u32 v134, v3, 11, v0
	global_load_lds_dwordx4 v132, s[24:25]
	s_add_i32 m0, s21, 0x12000
	s_add_u32 s8, s24, 0x40000
	global_load_lds_dwordx4 v128, s[24:25]
	s_addc_u32 s9, s25, 0
	s_add_i32 m0, s21, 0x14000
	v_mov_b32_e32 v133, 0
	global_load_lds_dwordx4 v132, s[8:9]
	s_add_i32 m0, s21, 0x16000
	s_add_u32 s22, s2, s0
	s_addc_u32 s23, s3, s1
	s_add_i32 s34, s21, 0x2000
	global_load_lds_dwordx4 v128, s[8:9]
	s_mov_b32 m0, s21
	s_add_u32 s0, s22, 0x40000
	global_load_lds_dwordx4 v134, s[22:23]
	s_mov_b32 m0, s34
	s_addc_u32 s1, s23, 0
	s_add_i32 s35, s21, 0x4000
	global_load_lds_dwordx4 v130, s[22:23]
	s_mov_b32 m0, s35
	s_add_i32 s36, s21, 0x6000
	global_load_lds_dwordx4 v134, s[0:1]
	s_mov_b32 m0, s36
	v_readlane_b32 s7, v244, 18
	global_load_lds_dwordx4 v130, s[0:1]
	v_mov_b32_e32 v129, v133
	v_mov_b32_e32 v135, v133
	v_mov_b32_e32 v131, v133
	s_cmp_eq_u32 s7, 1
	s_mov_b32 s37, 0
	v_lshl_add_u64 v[4:5], s[24:25], 0, v[132:133]
	v_lshl_add_u64 v[2:3], s[24:25], 0, v[128:129]
	v_lshl_add_u64 v[0:1], s[22:23], 0, v[134:135]
	s_cselect_b64 s[0:1], -1, 0
	s_cmp_lg_u32 s7, 1
	v_lshl_add_u64 v[6:7], s[22:23], 0, v[130:131]
	s_cbranch_scc1 .LBB0_1305
	s_barrier
	s_setprio 1

; #define PG8_STAGE(bufoff, gbase, voff) do { _Pragma("unroll") for (int _i = 0; _i < 2; ++_i) \
;         __builtin_amdgcn_global_load_lds((const unsigned*)((const char*)(gbase) + (voff)[_i]), (PG8_LAS unsigned*)(lds + (bufoff) + ldsw + _i * 8192), 16, 0, 0); } while (0)
; #define PG8_LDA(dst, b, h) do { _Pragma("unroll") for (int m = 0; m < 4; ++m) _Pragma("unroll") for (int k = 0; k < 2; ++k) dst[m][k] = *(const PG8_LAS bf16x8*)(lds + PG8_SA(b, h) + aoff + m * 2048 + k * 1024); } while (0)
; #define PG8_LDB(dst, b, h) do { _Pragma("unroll") for (int n = 0; n < 2; ++n) _Pragma("unroll") for (int k = 0; k < 2; ++k) dst[n][k] = *(const PG8_LAS bf16x8*)(lds + PG8_SB(b, h) + boff + n * 2048 + k * 1024); } while (0)
; #define PG8_MMA(ai, bj, At, Bt) do { __builtin_amdgcn_s_setprio(1); _Pragma("unroll") for (int m = 0; m < 4; ++m) _Pragma("unroll") for (int n = 0; n < 2; ++n) _Pragma("unroll") for (int k = 0; k < 2; ++k) \
;         acc[ai][bj][m][n] = __builtin_amdgcn_mfma_f32_16x16x32_bf16(Bt[n][k], At[m][k], acc[ai][bj][m][n], 0, 0, 0); __builtin_amdgcn_s_setprio(0); } while (0)
; #define PG8_WAIT_V(n) asm volatile("s_waitcnt vmcnt(" #n ")" ::: "memory")
; #define PG8_WAIT_L(n) asm volatile("s_waitcnt lgkmcnt(" #n ")" ::: "memory")
; #define PG8_BAR __builtin_amdgcn_s_barrier()
; #define PG8_SCHED __builtin_amdgcn_sched_barrier(0)
; template <class Epi, class Sched, bool ALIGN_EPI = false, bool SP2 = false>
; __device__ __forceinline__ void gemm_phase(PG8_LAS unsigned char* lds, const Gemm g, const Sched& S, const Epi& E, const int wid) {
;     ...
;             PG8_LDB(B0, 0, 0); PG8_LDB(B1, 0, 1); PG8_SCHED; PG8_LDA(At, 0, 0); PG8_STAGE(PG8_SA(1, 1), a1 + hstep, voffA);
;             PG8_WAIT_V(8); PG8_WAIT_L(0); PG8_BAR; PG8_MMA(0, 0, At, B0); PG8_MMA(0, 1, At, B1); PG8_BAR; PG8_SCHED;
;             PG8_LDA(At, 0, 1); PG8_STAGE(PG8_SB(0, 0), b2, voffB); PG8_STAGE(PG8_SB(0, 1), b2 + hstep, voffB); PG8_STAGE(PG8_SA(0, 0), a2, voffA);
;             PG8_WAIT_V(8); PG8_WAIT_L(0); PG8_BAR; PG8_MMA(1, 0, At, B0); PG8_MMA(1, 1, At, B1); PG8_BAR; PG8_SCHED;
.LBB0_1311:
	ds_read_b128 v[144:147], v151
	ds_read_b128 v[154:157], v151 offset:1024
	ds_read_b128 v[158:161], v151 offset:2048
	ds_read_b128 v[162:165], v151 offset:3072
	ds_read_b128 v[166:169], v152
	ds_read_b128 v[170:173], v152 offset:1024
	ds_read_b128 v[174:177], v152 offset:2048
	ds_read_b128 v[178:181], v152 offset:3072
	s_add_u32 s24, s22, 0xfffc0080
	s_addc_u32 s25, s23, -1
	s_cmp_eq_u32 s50, 12
	s_cselect_b32 s27, s15, s25
	s_cselect_b32 s26, s46, s24
	s_cselect_b32 s25, s13, s49
	s_cselect_b32 s24, s47, s48
	v_lshl_add_u64 v[214:215], s[22:23], 0, v[136:137]
	s_add_i32 m0, s21, 0xc000
	ds_read_b128 v[182:185], v153
	ds_read_b128 v[186:189], v153 offset:1024
	ds_read_b128 v[190:193], v153 offset:2048
	ds_read_b128 v[194:197], v153 offset:3072
	ds_read_b128 v[198:201], v153 offset:4096
	ds_read_b128 v[202:205], v153 offset:5120
	ds_read_b128 v[206:209], v153 offset:6144
	ds_read_b128 v[210:213], v153 offset:7168
	global_load_lds_dwordx4 v[214:215], off
	v_lshl_add_u64 v[214:215], s[22:23], 0, v[138:139]
	s_add_i32 m0, s21, 0xe000
	s_nop 0
	global_load_lds_dwordx4 v[214:215], off
	s_waitcnt vmcnt(8)
	s_waitcnt lgkmcnt(0)
	s_barrier
	s_waitcnt lgkmcnt(0)
	v_mfma_f32_16x16x32_bf16 v[124:127], v[144:147], v[182:185], v[124:127]
	v_mfma_f32_16x16x32_bf16 v[116:119], v[158:161], v[182:185], v[116:119]
	v_mfma_f32_16x16x32_bf16 v[108:111], v[144:147], v[190:193], v[108:111]
	v_mfma_f32_16x16x32_bf16 v[100:103], v[158:161], v[190:193], v[100:103]
	v_mfma_f32_16x16x32_bf16 v[92:95], v[144:147], v[198:201], v[92:95]
	v_mfma_f32_16x16x32_bf16 v[84:87], v[158:161], v[198:201], v[84:87]
	v_mfma_f32_16x16x32_bf16 v[76:79], v[144:147], v[206:209], v[76:79]
	v_mfma_f32_16x16x32_bf16 v[68:71], v[158:161], v[206:209], v[68:71]
	v_mfma_f32_16x16x32_bf16 v[124:127], v[154:157], v[186:189], v[124:127]
	v_mfma_f32_16x16x32_bf16 v[116:119], v[162:165], v[186:189], v[116:119]
	v_mfma_f32_16x16x32_bf16 v[108:111], v[154:157], v[194:197], v[108:111]
	v_mfma_f32_16x16x32_bf16 v[100:103], v[162:165], v[194:197], v[100:103]
	v_mfma_f32_16x16x32_bf16 v[92:95], v[154:157], v[202:205], v[92:95]
	v_mfma_f32_16x16x32_bf16 v[84:87], v[162:165], v[202:205], v[84:87]
	v_mfma_f32_16x16x32_bf16 v[76:79], v[154:157], v[210:213], v[76:79]
	v_mfma_f32_16x16x32_bf16 v[68:71], v[162:165], v[210:213], v[68:71]
	v_mfma_f32_16x16x32_bf16 v[120:123], v[166:169], v[182:185], v[120:123]
	v_mfma_f32_16x16x32_bf16 v[112:115], v[174:177], v[182:185], v[112:115]
	v_mfma_f32_16x16x32_bf16 v[104:107], v[166:169], v[190:193], v[104:107]
	v_mfma_f32_16x16x32_bf16 v[96:99], v[174:177], v[190:193], v[96:99]
	v_mfma_f32_16x16x32_bf16 v[88:91], v[166:169], v[198:201], v[88:91]
	v_mfma_f32_16x16x32_bf16 v[80:83], v[174:177], v[198:201], v[80:83]
	v_mfma_f32_16x16x32_bf16 v[72:75], v[166:169], v[206:209], v[72:75]
	v_mfma_f32_16x16x32_bf16 v[64:67], v[174:177], v[206:209], v[64:67]
	v_mfma_f32_16x16x32_bf16 v[120:123], v[170:173], v[186:189], v[120:123]
	v_mfma_f32_16x16x32_bf16 v[112:115], v[178:181], v[186:189], v[112:115]
	v_mfma_f32_16x16x32_bf16 v[104:107], v[170:173], v[194:197], v[104:107]
	v_mfma_f32_16x16x32_bf16 v[96:99], v[178:181], v[194:197], v[96:99]
	v_mfma_f32_16x16x32_bf16 v[88:91], v[170:173], v[202:205], v[88:91]
	v_mfma_f32_16x16x32_bf16 v[80:83], v[178:181], v[202:205], v[80:83]
	v_mfma_f32_16x16x32_bf16 v[72:75], v[170:173], v[210:213], v[72:75]
	v_mfma_f32_16x16x32_bf16 v[64:67], v[178:181], v[210:213], v[64:67]
	s_barrier
	s_add_i32 s51, s42, s33
	v_lshl_add_u64 v[214:215], s[24:25], 0, v[132:133]
	s_mov_b32 m0, s51
	ds_read_b128 v[182:185], v153 offset:16384
	ds_read_b128 v[186:189], v153 offset:17408
	ds_read_b128 v[190:193], v153 offset:18432
	ds_read_b128 v[194:197], v153 offset:19456
	ds_read_b128 v[198:201], v153 offset:20480
	ds_read_b128 v[202:205], v153 offset:21504
	ds_read_b128 v[206:209], v153 offset:22528
	ds_read_b128 v[210:213], v153 offset:23552
	global_load_lds_dwordx4 v[214:215], off
	s_add_i32 m0, s51, 0x2000
	s_add_u32 s52, s24, 0x40000
	v_lshl_add_u64 v[216:217], s[24:25], 0, v[128:129]
	s_addc_u32 s53, s25, 0
	s_add_i32 s51, s43, s33
	global_load_lds_dwordx4 v[216:217], off
	v_lshl_add_u64 v[218:219], s[52:53], 0, v[132:133]
	s_mov_b32 m0, s51
	v_lshl_add_u64 v[220:221], s[26:27], 0, v[130:131]
	global_load_lds_dwordx4 v[218:219], off
	v_lshl_add_u64 v[218:219], s[52:53], 0, v[128:129]
	s_add_i32 m0, s51, 0x2000
	s_nop 0
	global_load_lds_dwordx4 v[218:219], off
	v_lshl_add_u64 v[218:219], s[26:27], 0, v[134:135]
	s_mov_b32 m0, s21
	s_nop 0
	global_load_lds_dwordx4 v[218:219], off
	s_mov_b32 m0, s34
	s_nop 0
	global_load_lds_dwordx4 v[220:221], off
	s_waitcnt vmcnt(8)
	s_waitcnt lgkmcnt(0)
	s_barrier
; #define PG8_STAGE(bufoff, gbase, voff) do { _Pragma("unroll") for (int _i = 0; _i < 2; ++_i) \
;         __builtin_amdgcn_global_load_lds((const unsigned*)((const char*)(gbase) + (voff)[_i]), (PG8_LAS unsigned*)(lds + (bufoff) + ldsw + _i * 8192), 16, 0, 0); } while (0)
; #define PG8_LDA(dst, b, h) do { _Pragma("unroll") for (int m = 0; m < 4; ++m) _Pragma("unroll") for (int k = 0; k < 2; ++k) dst[m][k] = *(const PG8_LAS bf16x8*)(lds + PG8_SA(b, h) + aoff + m * 2048 + k * 1024); } while (0)
; #define PG8_LDB(dst, b, h) do { _Pragma("unroll") for (int n = 0; n < 2; ++n) _Pragma("unroll") for (int k = 0; k < 2; ++k) dst[n][k] = *(const PG8_LAS bf16x8*)(lds + PG8_SB(b, h) + boff + n * 2048 + k * 1024); } while (0)
; #define PG8_MMA(ai, bj, At, Bt) do { __builtin_amdgcn_s_setprio(1); _Pragma("unroll") for (int m = 0; m < 4; ++m) _Pragma("unroll") for (int n = 0; n < 2; ++n) _Pragma("unroll") for (int k = 0; k < 2; ++k) \
;         acc[ai][bj][m][n] = __builtin_amdgcn_mfma_f32_16x16x32_bf16(Bt[n][k], At[m][k], acc[ai][bj][m][n], 0, 0, 0); __builtin_amdgcn_s_setprio(0); } while (0)
; #define PG8_WAIT_V(n) asm volatile("s_waitcnt vmcnt(" #n ")" ::: "memory")
; #define PG8_WAIT_L(n) asm volatile("s_waitcnt lgkmcnt(" #n ")" ::: "memory")
; #define PG8_BAR __builtin_amdgcn_s_barrier()
; #define PG8_SCHED __builtin_amdgcn_sched_barrier(0)
; template <class Epi, class Sched, bool ALIGN_EPI = false, bool SP2 = false>
; __device__ __forceinline__ void gemm_phase(PG8_LAS unsigned char* lds, const Gemm g, const Sched& S, const Epi& E, const int wid) {
;     ...
;             PG8_WAIT_V(8); PG8_WAIT_L(0); PG8_BAR; PG8_MMA(1, 0, At, B0); PG8_MMA(1, 1, At, B1); PG8_BAR; PG8_SCHED;
;             PG8_LDB(B0, 1, 0); PG8_LDB(B1, 1, 1); PG8_SCHED; PG8_LDA(At, 1, 0); PG8_STAGE(PG8_SA(0, 1), a2 + hstep, voffA);
;             PG8_WAIT_V(8); PG8_WAIT_L(0); PG8_BAR; PG8_MMA(0, 0, At, B0); PG8_MMA(0, 1, At, B1); PG8_BAR; PG8_SCHED;
	s_waitcnt lgkmcnt(0)
	v_mfma_f32_16x16x32_bf16 v[60:63], v[144:147], v[182:185], v[60:63]
	v_mfma_f32_16x16x32_bf16 v[52:55], v[158:161], v[182:185], v[52:55]
	v_mfma_f32_16x16x32_bf16 v[44:47], v[144:147], v[190:193], v[44:47]
	v_mfma_f32_16x16x32_bf16 v[36:39], v[158:161], v[190:193], v[36:39]
	v_mfma_f32_16x16x32_bf16 v[28:31], v[144:147], v[198:201], v[28:31]
	v_mfma_f32_16x16x32_bf16 v[20:23], v[158:161], v[198:201], v[20:23]
	v_mfma_f32_16x16x32_bf16 v[12:15], v[144:147], v[206:209], v[12:15]
	v_mfma_f32_16x16x32_bf16 v[4:7], v[158:161], v[206:209], v[4:7]
	v_mfma_f32_16x16x32_bf16 v[60:63], v[154:157], v[186:189], v[60:63]
	v_mfma_f32_16x16x32_bf16 v[52:55], v[162:165], v[186:189], v[52:55]
	v_mfma_f32_16x16x32_bf16 v[44:47], v[154:157], v[194:197], v[44:47]
	v_mfma_f32_16x16x32_bf16 v[36:39], v[162:165], v[194:197], v[36:39]
	v_mfma_f32_16x16x32_bf16 v[28:31], v[154:157], v[202:205], v[28:31]
	v_mfma_f32_16x16x32_bf16 v[20:23], v[162:165], v[202:205], v[20:23]
	v_mfma_f32_16x16x32_bf16 v[12:15], v[154:157], v[210:213], v[12:15]
	v_mfma_f32_16x16x32_bf16 v[4:7], v[162:165], v[210:213], v[4:7]
	v_mfma_f32_16x16x32_bf16 v[56:59], v[166:169], v[182:185], v[56:59]
	v_mfma_f32_16x16x32_bf16 v[48:51], v[174:177], v[182:185], v[48:51]
	v_mfma_f32_16x16x32_bf16 v[40:43], v[166:169], v[190:193], v[40:43]
	v_mfma_f32_16x16x32_bf16 v[32:35], v[174:177], v[190:193], v[32:35]
	v_mfma_f32_16x16x32_bf16 v[24:27], v[166:169], v[198:201], v[24:27]
	v_mfma_f32_16x16x32_bf16 v[16:19], v[174:177], v[198:201], v[16:19]
	v_mfma_f32_16x16x32_bf16 v[8:11], v[166:169], v[206:209], v[8:11]
	v_mfma_f32_16x16x32_bf16 v[0:3], v[174:177], v[206:209], v[0:3]
	v_mfma_f32_16x16x32_bf16 v[56:59], v[170:173], v[186:189], v[56:59]
	v_mfma_f32_16x16x32_bf16 v[48:51], v[178:181], v[186:189], v[48:51]
	v_mfma_f32_16x16x32_bf16 v[40:43], v[170:173], v[194:197], v[40:43]
	v_mfma_f32_16x16x32_bf16 v[32:35], v[178:181], v[194:197], v[32:35]
	v_mfma_f32_16x16x32_bf16 v[24:27], v[170:173], v[202:205], v[24:27]
	v_mfma_f32_16x16x32_bf16 v[16:19], v[178:181], v[202:205], v[16:19]
	v_mfma_f32_16x16x32_bf16 v[8:11], v[170:173], v[210:213], v[8:11]
	v_mfma_f32_16x16x32_bf16 v[0:3], v[178:181], v[210:213], v[0:3]
	s_barrier
	s_add_i32 s51, 0, 0x18000
	s_add_i32 s52, 0, 0x1c000
	v_add_u32_e32 v162, s51, v149
	v_add_u32_e32 v178, s52, v149
	ds_read_b128 v[144:147], v162
	ds_read_b128 v[154:157], v162 offset:1024
	ds_read_b128 v[158:161], v162 offset:2048
	ds_read_b128 v[162:165], v162 offset:3072
	ds_read_b128 v[166:169], v178
	ds_read_b128 v[170:173], v178 offset:1024
	ds_read_b128 v[174:177], v178 offset:2048
	ds_read_b128 v[178:181], v178 offset:3072
	s_add_u32 s26, s26, 0x40000
	s_addc_u32 s27, s27, 0
	s_mov_b32 m0, s35
	v_lshl_add_u64 v[222:223], s[26:27], 0, v[134:135]
	ds_read_b128 v[182:185], v153 offset:32768
	ds_read_b128 v[186:189], v153 offset:33792
	ds_read_b128 v[190:193], v153 offset:34816
	ds_read_b128 v[194:197], v153 offset:35840
	ds_read_b128 v[198:201], v153 offset:36864
	ds_read_b128 v[202:205], v153 offset:37888
	ds_read_b128 v[206:209], v153 offset:38912
	ds_read_b128 v[210:213], v153 offset:39936
	global_load_lds_dwordx4 v[222:223], off
	v_lshl_add_u64 v[222:223], s[26:27], 0, v[130:131]
	s_mov_b32 m0, s36
	s_nop 0
	global_load_lds_dwordx4 v[222:223], off
	s_waitcnt vmcnt(8)
	s_waitcnt lgkmcnt(0)
	s_barrier
	s_waitcnt lgkmcnt(0)
	v_mfma_f32_16x16x32_bf16 v[124:127], v[144:147], v[182:185], v[124:127]
	v_mfma_f32_16x16x32_bf16 v[116:119], v[158:161], v[182:185], v[116:119]
	v_mfma_f32_16x16x32_bf16 v[108:111], v[144:147], v[190:193], v[108:111]
	v_mfma_f32_16x16x32_bf16 v[100:103], v[158:161], v[190:193], v[100:103]
	v_mfma_f32_16x16x32_bf16 v[92:95], v[144:147], v[198:201], v[92:95]
	v_mfma_f32_16x16x32_bf16 v[84:87], v[158:161], v[198:201], v[84:87]
	v_mfma_f32_16x16x32_bf16 v[76:79], v[144:147], v[206:209], v[76:79]
	v_mfma_f32_16x16x32_bf16 v[68:71], v[158:161], v[206:209], v[68:71]
	v_mfma_f32_16x16x32_bf16 v[124:127], v[154:157], v[186:189], v[124:127]
	v_mfma_f32_16x16x32_bf16 v[116:119], v[162:165], v[186:189], v[116:119]
	v_mfma_f32_16x16x32_bf16 v[108:111], v[154:157], v[194:197], v[108:111]
	v_mfma_f32_16x16x32_bf16 v[100:103], v[162:165], v[194:197], v[100:103]
	v_mfma_f32_16x16x32_bf16 v[92:95], v[154:157], v[202:205], v[92:95]
	v_mfma_f32_16x16x32_bf16 v[84:87], v[162:165], v[202:205], v[84:87]
	v_mfma_f32_16x16x32_bf16 v[76:79], v[154:157], v[210:213], v[76:79]
	v_mfma_f32_16x16x32_bf16 v[68:71], v[162:165], v[210:213], v[68:71]
	v_mfma_f32_16x16x32_bf16 v[120:123], v[166:169], v[182:185], v[120:123]
	v_mfma_f32_16x16x32_bf16 v[112:115], v[174:177], v[182:185], v[112:115]
	v_mfma_f32_16x16x32_bf16 v[104:107], v[166:169], v[190:193], v[104:107]
	v_mfma_f32_16x16x32_bf16 v[96:99], v[174:177], v[190:193], v[96:99]
	v_mfma_f32_16x16x32_bf16 v[88:91], v[166:169], v[198:201], v[88:91]
	v_mfma_f32_16x16x32_bf16 v[80:83], v[174:177], v[198:201], v[80:83]
	v_mfma_f32_16x16x32_bf16 v[72:75], v[166:169], v[206:209], v[72:75]
	v_mfma_f32_16x16x32_bf16 v[64:67], v[174:177], v[206:209], v[64:67]
	v_mfma_f32_16x16x32_bf16 v[120:123], v[170:173], v[186:189], v[120:123]
	v_mfma_f32_16x16x32_bf16 v[112:115], v[178:181], v[186:189], v[112:115]
	v_mfma_f32_16x16x32_bf16 v[104:107], v[170:173], v[194:197], v[104:107]
	v_mfma_f32_16x16x32_bf16 v[96:99], v[178:181], v[194:197], v[96:99]
	v_mfma_f32_16x16x32_bf16 v[88:91], v[170:173], v[202:205], v[88:91]
	v_mfma_f32_16x16x32_bf16 v[80:83], v[178:181], v[202:205], v[80:83]
	v_mfma_f32_16x16x32_bf16 v[72:75], v[170:173], v[210:213], v[72:75]
	v_mfma_f32_16x16x32_bf16 v[64:67], v[178:181], v[210:213], v[64:67]
	s_barrier
; #define PG8_STAGE(bufoff, gbase, voff) do { _Pragma("unroll") for (int _i = 0; _i < 2; ++_i) \
;         __builtin_amdgcn_global_load_lds((const unsigned*)((const char*)(gbase) + (voff)[_i]), (PG8_LAS unsigned*)(lds + (bufoff) + ldsw + _i * 8192), 16, 0, 0); } while (0)
; #define PG8_LDA(dst, b, h) do { _Pragma("unroll") for (int m = 0; m < 4; ++m) _Pragma("unroll") for (int k = 0; k < 2; ++k) dst[m][k] = *(const PG8_LAS bf16x8*)(lds + PG8_SA(b, h) + aoff + m * 2048 + k * 1024); } while (0)
; #define PG8_MMA(ai, bj, At, Bt) do { __builtin_amdgcn_s_setprio(1); _Pragma("unroll") for (int m = 0; m < 4; ++m) _Pragma("unroll") for (int n = 0; n < 2; ++n) _Pragma("unroll") for (int k = 0; k < 2; ++k) \
;         acc[ai][bj][m][n] = __builtin_amdgcn_mfma_f32_16x16x32_bf16(Bt[n][k], At[m][k], acc[ai][bj][m][n], 0, 0, 0); __builtin_amdgcn_s_setprio(0); } while (0)
; #define PG8_WAIT_V(n) asm volatile("s_waitcnt vmcnt(" #n ")" ::: "memory")
; #define PG8_WAIT_L(n) asm volatile("s_waitcnt lgkmcnt(" #n ")" ::: "memory")
; #define PG8_BAR __builtin_amdgcn_s_barrier()
; #define PG8_SCHED __builtin_amdgcn_sched_barrier(0)
; template <class Epi, class Sched, bool ALIGN_EPI = false, bool SP2 = false>
; __device__ __forceinline__ void gemm_phase(PG8_LAS unsigned char* lds, const Gemm g, const Sched& S, const Epi& E, const int wid) {
;     ...
;         for (int t = 0; t < nt; t += 2) {
;     ...
;             PG8_LDA(At, 1, 1); PG8_STAGE(PG8_SB(1, 0), b3, voffB); PG8_STAGE(PG8_SB(1, 1), b3 + hstep, voffB); PG8_STAGE(PG8_SA(1, 0), a3, voffA);
;             PG8_WAIT_V(8); PG8_WAIT_L(0); PG8_BAR; PG8_MMA(1, 0, At, B0); PG8_MMA(1, 1, At, B1); PG8_BAR; PG8_SCHED;
	s_add_i32 s26, s51, s33
	v_lshl_add_u64 v[214:215], v[214:215], 0, s[8:9]
	s_mov_b32 m0, s26
	ds_read_b128 v[182:185], v153 offset:49152
	ds_read_b128 v[186:189], v153 offset:50176
	ds_read_b128 v[190:193], v153 offset:51200
	ds_read_b128 v[194:197], v153 offset:52224
	ds_read_b128 v[198:201], v153 offset:53248
	ds_read_b128 v[202:205], v153 offset:54272
	ds_read_b128 v[206:209], v153 offset:55296
	ds_read_b128 v[210:213], v153 offset:56320
	global_load_lds_dwordx4 v[214:215], off
	s_add_i32 m0, s26, 0x2000
	s_add_u32 s24, s24, 0x40080
	v_lshl_add_u64 v[214:215], v[216:217], 0, s[8:9]
	s_addc_u32 s25, s25, 0
	s_add_i32 s26, s52, s33
	global_load_lds_dwordx4 v[214:215], off
	v_lshl_add_u64 v[214:215], s[24:25], 0, v[132:133]
	s_mov_b32 m0, s26
	s_nop 0
	global_load_lds_dwordx4 v[214:215], off
	v_lshl_add_u64 v[214:215], s[24:25], 0, v[128:129]
	s_add_i32 m0, s26, 0x2000
	s_nop 0
	global_load_lds_dwordx4 v[214:215], off
	v_lshl_add_u64 v[214:215], v[218:219], 0, s[8:9]
	s_mov_b32 m0, s38
	s_nop 0
	global_load_lds_dwordx4 v[214:215], off
	v_lshl_add_u64 v[214:215], v[220:221], 0, s[8:9]
	s_mov_b32 m0, s39
	s_nop 0
	global_load_lds_dwordx4 v[214:215], off
	s_waitcnt vmcnt(8)
	s_waitcnt lgkmcnt(0)
	s_barrier
	s_waitcnt lgkmcnt(0)
	v_mfma_f32_16x16x32_bf16 v[60:63], v[144:147], v[182:185], v[60:63]
	v_mfma_f32_16x16x32_bf16 v[52:55], v[158:161], v[182:185], v[52:55]
	v_mfma_f32_16x16x32_bf16 v[44:47], v[144:147], v[190:193], v[44:47]
	v_mfma_f32_16x16x32_bf16 v[36:39], v[158:161], v[190:193], v[36:39]
	v_mfma_f32_16x16x32_bf16 v[28:31], v[144:147], v[198:201], v[28:31]
	v_mfma_f32_16x16x32_bf16 v[20:23], v[158:161], v[198:201], v[20:23]
	v_mfma_f32_16x16x32_bf16 v[12:15], v[144:147], v[206:209], v[12:15]
	v_mfma_f32_16x16x32_bf16 v[4:7], v[158:161], v[206:209], v[4:7]
	v_mfma_f32_16x16x32_bf16 v[60:63], v[154:157], v[186:189], v[60:63]
	v_mfma_f32_16x16x32_bf16 v[52:55], v[162:165], v[186:189], v[52:55]
	v_mfma_f32_16x16x32_bf16 v[44:47], v[154:157], v[194:197], v[44:47]
	v_mfma_f32_16x16x32_bf16 v[36:39], v[162:165], v[194:197], v[36:39]
	v_mfma_f32_16x16x32_bf16 v[28:31], v[154:157], v[202:205], v[28:31]
	v_mfma_f32_16x16x32_bf16 v[20:23], v[162:165], v[202:205], v[20:23]
	v_mfma_f32_16x16x32_bf16 v[12:15], v[154:157], v[210:213], v[12:15]
	v_mfma_f32_16x16x32_bf16 v[4:7], v[162:165], v[210:213], v[4:7]
	v_mfma_f32_16x16x32_bf16 v[56:59], v[166:169], v[182:185], v[56:59]
	v_mfma_f32_16x16x32_bf16 v[48:51], v[174:177], v[182:185], v[48:51]
	v_mfma_f32_16x16x32_bf16 v[40:43], v[166:169], v[190:193], v[40:43]
	v_mfma_f32_16x16x32_bf16 v[32:35], v[174:177], v[190:193], v[32:35]
	v_mfma_f32_16x16x32_bf16 v[24:27], v[166:169], v[198:201], v[24:27]
	v_mfma_f32_16x16x32_bf16 v[16:19], v[174:177], v[198:201], v[16:19]
	v_mfma_f32_16x16x32_bf16 v[8:11], v[166:169], v[206:209], v[8:11]
	v_mfma_f32_16x16x32_bf16 v[0:3], v[174:177], v[206:209], v[0:3]
	v_mfma_f32_16x16x32_bf16 v[56:59], v[170:173], v[186:189], v[56:59]
	v_mfma_f32_16x16x32_bf16 v[48:51], v[178:181], v[186:189], v[48:51]
	v_mfma_f32_16x16x32_bf16 v[40:43], v[170:173], v[194:197], v[40:43]
	v_mfma_f32_16x16x32_bf16 v[32:35], v[178:181], v[194:197], v[32:35]
	v_mfma_f32_16x16x32_bf16 v[24:27], v[170:173], v[202:205], v[24:27]
	v_mfma_f32_16x16x32_bf16 v[16:19], v[178:181], v[202:205], v[16:19]
	v_mfma_f32_16x16x32_bf16 v[8:11], v[170:173], v[210:213], v[8:11]
	v_mfma_f32_16x16x32_bf16 v[0:3], v[178:181], v[210:213], v[0:3]
	s_barrier
	s_add_i32 s50, s50, 2
	s_add_u32 s22, s22, 0x100
	s_addc_u32 s23, s23, 0
	s_add_u32 s48, s48, 0x100
	s_addc_u32 s49, s49, 0
	s_cmp_gt_u32 s50, 13
	s_cbranch_scc0 .LBB0_1311
	s_and_b64 vcc, exec, s[10:11]
	s_cbranch_vccz .LBB0_1314
	s_barrier

; #define PG8_WAIT_V(n) asm volatile("s_waitcnt vmcnt(" #n ")" ::: "memory")
; #define PG8_BAR __builtin_amdgcn_s_barrier()
;     __host__ __device__ bool next(int i, Unit& u) const {
;         const long L = (long)i * G + c; if (L >= nwg) return false;
;         int wgid = (int)L; { const int q = nwg / NXCD, r = nwg % NXCD, xcd = wgid % NXCD, off = wgid / NXCD; wgid = (xcd < r ? xcd * (q + 1) : r * (q + 1) + (xcd - r) * q) + off; }
;         const int nig = WGM * nN, gid = wgid / nig, fm = gid * WGM, gsz = (nM - fm) < WGM ? (nM - fm) : WGM;
;         u.pm = fm + ((wgid % nig) % gsz); u.pn = (wgid % nig) / gsz; return true;
; template <class Epi, class Sched, bool ALIGN_EPI = false, bool SP2 = false>
; __device__ __forceinline__ void gemm_phase(PG8_LAS unsigned char* lds, const Gemm g, const Sched& S, const Epi& E, const int wid) {
;     const int lane = lane_now(), tid = wid * 64 + lane, wr = wid >> 2, wc = wid & 3, fr = lane & 15, fq = lane >> 4;
;     const int K = g.K, nt = K / BK;
;     unsigned voffA[2], voffB[2];
; #pragma unroll
;     for (int i = 0; i < 2; ++i) { int R, C; stage_rc(tid * 16 + i * 8192, R, C); const int Rb = Epi::PERM ? ((R & ~31) + perm32(R & 31)) : R;
;         voffA[i] = (unsigned)(R * K + C) * 2u; voffB[i] = (unsigned)(Rb * K + C) * 2u; }
;     const size_t kstep = (size_t)(BK * 2);
;     const size_t hstep = (size_t)HALF * K * 2;
;     const size_t tstep = 2 * hstep;
;     const unsigned ldsw = (unsigned)wid * 1024u;
;     const int aoff = lds_byte(wr * 64 + fr, fq * 8), boff = lds_byte(wc * 32 + fr, fq * 8);
;     ...
;     Unit cur, nxt; int ui = 0;
;     if (!S.next(0, cur)) return;
;     f32x4 acc[2][2][4][2];
; #pragma unroll
;     for (int a = 0; a < 2; ++a)
; #pragma unroll
;         for (int b = 0; b < 2; ++b)
; #pragma unroll
;             for (int m = 0; m < 4; ++m)
; #pragma unroll
;                 for (int n = 0; n < 2; ++n) acc[a][b][m][n] = (f32x4){0.f, 0.f, 0.f, 0.f};
;     bf16x8 At[4][2], B0[2][2], B1[2][2];
;     const char* cA = (const char*)g.A + (size_t)cur.pm * tstep; const char* cB = (const char*)g.Bt + (size_t)cur.pn * tstep;
;     S.a_ready(cur);
;     if constexpr (SP2) {
;         PG8_STAGE(PG8_SB(0, 0), cB, voffB); PG8_STAGE(PG8_SB(0, 1), cB + hstep, voffB); PG8_STAGE(PG8_SA(0, 0), cA, voffA); PG8_STAGE(PG8_SA(0, 1), cA + hstep, voffA);
;         if (wr == 1) PG8_BAR;
;         PG8_WAIT_V(2); PG8_BAR;
.LBB0_1377:
	v_lshl_add_u32 v0, v8, 4, s33
	v_ashrrev_i32_e32 v1, 31, v0
	v_lshrrev_b32_e32 v1, 22, v1
	v_add_u32_e32 v1, v0, v1
	v_ashrrev_i32_e32 v9, 10, v1
	v_mul_i32_i24_e32 v1, 0x400, v9
	v_sub_u32_e32 v1, v0, v1
	v_lshrrev_b32_e32 v2, 4, v1
	v_bitop3_b32 v1, v2, v1, 32 bitop3:0x6c
	v_ashrrev_i32_e32 v3, 31, v1
	v_lshrrev_b32_e32 v3, 26, v3
	v_lshlrev_b32_e32 v2, 3, v9
	v_add_u32_e32 v3, v1, v3
	v_and_b32_e32 v2, -16, v2
	v_ashrrev_i32_e32 v11, 6, v3
	v_and_b32_e32 v3, 0xc0, v3
	v_add_u32_e32 v2, v11, v2
	v_lshlrev_b32_e32 v4, 5, v9
	v_sub_u32_e32 v1, v1, v3
	v_mov_b32_e32 v3, 1
	v_and_b32_e32 v10, 32, v4
	v_ashrrev_i16_sdwa v1, v3, sext(v1) dst_sel:DWORD dst_unused:UNUSED_PAD src0_sel:DWORD src1_sel:BYTE_0
	v_lshlrev_b32_e32 v4, 1, v2
	v_lshrrev_b32_e32 v5, 2, v2
	v_and_b32_e32 v6, 3, v11
	s_mov_b32 s3, 0xffffe0
	v_bfe_i32 v12, v1, 0, 16
	v_and_b32_e32 v4, 24, v4
	v_and_b32_e32 v5, 4, v5
	v_and_or_b32 v6, v2, s3, v6
	s_movk_i32 s0, 0xb00
	v_add_u32_e32 v1, v10, v12
	v_or3_b32 v4, v6, v5, v4
	v_mul_lo_u32 v2, v2, s0
	v_add_lshl_u32 v128, v1, v2, 1
	v_mul_u32_u24_e32 v2, 0xb00, v4
	v_add_u32_e32 v0, 0x2000, v0
	v_add_lshl_u32 v130, v2, v1, 1
	v_ashrrev_i32_e32 v1, 31, v0
	v_lshrrev_b32_e32 v1, 22, v1
	v_add_u32_e32 v1, v0, v1
	v_ashrrev_i32_e32 v13, 10, v1
	v_mul_i32_i24_e32 v1, 0x400, v13
	v_sub_u32_e32 v0, v0, v1
	v_lshrrev_b32_e32 v1, 4, v0
	v_bitop3_b32 v0, v1, v0, 32 bitop3:0x6c
	s_add_u32 s29, s92, 0x1c80000
	v_ashrrev_i32_e32 v2, 31, v0
	s_addc_u32 s30, s93, 0
	v_lshrrev_b32_e32 v2, 26, v2
	s_add_i32 s1, s2, s1
	v_lshlrev_b32_e32 v1, 3, v13
	v_add_u32_e32 v2, v0, v2
	s_ashr_i32 s2, s1, 31
	v_and_b32_e32 v1, -16, v1
	v_ashrrev_i32_e32 v14, 6, v2
	v_lshlrev_b32_e32 v4, 5, v13
	s_lshr_b32 s2, s2, 28
	v_add_u32_e32 v1, v14, v1
	v_and_b32_e32 v15, 32, v4
	v_and_b32_e32 v4, 3, v14
	s_add_i32 s2, s1, s2
	v_and_or_b32 v4, v1, s3, v4
	s_ashr_i32 s3, s2, 4
	s_and_b32 s2, s2, 0xfff0
	s_sub_i32 s2, s1, s2
	s_bfe_i32 s1, s2, 0x80000
	s_bfe_u32 s1, s1, 0x2000d
	s_add_i32 s4, s2, s1
	v_and_b32_e32 v2, 0xffc0, v2
	s_bfe_i32 s1, s4, 0x80000
	s_and_b32 s4, s4, 0xfc
	v_sub_u32_e32 v0, v0, v2
	s_sub_i32 s2, s2, s4
	v_lshrrev_b16_e32 v2, 7, v0
	s_lshl_b32 s3, s3, 2
	s_sext_i32_i16 s5, s1
	s_sext_i32_i8 s2, s2
	v_and_b32_e32 v2, 1, v2
	s_add_i32 s47, s3, s2
	s_ashr_i32 s2, s5, 2
	v_add_u16_e32 v0, v0, v2
	s_lshr_b32 s1, s5, 2
	s_mul_hi_i32 s3, s2, 0x160000
	s_mul_i32 s2, s2, 0x160000
	v_ashrrev_i16_sdwa v0, v3, sext(v0) dst_sel:DWORD dst_unused:UNUSED_PAD src0_sel:DWORD src1_sel:BYTE_0
	v_lshlrev_b32_e32 v2, 1, v1
	v_lshrrev_b32_e32 v3, 2, v1
	s_add_u32 s22, s29, s2
	v_bfe_i32 v16, v0, 0, 16
	v_and_b32_e32 v2, 24, v2
	v_and_b32_e32 v3, 4, v3
	s_addc_u32 s23, s30, s3
	s_add_i32 s31, s33, 0
	v_add_u32_e32 v0, v15, v16
	v_or3_b32 v2, v4, v3, v2
	v_mul_lo_u32 v1, v1, s0
	s_add_i32 m0, s31, 0x10000
	v_add_lshl_u32 v132, v0, v1, 1
	v_mul_u32_u24_e32 v1, 0xb00, v2
	global_load_lds_dwordx4 v130, s[22:23]
	s_add_i32 m0, s31, 0x12000
	v_add_lshl_u32 v134, v1, v0, 1
	s_add_u32 s2, s22, 0xb0000
	global_load_lds_dwordx4 v134, s[22:23]
	s_addc_u32 s3, s23, 0
	s_add_i32 m0, s31, 0x14000
	s_mul_i32 s6, s47, 0x160000
	global_load_lds_dwordx4 v130, s[2:3]
	s_add_i32 m0, s31, 0x16000
	s_mul_hi_i32 s4, s47, 0x160000
	s_add_u32 s20, s96, s6
	s_addc_u32 s21, s97, s4
	s_add_i32 s34, s31, 0x2000
	global_load_lds_dwordx4 v134, s[2:3]
	s_mov_b32 m0, s31
	s_add_u32 s2, s20, 0xb0000
	global_load_lds_dwordx4 v128, s[20:21]
	s_mov_b32 m0, s34
	s_addc_u32 s3, s21, 0
	s_add_i32 s35, s31, 0x4000
	global_load_lds_dwordx4 v132, s[20:21]
	s_mov_b32 m0, s35
	s_add_i32 s36, s31, 0x6000
	global_load_lds_dwordx4 v128, s[2:3]
	s_mov_b32 m0, s36
	v_mov_b32_e32 v131, 0
	global_load_lds_dwordx4 v132, s[2:3]
	v_readlane_b32 s4, v244, 18
	v_mov_b32_e32 v135, v131
	v_mov_b32_e32 v129, v131
	v_mov_b32_e32 v133, v131
	s_cmp_eq_u32 s4, 1
	s_mov_b32 s37, 0
	v_lshl_add_u64 v[4:5], s[22:23], 0, v[130:131]
	v_lshl_add_u64 v[2:3], s[22:23], 0, v[134:135]
	s_mov_b64 s[2:3], 0xb0000
	v_lshl_add_u64 v[0:1], s[20:21], 0, v[128:129]
	s_cselect_b64 s[6:7], -1, 0
	s_cmp_lg_u32 s4, 1
	v_lshl_add_u64 v[6:7], s[20:21], 0, v[132:133]
	s_cbranch_scc1 .LBB0_1379
	s_barrier
	s_setprio 1

; #define PG8_STAGE(bufoff, gbase, voff) do { _Pragma("unroll") for (int _i = 0; _i < 2; ++_i) \
;         __builtin_amdgcn_global_load_lds((const unsigned*)((const char*)(gbase) + (voff)[_i]), (PG8_LAS unsigned*)(lds + (bufoff) + ldsw + _i * 8192), 16, 0, 0); } while (0)
; #define PG8_LDA(dst, b, h) do { _Pragma("unroll") for (int m = 0; m < 4; ++m) _Pragma("unroll") for (int k = 0; k < 2; ++k) dst[m][k] = *(const PG8_LAS bf16x8*)(lds + PG8_SA(b, h) + aoff + m * 2048 + k * 1024); } while (0)
; #define PG8_LDB(dst, b, h) do { _Pragma("unroll") for (int n = 0; n < 2; ++n) _Pragma("unroll") for (int k = 0; k < 2; ++k) dst[n][k] = *(const PG8_LAS bf16x8*)(lds + PG8_SB(b, h) + boff + n * 2048 + k * 1024); } while (0)
; #define PG8_MMA(ai, bj, At, Bt) do { __builtin_amdgcn_s_setprio(1); _Pragma("unroll") for (int m = 0; m < 4; ++m) _Pragma("unroll") for (int n = 0; n < 2; ++n) _Pragma("unroll") for (int k = 0; k < 2; ++k) \
;         acc[ai][bj][m][n] = __builtin_amdgcn_mfma_f32_16x16x32_bf16(Bt[n][k], At[m][k], acc[ai][bj][m][n], 0, 0, 0); __builtin_amdgcn_s_setprio(0); } while (0)
; #define PG8_WAIT_V(n) asm volatile("s_waitcnt vmcnt(" #n ")" ::: "memory")
; #define PG8_WAIT_L(n) asm volatile("s_waitcnt lgkmcnt(" #n ")" ::: "memory")
; #define PG8_BAR __builtin_amdgcn_s_barrier()
; #define PG8_SCHED __builtin_amdgcn_sched_barrier(0)
; template <class Epi, class Sched, bool ALIGN_EPI = false, bool SP2 = false>
; __device__ __forceinline__ void gemm_phase(PG8_LAS unsigned char* lds, const Gemm g, const Sched& S, const Epi& E, const int wid) {
;     ...
;             PG8_LDB(B0, 0, 0); PG8_LDB(B1, 0, 1); PG8_SCHED; PG8_LDA(At, 0, 0); PG8_STAGE(PG8_SA(1, 1), a1 + hstep, voffA);
;             PG8_WAIT_V(8); PG8_WAIT_L(0); PG8_BAR; PG8_MMA(0, 0, At, B0); PG8_MMA(0, 1, At, B1); PG8_BAR; PG8_SCHED;
;             PG8_LDA(At, 0, 1); PG8_STAGE(PG8_SB(0, 0), b2, voffB); PG8_STAGE(PG8_SB(0, 1), b2 + hstep, voffB); PG8_STAGE(PG8_SA(0, 0), a2, voffA);
;             PG8_WAIT_V(8); PG8_WAIT_L(0); PG8_BAR; PG8_MMA(1, 0, At, B0); PG8_MMA(1, 1, At, B1); PG8_BAR; PG8_SCHED;
.LBB0_1393:
	ds_read_b128 v[144:147], v159
	ds_read_b128 v[148:151], v159 offset:1024
	ds_read_b128 v[152:155], v159 offset:2048
	ds_read_b128 v[162:165], v159 offset:3072
	ds_read_b128 v[166:169], v160
	ds_read_b128 v[170:173], v160 offset:1024
	ds_read_b128 v[174:177], v160 offset:2048
	ds_read_b128 v[178:181], v160 offset:3072
	s_add_u32 s22, s20, 0x100
	s_addc_u32 s23, s21, 0
	s_cmp_eq_u32 s51, 40
	s_cselect_b32 s27, s5, s23
	s_cselect_b32 s26, s4, s22
	s_cselect_b32 s25, s19, s50
	s_cselect_b32 s24, s18, s49
	v_lshl_add_u64 v[214:215], s[20:21], 0, v[136:137]
	s_add_i32 m0, s31, 0xc000
	ds_read_b128 v[182:185], v161
	ds_read_b128 v[186:189], v161 offset:1024
	ds_read_b128 v[190:193], v161 offset:2048
	ds_read_b128 v[194:197], v161 offset:3072
	ds_read_b128 v[198:201], v161 offset:4096
	ds_read_b128 v[202:205], v161 offset:5120
	ds_read_b128 v[206:209], v161 offset:6144
	ds_read_b128 v[210:213], v161 offset:7168
	global_load_lds_dwordx4 v[214:215], off
	v_lshl_add_u64 v[214:215], s[20:21], 0, v[138:139]
	s_add_i32 m0, s31, 0xe000
	s_nop 0
	global_load_lds_dwordx4 v[214:215], off
	s_waitcnt vmcnt(8)
	s_waitcnt lgkmcnt(0)
	s_barrier
	s_waitcnt lgkmcnt(0)
	v_mfma_f32_16x16x32_bf16 v[124:127], v[144:147], v[182:185], v[124:127]
	v_mfma_f32_16x16x32_bf16 v[120:123], v[152:155], v[182:185], v[120:123]
	v_mfma_f32_16x16x32_bf16 v[116:119], v[144:147], v[190:193], v[116:119]
	v_mfma_f32_16x16x32_bf16 v[112:115], v[152:155], v[190:193], v[112:115]
	v_mfma_f32_16x16x32_bf16 v[108:111], v[144:147], v[198:201], v[108:111]
	v_mfma_f32_16x16x32_bf16 v[104:107], v[152:155], v[198:201], v[104:107]
	v_mfma_f32_16x16x32_bf16 v[100:103], v[144:147], v[206:209], v[100:103]
	v_mfma_f32_16x16x32_bf16 v[96:99], v[152:155], v[206:209], v[96:99]
	v_mfma_f32_16x16x32_bf16 v[124:127], v[148:151], v[186:189], v[124:127]
	v_mfma_f32_16x16x32_bf16 v[120:123], v[162:165], v[186:189], v[120:123]
	v_mfma_f32_16x16x32_bf16 v[116:119], v[148:151], v[194:197], v[116:119]
	v_mfma_f32_16x16x32_bf16 v[112:115], v[162:165], v[194:197], v[112:115]
	v_mfma_f32_16x16x32_bf16 v[108:111], v[148:151], v[202:205], v[108:111]
	v_mfma_f32_16x16x32_bf16 v[104:107], v[162:165], v[202:205], v[104:107]
	v_mfma_f32_16x16x32_bf16 v[100:103], v[148:151], v[210:213], v[100:103]
	v_mfma_f32_16x16x32_bf16 v[96:99], v[162:165], v[210:213], v[96:99]
	v_mfma_f32_16x16x32_bf16 v[60:63], v[166:169], v[182:185], v[60:63]
	v_mfma_f32_16x16x32_bf16 v[56:59], v[174:177], v[182:185], v[56:59]
	v_mfma_f32_16x16x32_bf16 v[52:55], v[166:169], v[190:193], v[52:55]
	v_mfma_f32_16x16x32_bf16 v[48:51], v[174:177], v[190:193], v[48:51]
	v_mfma_f32_16x16x32_bf16 v[44:47], v[166:169], v[198:201], v[44:47]
	v_mfma_f32_16x16x32_bf16 v[40:43], v[174:177], v[198:201], v[40:43]
	v_mfma_f32_16x16x32_bf16 v[36:39], v[166:169], v[206:209], v[36:39]
	v_mfma_f32_16x16x32_bf16 v[32:35], v[174:177], v[206:209], v[32:35]
	v_mfma_f32_16x16x32_bf16 v[60:63], v[170:173], v[186:189], v[60:63]
	v_mfma_f32_16x16x32_bf16 v[56:59], v[178:181], v[186:189], v[56:59]
	v_mfma_f32_16x16x32_bf16 v[52:55], v[170:173], v[194:197], v[52:55]
	v_mfma_f32_16x16x32_bf16 v[48:51], v[178:181], v[194:197], v[48:51]
	v_mfma_f32_16x16x32_bf16 v[44:47], v[170:173], v[202:205], v[44:47]
	v_mfma_f32_16x16x32_bf16 v[40:43], v[178:181], v[202:205], v[40:43]
	v_mfma_f32_16x16x32_bf16 v[36:39], v[170:173], v[210:213], v[36:39]
	v_mfma_f32_16x16x32_bf16 v[32:35], v[178:181], v[210:213], v[32:35]
	s_barrier
	s_add_i32 s20, s43, s33
	v_lshl_add_u64 v[214:215], s[24:25], 0, v[130:131]
	s_mov_b32 m0, s20
	ds_read_b128 v[182:185], v161 offset:16384
	ds_read_b128 v[186:189], v161 offset:17408
	ds_read_b128 v[190:193], v161 offset:18432
	ds_read_b128 v[194:197], v161 offset:19456
	ds_read_b128 v[198:201], v161 offset:20480
	ds_read_b128 v[202:205], v161 offset:21504
	ds_read_b128 v[206:209], v161 offset:22528
	ds_read_b128 v[210:213], v161 offset:23552
	global_load_lds_dwordx4 v[214:215], off
	s_add_i32 m0, s20, 0x2000
	s_add_u32 s20, s24, 0xb0000
	v_lshl_add_u64 v[216:217], s[24:25], 0, v[134:135]
	s_addc_u32 s21, s25, 0
	s_add_i32 s52, s44, s33
	global_load_lds_dwordx4 v[216:217], off
	v_lshl_add_u64 v[218:219], s[20:21], 0, v[130:131]
	s_mov_b32 m0, s52
	v_lshl_add_u64 v[220:221], s[26:27], 0, v[132:133]
	global_load_lds_dwordx4 v[218:219], off
	v_lshl_add_u64 v[218:219], s[20:21], 0, v[134:135]
	s_add_i32 m0, s52, 0x2000
	s_nop 0
	global_load_lds_dwordx4 v[218:219], off
	v_lshl_add_u64 v[218:219], s[26:27], 0, v[128:129]
	s_mov_b32 m0, s31
	s_nop 0
	global_load_lds_dwordx4 v[218:219], off
	s_mov_b32 m0, s34
	s_nop 0
	global_load_lds_dwordx4 v[220:221], off
	s_waitcnt vmcnt(8)
	s_waitcnt lgkmcnt(0)
	s_barrier
; #define PG8_STAGE(bufoff, gbase, voff) do { _Pragma("unroll") for (int _i = 0; _i < 2; ++_i) \
;         __builtin_amdgcn_global_load_lds((const unsigned*)((const char*)(gbase) + (voff)[_i]), (PG8_LAS unsigned*)(lds + (bufoff) + ldsw + _i * 8192), 16, 0, 0); } while (0)
; #define PG8_LDA(dst, b, h) do { _Pragma("unroll") for (int m = 0; m < 4; ++m) _Pragma("unroll") for (int k = 0; k < 2; ++k) dst[m][k] = *(const PG8_LAS bf16x8*)(lds + PG8_SA(b, h) + aoff + m * 2048 + k * 1024); } while (0)
; #define PG8_LDB(dst, b, h) do { _Pragma("unroll") for (int n = 0; n < 2; ++n) _Pragma("unroll") for (int k = 0; k < 2; ++k) dst[n][k] = *(const PG8_LAS bf16x8*)(lds + PG8_SB(b, h) + boff + n * 2048 + k * 1024); } while (0)
; #define PG8_MMA(ai, bj, At, Bt) do { __builtin_amdgcn_s_setprio(1); _Pragma("unroll") for (int m = 0; m < 4; ++m) _Pragma("unroll") for (int n = 0; n < 2; ++n) _Pragma("unroll") for (int k = 0; k < 2; ++k) \
;         acc[ai][bj][m][n] = __builtin_amdgcn_mfma_f32_16x16x32_bf16(Bt[n][k], At[m][k], acc[ai][bj][m][n], 0, 0, 0); __builtin_amdgcn_s_setprio(0); } while (0)
; #define PG8_WAIT_V(n) asm volatile("s_waitcnt vmcnt(" #n ")" ::: "memory")
; #define PG8_WAIT_L(n) asm volatile("s_waitcnt lgkmcnt(" #n ")" ::: "memory")
; #define PG8_BAR __builtin_amdgcn_s_barrier()
; #define PG8_SCHED __builtin_amdgcn_sched_barrier(0)
; template <class Epi, class Sched, bool ALIGN_EPI = false, bool SP2 = false>
; __device__ __forceinline__ void gemm_phase(PG8_LAS unsigned char* lds, const Gemm g, const Sched& S, const Epi& E, const int wid) {
;     ...
;             PG8_WAIT_V(8); PG8_WAIT_L(0); PG8_BAR; PG8_MMA(1, 0, At, B0); PG8_MMA(1, 1, At, B1); PG8_BAR; PG8_SCHED;
;             PG8_LDB(B0, 1, 0); PG8_LDB(B1, 1, 1); PG8_SCHED; PG8_LDA(At, 1, 0); PG8_STAGE(PG8_SA(0, 1), a2 + hstep, voffA);
;             PG8_WAIT_V(8); PG8_WAIT_L(0); PG8_BAR; PG8_MMA(0, 0, At, B0); PG8_MMA(0, 1, At, B1); PG8_BAR; PG8_SCHED;
	s_waitcnt lgkmcnt(0)
	v_mfma_f32_16x16x32_bf16 v[92:95], v[144:147], v[182:185], v[92:95]
	v_mfma_f32_16x16x32_bf16 v[88:91], v[152:155], v[182:185], v[88:91]
	v_mfma_f32_16x16x32_bf16 v[84:87], v[144:147], v[190:193], v[84:87]
	v_mfma_f32_16x16x32_bf16 v[80:83], v[152:155], v[190:193], v[80:83]
	v_mfma_f32_16x16x32_bf16 v[76:79], v[144:147], v[198:201], v[76:79]
	v_mfma_f32_16x16x32_bf16 v[72:75], v[152:155], v[198:201], v[72:75]
	v_mfma_f32_16x16x32_bf16 v[68:71], v[144:147], v[206:209], v[68:71]
	v_mfma_f32_16x16x32_bf16 v[64:67], v[152:155], v[206:209], v[64:67]
	v_mfma_f32_16x16x32_bf16 v[92:95], v[148:151], v[186:189], v[92:95]
	v_mfma_f32_16x16x32_bf16 v[88:91], v[162:165], v[186:189], v[88:91]
	v_mfma_f32_16x16x32_bf16 v[84:87], v[148:151], v[194:197], v[84:87]
	v_mfma_f32_16x16x32_bf16 v[80:83], v[162:165], v[194:197], v[80:83]
	v_mfma_f32_16x16x32_bf16 v[76:79], v[148:151], v[202:205], v[76:79]
	v_mfma_f32_16x16x32_bf16 v[72:75], v[162:165], v[202:205], v[72:75]
	v_mfma_f32_16x16x32_bf16 v[68:71], v[148:151], v[210:213], v[68:71]
	v_mfma_f32_16x16x32_bf16 v[64:67], v[162:165], v[210:213], v[64:67]
	v_mfma_f32_16x16x32_bf16 v[28:31], v[166:169], v[182:185], v[28:31]
	v_mfma_f32_16x16x32_bf16 v[24:27], v[174:177], v[182:185], v[24:27]
	v_mfma_f32_16x16x32_bf16 v[20:23], v[166:169], v[190:193], v[20:23]
	v_mfma_f32_16x16x32_bf16 v[16:19], v[174:177], v[190:193], v[16:19]
	v_mfma_f32_16x16x32_bf16 v[12:15], v[166:169], v[198:201], v[12:15]
	v_mfma_f32_16x16x32_bf16 v[8:11], v[174:177], v[198:201], v[8:11]
	v_mfma_f32_16x16x32_bf16 v[4:7], v[166:169], v[206:209], v[4:7]
	v_mfma_f32_16x16x32_bf16 v[0:3], v[174:177], v[206:209], v[0:3]
	v_mfma_f32_16x16x32_bf16 v[28:31], v[170:173], v[186:189], v[28:31]
	v_mfma_f32_16x16x32_bf16 v[24:27], v[178:181], v[186:189], v[24:27]
	v_mfma_f32_16x16x32_bf16 v[20:23], v[170:173], v[194:197], v[20:23]
	v_mfma_f32_16x16x32_bf16 v[16:19], v[178:181], v[194:197], v[16:19]
	v_mfma_f32_16x16x32_bf16 v[12:15], v[170:173], v[202:205], v[12:15]
	v_mfma_f32_16x16x32_bf16 v[8:11], v[178:181], v[202:205], v[8:11]
	v_mfma_f32_16x16x32_bf16 v[4:7], v[170:173], v[210:213], v[4:7]
	v_mfma_f32_16x16x32_bf16 v[0:3], v[178:181], v[210:213], v[0:3]
	s_barrier
	s_add_i32 s52, 0, 0x18000
	s_add_i32 s53, 0, 0x1c000
	v_add_u32_e32 v162, s52, v157
	v_add_u32_e32 v178, s53, v157
	ds_read_b128 v[144:147], v162
	ds_read_b128 v[148:151], v162 offset:1024
	ds_read_b128 v[152:155], v162 offset:2048
	ds_read_b128 v[162:165], v162 offset:3072
	ds_read_b128 v[166:169], v178
	ds_read_b128 v[170:173], v178 offset:1024
	ds_read_b128 v[174:177], v178 offset:2048
	ds_read_b128 v[178:181], v178 offset:3072
	s_add_u32 s20, s26, 0xb0000
	s_addc_u32 s21, s27, 0
	s_mov_b32 m0, s35
	v_lshl_add_u64 v[222:223], s[20:21], 0, v[128:129]
	ds_read_b128 v[182:185], v161 offset:32768
	ds_read_b128 v[186:189], v161 offset:33792
	ds_read_b128 v[190:193], v161 offset:34816
	ds_read_b128 v[194:197], v161 offset:35840
	ds_read_b128 v[198:201], v161 offset:36864
	ds_read_b128 v[202:205], v161 offset:37888
	ds_read_b128 v[206:209], v161 offset:38912
	ds_read_b128 v[210:213], v161 offset:39936
	global_load_lds_dwordx4 v[222:223], off
	v_lshl_add_u64 v[222:223], s[20:21], 0, v[132:133]
	s_mov_b32 m0, s36
	s_nop 0
	global_load_lds_dwordx4 v[222:223], off
	s_waitcnt vmcnt(8)
	s_waitcnt lgkmcnt(0)
	s_barrier
	s_waitcnt lgkmcnt(0)
	v_mfma_f32_16x16x32_bf16 v[124:127], v[144:147], v[182:185], v[124:127]
	v_mfma_f32_16x16x32_bf16 v[120:123], v[152:155], v[182:185], v[120:123]
	v_mfma_f32_16x16x32_bf16 v[116:119], v[144:147], v[190:193], v[116:119]
	v_mfma_f32_16x16x32_bf16 v[112:115], v[152:155], v[190:193], v[112:115]
	v_mfma_f32_16x16x32_bf16 v[108:111], v[144:147], v[198:201], v[108:111]
	v_mfma_f32_16x16x32_bf16 v[104:107], v[152:155], v[198:201], v[104:107]
	v_mfma_f32_16x16x32_bf16 v[100:103], v[144:147], v[206:209], v[100:103]
	v_mfma_f32_16x16x32_bf16 v[96:99], v[152:155], v[206:209], v[96:99]
	v_mfma_f32_16x16x32_bf16 v[124:127], v[148:151], v[186:189], v[124:127]
	v_mfma_f32_16x16x32_bf16 v[120:123], v[162:165], v[186:189], v[120:123]
	v_mfma_f32_16x16x32_bf16 v[116:119], v[148:151], v[194:197], v[116:119]
	v_mfma_f32_16x16x32_bf16 v[112:115], v[162:165], v[194:197], v[112:115]
	v_mfma_f32_16x16x32_bf16 v[108:111], v[148:151], v[202:205], v[108:111]
	v_mfma_f32_16x16x32_bf16 v[104:107], v[162:165], v[202:205], v[104:107]
	v_mfma_f32_16x16x32_bf16 v[100:103], v[148:151], v[210:213], v[100:103]
	v_mfma_f32_16x16x32_bf16 v[96:99], v[162:165], v[210:213], v[96:99]
	v_mfma_f32_16x16x32_bf16 v[60:63], v[166:169], v[182:185], v[60:63]
	v_mfma_f32_16x16x32_bf16 v[56:59], v[174:177], v[182:185], v[56:59]
	v_mfma_f32_16x16x32_bf16 v[52:55], v[166:169], v[190:193], v[52:55]
	v_mfma_f32_16x16x32_bf16 v[48:51], v[174:177], v[190:193], v[48:51]
	v_mfma_f32_16x16x32_bf16 v[44:47], v[166:169], v[198:201], v[44:47]
	v_mfma_f32_16x16x32_bf16 v[40:43], v[174:177], v[198:201], v[40:43]
	v_mfma_f32_16x16x32_bf16 v[36:39], v[166:169], v[206:209], v[36:39]
	v_mfma_f32_16x16x32_bf16 v[32:35], v[174:177], v[206:209], v[32:35]
	v_mfma_f32_16x16x32_bf16 v[60:63], v[170:173], v[186:189], v[60:63]
	v_mfma_f32_16x16x32_bf16 v[56:59], v[178:181], v[186:189], v[56:59]
	v_mfma_f32_16x16x32_bf16 v[52:55], v[170:173], v[194:197], v[52:55]
	v_mfma_f32_16x16x32_bf16 v[48:51], v[178:181], v[194:197], v[48:51]
	v_mfma_f32_16x16x32_bf16 v[44:47], v[170:173], v[202:205], v[44:47]
	v_mfma_f32_16x16x32_bf16 v[40:43], v[178:181], v[202:205], v[40:43]
	v_mfma_f32_16x16x32_bf16 v[36:39], v[170:173], v[210:213], v[36:39]
	v_mfma_f32_16x16x32_bf16 v[32:35], v[178:181], v[210:213], v[32:35]
	s_barrier
; #define PG8_STAGE(bufoff, gbase, voff) do { _Pragma("unroll") for (int _i = 0; _i < 2; ++_i) \
;         __builtin_amdgcn_global_load_lds((const unsigned*)((const char*)(gbase) + (voff)[_i]), (PG8_LAS unsigned*)(lds + (bufoff) + ldsw + _i * 8192), 16, 0, 0); } while (0)
; #define PG8_LDA(dst, b, h) do { _Pragma("unroll") for (int m = 0; m < 4; ++m) _Pragma("unroll") for (int k = 0; k < 2; ++k) dst[m][k] = *(const PG8_LAS bf16x8*)(lds + PG8_SA(b, h) + aoff + m * 2048 + k * 1024); } while (0)
; #define PG8_MMA(ai, bj, At, Bt) do { __builtin_amdgcn_s_setprio(1); _Pragma("unroll") for (int m = 0; m < 4; ++m) _Pragma("unroll") for (int n = 0; n < 2; ++n) _Pragma("unroll") for (int k = 0; k < 2; ++k) \
;         acc[ai][bj][m][n] = __builtin_amdgcn_mfma_f32_16x16x32_bf16(Bt[n][k], At[m][k], acc[ai][bj][m][n], 0, 0, 0); __builtin_amdgcn_s_setprio(0); } while (0)
; #define PG8_WAIT_V(n) asm volatile("s_waitcnt vmcnt(" #n ")" ::: "memory")
; #define PG8_WAIT_L(n) asm volatile("s_waitcnt lgkmcnt(" #n ")" ::: "memory")
; #define PG8_BAR __builtin_amdgcn_s_barrier()
; #define PG8_SCHED __builtin_amdgcn_sched_barrier(0)
; template <class Epi, class Sched, bool ALIGN_EPI = false, bool SP2 = false>
; __device__ __forceinline__ void gemm_phase(PG8_LAS unsigned char* lds, const Gemm g, const Sched& S, const Epi& E, const int wid) {
;     ...
;         for (int t = 0; t < nt; t += 2) {
;     ...
;             PG8_LDA(At, 1, 1); PG8_STAGE(PG8_SB(1, 0), b3, voffB); PG8_STAGE(PG8_SB(1, 1), b3 + hstep, voffB); PG8_STAGE(PG8_SA(1, 0), a3, voffA);
;             PG8_WAIT_V(8); PG8_WAIT_L(0); PG8_BAR; PG8_MMA(1, 0, At, B0); PG8_MMA(1, 1, At, B1); PG8_BAR; PG8_SCHED;
	s_add_i32 s20, s52, s33
	v_lshl_add_u64 v[214:215], v[214:215], 0, s[8:9]
	s_mov_b32 m0, s20
	ds_read_b128 v[182:185], v161 offset:49152
	ds_read_b128 v[186:189], v161 offset:50176
	ds_read_b128 v[190:193], v161 offset:51200
	ds_read_b128 v[194:197], v161 offset:52224
	ds_read_b128 v[198:201], v161 offset:53248
	ds_read_b128 v[202:205], v161 offset:54272
	ds_read_b128 v[206:209], v161 offset:55296
	ds_read_b128 v[210:213], v161 offset:56320
	global_load_lds_dwordx4 v[214:215], off
	s_add_i32 m0, s20, 0x2000
	s_add_u32 s20, s24, 0xb0080
	v_lshl_add_u64 v[214:215], v[216:217], 0, s[8:9]
	s_addc_u32 s21, s25, 0
	s_add_i32 s24, s53, s33
	global_load_lds_dwordx4 v[214:215], off
	v_lshl_add_u64 v[214:215], s[20:21], 0, v[130:131]
	s_mov_b32 m0, s24
	s_nop 0
	global_load_lds_dwordx4 v[214:215], off
	v_lshl_add_u64 v[214:215], s[20:21], 0, v[134:135]
	s_add_i32 m0, s24, 0x2000
	s_nop 0
	global_load_lds_dwordx4 v[214:215], off
	v_lshl_add_u64 v[214:215], v[218:219], 0, s[8:9]
	s_mov_b32 m0, s40
	s_nop 0
	global_load_lds_dwordx4 v[214:215], off
	v_lshl_add_u64 v[214:215], v[220:221], 0, s[8:9]
	s_mov_b32 m0, s41
	s_nop 0
	global_load_lds_dwordx4 v[214:215], off
	s_waitcnt vmcnt(8)
	s_waitcnt lgkmcnt(0)
	s_barrier
	s_waitcnt lgkmcnt(0)
	v_mfma_f32_16x16x32_bf16 v[92:95], v[144:147], v[182:185], v[92:95]
	v_mfma_f32_16x16x32_bf16 v[88:91], v[152:155], v[182:185], v[88:91]
	v_mfma_f32_16x16x32_bf16 v[84:87], v[144:147], v[190:193], v[84:87]
	v_mfma_f32_16x16x32_bf16 v[80:83], v[152:155], v[190:193], v[80:83]
	v_mfma_f32_16x16x32_bf16 v[76:79], v[144:147], v[198:201], v[76:79]
	v_mfma_f32_16x16x32_bf16 v[72:75], v[152:155], v[198:201], v[72:75]
	v_mfma_f32_16x16x32_bf16 v[68:71], v[144:147], v[206:209], v[68:71]
	v_mfma_f32_16x16x32_bf16 v[64:67], v[152:155], v[206:209], v[64:67]
	v_mfma_f32_16x16x32_bf16 v[92:95], v[148:151], v[186:189], v[92:95]
	v_mfma_f32_16x16x32_bf16 v[88:91], v[162:165], v[186:189], v[88:91]
	v_mfma_f32_16x16x32_bf16 v[84:87], v[148:151], v[194:197], v[84:87]
	v_mfma_f32_16x16x32_bf16 v[80:83], v[162:165], v[194:197], v[80:83]
	v_mfma_f32_16x16x32_bf16 v[76:79], v[148:151], v[202:205], v[76:79]
	v_mfma_f32_16x16x32_bf16 v[72:75], v[162:165], v[202:205], v[72:75]
	v_mfma_f32_16x16x32_bf16 v[68:71], v[148:151], v[210:213], v[68:71]
	v_mfma_f32_16x16x32_bf16 v[64:67], v[162:165], v[210:213], v[64:67]
	v_mfma_f32_16x16x32_bf16 v[28:31], v[166:169], v[182:185], v[28:31]
	v_mfma_f32_16x16x32_bf16 v[24:27], v[174:177], v[182:185], v[24:27]
	v_mfma_f32_16x16x32_bf16 v[20:23], v[166:169], v[190:193], v[20:23]
	v_mfma_f32_16x16x32_bf16 v[16:19], v[174:177], v[190:193], v[16:19]
	v_mfma_f32_16x16x32_bf16 v[12:15], v[166:169], v[198:201], v[12:15]
	v_mfma_f32_16x16x32_bf16 v[8:11], v[174:177], v[198:201], v[8:11]
	v_mfma_f32_16x16x32_bf16 v[4:7], v[166:169], v[206:209], v[4:7]
	v_mfma_f32_16x16x32_bf16 v[0:3], v[174:177], v[206:209], v[0:3]
	v_mfma_f32_16x16x32_bf16 v[28:31], v[170:173], v[186:189], v[28:31]
	v_mfma_f32_16x16x32_bf16 v[24:27], v[178:181], v[186:189], v[24:27]
	v_mfma_f32_16x16x32_bf16 v[20:23], v[170:173], v[194:197], v[20:23]
	v_mfma_f32_16x16x32_bf16 v[16:19], v[178:181], v[194:197], v[16:19]
	v_mfma_f32_16x16x32_bf16 v[12:15], v[170:173], v[202:205], v[12:15]
	v_mfma_f32_16x16x32_bf16 v[8:11], v[178:181], v[202:205], v[8:11]
	v_mfma_f32_16x16x32_bf16 v[4:7], v[170:173], v[210:213], v[4:7]
	v_mfma_f32_16x16x32_bf16 v[0:3], v[178:181], v[210:213], v[0:3]
	s_barrier
	s_add_i32 s51, s51, 2
	s_add_u32 s49, s49, 0x100
	s_addc_u32 s50, s50, 0
	s_cmp_gt_u32 s51, 41
	s_mov_b64 s[20:21], s[22:23]
	s_cbranch_scc0 .LBB0_1393
	s_and_b64 vcc, exec, s[10:11]
	s_cbranch_vccz .LBB0_1396
	s_barrier
